# removed the s_setprio 0/1 flip pair inside each 32-MFMA segment of all GEMM mainloops (priority stays raised for the whole segment)
# baseline (speedup 1.0000x reference)
; #define PG8_STAGE(bufoff, gbase, voff) do { _Pragma("unroll") for (int _i = 0; _i < 2; ++_i) \
;         __builtin_amdgcn_global_load_lds((const unsigned*)((const char*)(gbase) + (voff)[_i]), (LAS unsigned*)(lds + (bufoff) + ldsw + _i * 8192), 16, 0, 0); } while (0)
; #define PG8_LDA(dst, b, h) do { _Pragma("unroll") for (int m = 0; m < 4; ++m) _Pragma("unroll") for (int k = 0; k < 2; ++k) dst[m][k] = *(const LAS bf16x8*)(lds + PG8_SA(b, h) + aoff + m * 2048 + k * 1024); } while (0)
; #define PG8_LDB(dst, b, h) do { _Pragma("unroll") for (int n = 0; n < 2; ++n) _Pragma("unroll") for (int k = 0; k < 2; ++k) dst[n][k] = *(const LAS bf16x8*)(lds + PG8_SB(b, h) + boff + n * 2048 + k * 1024); } while (0)
; #define PG8_MMA(ai, bj, At, Bt) do { __builtin_amdgcn_s_setprio(1); _Pragma("unroll") for (int m = 0; m < 4; ++m) _Pragma("unroll") for (int n = 0; n < 2; ++n) _Pragma("unroll") for (int k = 0; k < 2; ++k) \
;         acc[ai][bj][m][n] = __builtin_amdgcn_mfma_f32_16x16x32_bf16(Bt[n][k], At[m][k], acc[ai][bj][m][n], 0, 0, 0); __builtin_amdgcn_s_setprio(0); } while (0)
; #define PG8_WAIT_V(n) asm volatile("s_waitcnt vmcnt(" #n ")" ::: "memory")
; #define PG8_WAIT_L(n) asm volatile("s_waitcnt lgkmcnt(" #n ")" ::: "memory")
; #define PG8_BAR __builtin_amdgcn_s_barrier()
; #define PG8_SCHED __builtin_amdgcn_sched_barrier(0)
; template <class Epi>
; __device__ __forceinline__ void gemm_phase(LAS unsigned char* lds, const Sched& S, const int K, const Epi& E) {
;     ...
;             const bool last = (t == nt - 2);
;             const char* a1 = cA + (size_t)(t + 1) * kstep;
;             const char* a2 = last ? nA : cA + (size_t)(t + 2) * kstep; const char* b2 = last ? nB : cB + (size_t)(t + 2) * kstep;
;             const char* a3 = a2 + kstep; const char* b3 = b2 + kstep;
;             PG8_LDB(B0, 0, 0); PG8_LDB(B1, 0, 1); PG8_SCHED; PG8_LDA(At, 0, 0); PG8_STAGE(PG8_SA(1, 1), a1 + hstepA, voffA);
;             PG8_WAIT_V(8); PG8_WAIT_L(0); PG8_BAR; PG8_MMA(0, 0, At, B0); PG8_MMA(0, 1, At, B1); PG8_BAR; PG8_SCHED;
;             PG8_LDA(At, 0, 1); PG8_STAGE(PG8_SB(0, 0), b2, voffB); PG8_STAGE(PG8_SB(0, 1), b2 + hstepB, voffB); PG8_STAGE(PG8_SA(0, 0), a2, voffA);
;             PG8_WAIT_V(8); PG8_WAIT_L(0); PG8_BAR; PG8_MMA(1, 0, At, B0); PG8_MMA(1, 1, At, B1); PG8_BAR; PG8_SCHED;
.LBB0_457:
	s_add_u32 s58, s36, 0xfff80080
	s_addc_u32 s59, s37, -1
	s_add_i32 s76, 0, 0x10000
	s_cmp_eq_u32 s97, 28
	s_cselect_b32 s93, s29, s59
	s_cselect_b32 s92, s28, s58
	v_add_u32_e32 v143, s76, v151
	s_cselect_b32 s59, s35, s64
	s_cselect_b32 s58, s34, s51
	s_add_i32 s77, 0, 0x14000
	ds_read_b128 v[144:147], v143
	ds_read_b128 v[156:159], v143 offset:1024
	ds_read_b128 v[160:163], v143 offset:2048
	ds_read_b128 v[164:167], v143 offset:3072
	v_add_u32_e32 v143, s77, v151
	ds_read_b128 v[168:171], v143
	ds_read_b128 v[198:201], v143 offset:1024
	ds_read_b128 v[202:205], v143 offset:2048
	ds_read_b128 v[206:209], v143 offset:3072
	v_lshl_add_u64 v[148:149], s[36:37], 0, v[138:139]
	s_add_i32 m0, s60, 0xc000
	ds_read_b128 v[210:213], v154
	ds_read_b128 v[214:217], v154 offset:1024
	ds_read_b128 v[218:221], v154 offset:2048
	ds_read_b128 v[228:231], v154 offset:3072
	ds_read_b128 v[232:235], v154 offset:4096
	ds_read_b128 v[236:239], v154 offset:5120
	ds_read_b128 v[240:243], v154 offset:6144
	ds_read_b128 v[244:247], v154 offset:7168
	global_load_lds_dwordx4 v[148:149], off
	v_lshl_add_u64 v[148:149], s[36:37], 0, v[140:141]
	s_add_i32 m0, s60, 0xe000
	s_nop 0
	global_load_lds_dwordx4 v[148:149], off
	s_waitcnt vmcnt(8)
	s_waitcnt lgkmcnt(0)
	s_barrier
	s_setprio 1
	s_waitcnt lgkmcnt(0)
	v_mfma_f32_16x16x32_bf16 v[124:127], v[144:147], v[210:213], v[124:127]
	v_mfma_f32_16x16x32_bf16 v[120:123], v[160:163], v[210:213], v[120:123]
	v_mfma_f32_16x16x32_bf16 v[108:111], v[144:147], v[218:221], v[108:111]
	v_mfma_f32_16x16x32_bf16 v[104:107], v[160:163], v[218:221], v[104:107]
	v_mfma_f32_16x16x32_bf16 v[92:95], v[144:147], v[232:235], v[92:95]
	v_mfma_f32_16x16x32_bf16 v[88:91], v[160:163], v[232:235], v[88:91]
	v_mfma_f32_16x16x32_bf16 v[76:79], v[144:147], v[240:243], v[76:79]
	v_mfma_f32_16x16x32_bf16 v[72:75], v[160:163], v[240:243], v[72:75]
	v_mfma_f32_16x16x32_bf16 v[124:127], v[156:159], v[214:217], v[124:127]
	v_mfma_f32_16x16x32_bf16 v[120:123], v[164:167], v[214:217], v[120:123]
	v_mfma_f32_16x16x32_bf16 v[108:111], v[156:159], v[228:231], v[108:111]
	v_mfma_f32_16x16x32_bf16 v[104:107], v[164:167], v[228:231], v[104:107]
	v_mfma_f32_16x16x32_bf16 v[92:95], v[156:159], v[236:239], v[92:95]
	v_mfma_f32_16x16x32_bf16 v[88:91], v[164:167], v[236:239], v[88:91]
	v_mfma_f32_16x16x32_bf16 v[76:79], v[156:159], v[244:247], v[76:79]
	v_mfma_f32_16x16x32_bf16 v[72:75], v[164:167], v[244:247], v[72:75]
	v_mfma_f32_16x16x32_bf16 v[116:119], v[168:171], v[210:213], v[116:119]
	v_mfma_f32_16x16x32_bf16 v[112:115], v[202:205], v[210:213], v[112:115]
	v_mfma_f32_16x16x32_bf16 v[100:103], v[168:171], v[218:221], v[100:103]
	v_mfma_f32_16x16x32_bf16 v[96:99], v[202:205], v[218:221], v[96:99]
	v_mfma_f32_16x16x32_bf16 v[84:87], v[168:171], v[232:235], v[84:87]
	v_mfma_f32_16x16x32_bf16 v[80:83], v[202:205], v[232:235], v[80:83]
	v_mfma_f32_16x16x32_bf16 v[68:71], v[168:171], v[240:243], v[68:71]
	v_mfma_f32_16x16x32_bf16 v[64:67], v[202:205], v[240:243], v[64:67]
	v_mfma_f32_16x16x32_bf16 v[116:119], v[198:201], v[214:217], v[116:119]
	v_mfma_f32_16x16x32_bf16 v[112:115], v[206:209], v[214:217], v[112:115]
	v_mfma_f32_16x16x32_bf16 v[100:103], v[198:201], v[228:231], v[100:103]
	v_mfma_f32_16x16x32_bf16 v[96:99], v[206:209], v[228:231], v[96:99]
	v_mfma_f32_16x16x32_bf16 v[84:87], v[198:201], v[236:239], v[84:87]
	v_mfma_f32_16x16x32_bf16 v[80:83], v[206:209], v[236:239], v[80:83]
	v_mfma_f32_16x16x32_bf16 v[68:71], v[198:201], v[244:247], v[68:71]
	v_mfma_f32_16x16x32_bf16 v[64:67], v[206:209], v[244:247], v[64:67]
	s_setprio 0
	s_barrier
	s_add_i32 s76, s76, s57
	v_lshl_add_u64 v[148:149], s[58:59], 0, v[132:133]
	s_mov_b32 m0, s76
	ds_read_b128 v[210:213], v154 offset:16384
	ds_read_b128 v[214:217], v154 offset:17408
	ds_read_b128 v[218:221], v154 offset:18432
	ds_read_b128 v[228:231], v154 offset:19456
	ds_read_b128 v[232:235], v154 offset:20480
	ds_read_b128 v[236:239], v154 offset:21504
	ds_read_b128 v[240:243], v154 offset:22528
	ds_read_b128 v[244:247], v154 offset:23552
	global_load_lds_dwordx4 v[148:149], off
	s_add_i32 m0, s76, 0x2000
	s_add_u32 vcc_lo, s58, 0x80000
	v_lshl_add_u64 v[248:249], s[58:59], 0, v[128:129]
	s_addc_u32 vcc_hi, s59, 0
	s_add_i32 s76, s77, s57
	global_load_lds_dwordx4 v[248:249], off
	v_lshl_add_u64 v[250:251], vcc, 0, v[132:133]
	s_mov_b32 m0, s76
	v_lshl_add_u64 v[224:225], s[92:93], 0, v[130:131]
	global_load_lds_dwordx4 v[250:251], off
	v_lshl_add_u64 v[250:251], vcc, 0, v[128:129]
	s_add_i32 m0, s76, 0x2000
	s_nop 0
	global_load_lds_dwordx4 v[250:251], off
	v_lshl_add_u64 v[250:251], s[92:93], 0, v[134:135]
	s_mov_b32 m0, s60
	s_nop 0
	global_load_lds_dwordx4 v[250:251], off
	s_mov_b32 m0, s63
	s_nop 0
	global_load_lds_dwordx4 v[224:225], off
	s_waitcnt vmcnt(8)
	s_waitcnt lgkmcnt(0)
	s_barrier
; #define PG8_STAGE(bufoff, gbase, voff) do { _Pragma("unroll") for (int _i = 0; _i < 2; ++_i) \
;         __builtin_amdgcn_global_load_lds((const unsigned*)((const char*)(gbase) + (voff)[_i]), (LAS unsigned*)(lds + (bufoff) + ldsw + _i * 8192), 16, 0, 0); } while (0)
; #define PG8_LDA(dst, b, h) do { _Pragma("unroll") for (int m = 0; m < 4; ++m) _Pragma("unroll") for (int k = 0; k < 2; ++k) dst[m][k] = *(const LAS bf16x8*)(lds + PG8_SA(b, h) + aoff + m * 2048 + k * 1024); } while (0)
; #define PG8_LDB(dst, b, h) do { _Pragma("unroll") for (int n = 0; n < 2; ++n) _Pragma("unroll") for (int k = 0; k < 2; ++k) dst[n][k] = *(const LAS bf16x8*)(lds + PG8_SB(b, h) + boff + n * 2048 + k * 1024); } while (0)
; #define PG8_MMA(ai, bj, At, Bt) do { __builtin_amdgcn_s_setprio(1); _Pragma("unroll") for (int m = 0; m < 4; ++m) _Pragma("unroll") for (int n = 0; n < 2; ++n) _Pragma("unroll") for (int k = 0; k < 2; ++k) \
;         acc[ai][bj][m][n] = __builtin_amdgcn_mfma_f32_16x16x32_bf16(Bt[n][k], At[m][k], acc[ai][bj][m][n], 0, 0, 0); __builtin_amdgcn_s_setprio(0); } while (0)
; #define PG8_WAIT_V(n) asm volatile("s_waitcnt vmcnt(" #n ")" ::: "memory")
; #define PG8_WAIT_L(n) asm volatile("s_waitcnt lgkmcnt(" #n ")" ::: "memory")
; #define PG8_BAR __builtin_amdgcn_s_barrier()
; #define PG8_SCHED __builtin_amdgcn_sched_barrier(0)
; template <class Epi>
; __device__ __forceinline__ void gemm_phase(LAS unsigned char* lds, const Sched& S, const int K, const Epi& E) {
;     ...
;             PG8_WAIT_V(8); PG8_WAIT_L(0); PG8_BAR; PG8_MMA(1, 0, At, B0); PG8_MMA(1, 1, At, B1); PG8_BAR; PG8_SCHED;
;             PG8_LDB(B0, 1, 0); PG8_LDB(B1, 1, 1); PG8_SCHED; PG8_LDA(At, 1, 0); PG8_STAGE(PG8_SA(0, 1), a2 + hstepA, voffA);
;             PG8_WAIT_V(8); PG8_WAIT_L(0); PG8_BAR; PG8_MMA(0, 0, At, B0); PG8_MMA(0, 1, At, B1); PG8_BAR; PG8_SCHED;
	s_setprio 1
	s_waitcnt lgkmcnt(0)
	v_mfma_f32_16x16x32_bf16 v[60:63], v[144:147], v[210:213], v[60:63]
	v_mfma_f32_16x16x32_bf16 v[56:59], v[160:163], v[210:213], v[56:59]
	v_mfma_f32_16x16x32_bf16 v[44:47], v[144:147], v[218:221], v[44:47]
	v_mfma_f32_16x16x32_bf16 v[40:43], v[160:163], v[218:221], v[40:43]
	v_mfma_f32_16x16x32_bf16 v[28:31], v[144:147], v[232:235], v[28:31]
	v_mfma_f32_16x16x32_bf16 v[24:27], v[160:163], v[232:235], v[24:27]
	v_mfma_f32_16x16x32_bf16 v[12:15], v[144:147], v[240:243], v[12:15]
	v_mfma_f32_16x16x32_bf16 v[8:11], v[160:163], v[240:243], v[8:11]
	v_mfma_f32_16x16x32_bf16 v[60:63], v[156:159], v[214:217], v[60:63]
	v_mfma_f32_16x16x32_bf16 v[56:59], v[164:167], v[214:217], v[56:59]
	v_mfma_f32_16x16x32_bf16 v[44:47], v[156:159], v[228:231], v[44:47]
	v_mfma_f32_16x16x32_bf16 v[40:43], v[164:167], v[228:231], v[40:43]
	v_mfma_f32_16x16x32_bf16 v[28:31], v[156:159], v[236:239], v[28:31]
	v_mfma_f32_16x16x32_bf16 v[24:27], v[164:167], v[236:239], v[24:27]
	v_mfma_f32_16x16x32_bf16 v[12:15], v[156:159], v[244:247], v[12:15]
	v_mfma_f32_16x16x32_bf16 v[8:11], v[164:167], v[244:247], v[8:11]
	v_mfma_f32_16x16x32_bf16 v[52:55], v[168:171], v[210:213], v[52:55]
	v_mfma_f32_16x16x32_bf16 v[48:51], v[202:205], v[210:213], v[48:51]
	v_mfma_f32_16x16x32_bf16 v[36:39], v[168:171], v[218:221], v[36:39]
	v_mfma_f32_16x16x32_bf16 v[32:35], v[202:205], v[218:221], v[32:35]
	v_mfma_f32_16x16x32_bf16 v[20:23], v[168:171], v[232:235], v[20:23]
	v_mfma_f32_16x16x32_bf16 v[16:19], v[202:205], v[232:235], v[16:19]
	v_mfma_f32_16x16x32_bf16 v[4:7], v[168:171], v[240:243], v[4:7]
	v_mfma_f32_16x16x32_bf16 v[0:3], v[202:205], v[240:243], v[0:3]
	v_mfma_f32_16x16x32_bf16 v[52:55], v[198:201], v[214:217], v[52:55]
	v_mfma_f32_16x16x32_bf16 v[48:51], v[206:209], v[214:217], v[48:51]
	v_mfma_f32_16x16x32_bf16 v[36:39], v[198:201], v[228:231], v[36:39]
	v_mfma_f32_16x16x32_bf16 v[32:35], v[206:209], v[228:231], v[32:35]
	v_mfma_f32_16x16x32_bf16 v[20:23], v[198:201], v[236:239], v[20:23]
	v_mfma_f32_16x16x32_bf16 v[16:19], v[206:209], v[236:239], v[16:19]
	v_mfma_f32_16x16x32_bf16 v[4:7], v[198:201], v[244:247], v[4:7]
	v_mfma_f32_16x16x32_bf16 v[0:3], v[206:209], v[244:247], v[0:3]
	s_setprio 0
	s_barrier
	s_add_i32 s76, 0, 0x18000
	v_add_u32_e32 v143, s76, v151
	s_add_i32 s77, 0, 0x1c000
	ds_read_b128 v[144:147], v143
	ds_read_b128 v[156:159], v143 offset:1024
	ds_read_b128 v[160:163], v143 offset:2048
	ds_read_b128 v[164:167], v143 offset:3072
	v_add_u32_e32 v143, s77, v151
	ds_read_b128 v[168:171], v143
	ds_read_b128 v[198:201], v143 offset:1024
	ds_read_b128 v[202:205], v143 offset:2048
	ds_read_b128 v[206:209], v143 offset:3072
	s_add_u32 s92, s92, 0x80000
	s_addc_u32 s93, s93, 0
	s_mov_b32 m0, s66
	v_lshl_add_u64 v[194:195], s[92:93], 0, v[134:135]
	ds_read_b128 v[210:213], v154 offset:32768
	ds_read_b128 v[214:217], v154 offset:33792
	ds_read_b128 v[218:221], v154 offset:34816
	ds_read_b128 v[228:231], v154 offset:35840
	ds_read_b128 v[232:235], v154 offset:36864
	ds_read_b128 v[236:239], v154 offset:37888
	ds_read_b128 v[240:243], v154 offset:38912
	ds_read_b128 v[244:247], v154 offset:39936
	global_load_lds_dwordx4 v[194:195], off
	v_lshl_add_u64 v[194:195], s[92:93], 0, v[130:131]
	s_mov_b32 m0, s67
	s_nop 0
	global_load_lds_dwordx4 v[194:195], off
	s_waitcnt vmcnt(8)
	s_waitcnt lgkmcnt(0)
	s_barrier
	s_setprio 1
	s_waitcnt lgkmcnt(0)
	v_mfma_f32_16x16x32_bf16 v[124:127], v[144:147], v[210:213], v[124:127]
	v_mfma_f32_16x16x32_bf16 v[120:123], v[160:163], v[210:213], v[120:123]
	v_mfma_f32_16x16x32_bf16 v[108:111], v[144:147], v[218:221], v[108:111]
	v_mfma_f32_16x16x32_bf16 v[104:107], v[160:163], v[218:221], v[104:107]
	v_mfma_f32_16x16x32_bf16 v[92:95], v[144:147], v[232:235], v[92:95]
	v_mfma_f32_16x16x32_bf16 v[88:91], v[160:163], v[232:235], v[88:91]
	v_mfma_f32_16x16x32_bf16 v[76:79], v[144:147], v[240:243], v[76:79]
	v_mfma_f32_16x16x32_bf16 v[72:75], v[160:163], v[240:243], v[72:75]
	v_mfma_f32_16x16x32_bf16 v[124:127], v[156:159], v[214:217], v[124:127]
	v_mfma_f32_16x16x32_bf16 v[120:123], v[164:167], v[214:217], v[120:123]
	v_mfma_f32_16x16x32_bf16 v[108:111], v[156:159], v[228:231], v[108:111]
	v_mfma_f32_16x16x32_bf16 v[104:107], v[164:167], v[228:231], v[104:107]
	v_mfma_f32_16x16x32_bf16 v[92:95], v[156:159], v[236:239], v[92:95]
	v_mfma_f32_16x16x32_bf16 v[88:91], v[164:167], v[236:239], v[88:91]
	v_mfma_f32_16x16x32_bf16 v[76:79], v[156:159], v[244:247], v[76:79]
	v_mfma_f32_16x16x32_bf16 v[72:75], v[164:167], v[244:247], v[72:75]
	v_mfma_f32_16x16x32_bf16 v[116:119], v[168:171], v[210:213], v[116:119]
	v_mfma_f32_16x16x32_bf16 v[112:115], v[202:205], v[210:213], v[112:115]
	v_mfma_f32_16x16x32_bf16 v[100:103], v[168:171], v[218:221], v[100:103]
	v_mfma_f32_16x16x32_bf16 v[96:99], v[202:205], v[218:221], v[96:99]
	v_mfma_f32_16x16x32_bf16 v[84:87], v[168:171], v[232:235], v[84:87]
	v_mfma_f32_16x16x32_bf16 v[80:83], v[202:205], v[232:235], v[80:83]
	v_mfma_f32_16x16x32_bf16 v[68:71], v[168:171], v[240:243], v[68:71]
	v_mfma_f32_16x16x32_bf16 v[64:67], v[202:205], v[240:243], v[64:67]
	v_mfma_f32_16x16x32_bf16 v[116:119], v[198:201], v[214:217], v[116:119]
	v_mfma_f32_16x16x32_bf16 v[112:115], v[206:209], v[214:217], v[112:115]
	v_mfma_f32_16x16x32_bf16 v[100:103], v[198:201], v[228:231], v[100:103]
	v_mfma_f32_16x16x32_bf16 v[96:99], v[206:209], v[228:231], v[96:99]
	v_mfma_f32_16x16x32_bf16 v[84:87], v[198:201], v[236:239], v[84:87]
	v_mfma_f32_16x16x32_bf16 v[80:83], v[206:209], v[236:239], v[80:83]
	v_mfma_f32_16x16x32_bf16 v[68:71], v[198:201], v[244:247], v[68:71]
	v_mfma_f32_16x16x32_bf16 v[64:67], v[206:209], v[244:247], v[64:67]
	s_setprio 0
	s_barrier
; #define PG8_STAGE(bufoff, gbase, voff) do { _Pragma("unroll") for (int _i = 0; _i < 2; ++_i) \
;         __builtin_amdgcn_global_load_lds((const unsigned*)((const char*)(gbase) + (voff)[_i]), (LAS unsigned*)(lds + (bufoff) + ldsw + _i * 8192), 16, 0, 0); } while (0)
; #define PG8_LDA(dst, b, h) do { _Pragma("unroll") for (int m = 0; m < 4; ++m) _Pragma("unroll") for (int k = 0; k < 2; ++k) dst[m][k] = *(const LAS bf16x8*)(lds + PG8_SA(b, h) + aoff + m * 2048 + k * 1024); } while (0)
; #define PG8_MMA(ai, bj, At, Bt) do { __builtin_amdgcn_s_setprio(1); _Pragma("unroll") for (int m = 0; m < 4; ++m) _Pragma("unroll") for (int n = 0; n < 2; ++n) _Pragma("unroll") for (int k = 0; k < 2; ++k) \
;         acc[ai][bj][m][n] = __builtin_amdgcn_mfma_f32_16x16x32_bf16(Bt[n][k], At[m][k], acc[ai][bj][m][n], 0, 0, 0); __builtin_amdgcn_s_setprio(0); } while (0)
; #define PG8_WAIT_V(n) asm volatile("s_waitcnt vmcnt(" #n ")" ::: "memory")
; #define PG8_WAIT_L(n) asm volatile("s_waitcnt lgkmcnt(" #n ")" ::: "memory")
; #define PG8_BAR __builtin_amdgcn_s_barrier()
; #define PG8_SCHED __builtin_amdgcn_sched_barrier(0)
; template <class Epi>
; __device__ __forceinline__ void gemm_phase(LAS unsigned char* lds, const Sched& S, const int K, const Epi& E) {
;     ...
;             PG8_LDA(At, 1, 1); PG8_STAGE(PG8_SB(1, 0), b3, voffB); PG8_STAGE(PG8_SB(1, 1), b3 + hstepB, voffB); PG8_STAGE(PG8_SA(1, 0), a3, voffA);
;             PG8_WAIT_V(8); PG8_WAIT_L(0); PG8_BAR; PG8_MMA(1, 0, At, B0); PG8_MMA(1, 1, At, B1); PG8_BAR; PG8_SCHED;
;         }
;         if (wr == 0) PG8_BAR;
	s_add_i32 s76, s76, s57
	v_lshl_add_u64 v[148:149], v[148:149], 0, s[74:75]
	s_mov_b32 m0, s76
	ds_read_b128 v[210:213], v154 offset:49152
	ds_read_b128 v[214:217], v154 offset:50176
	ds_read_b128 v[218:221], v154 offset:51200
	ds_read_b128 v[228:231], v154 offset:52224
	ds_read_b128 v[232:235], v154 offset:53248
	ds_read_b128 v[236:239], v154 offset:54272
	ds_read_b128 v[240:243], v154 offset:55296
	ds_read_b128 v[244:247], v154 offset:56320
	global_load_lds_dwordx4 v[148:149], off
	s_add_i32 m0, s76, 0x2000
	s_add_u32 s58, s58, 0x80080
	v_lshl_add_u64 v[148:149], v[248:249], 0, s[74:75]
	s_addc_u32 s59, s59, 0
	s_add_i32 s76, s77, s57
	global_load_lds_dwordx4 v[148:149], off
	v_lshl_add_u64 v[148:149], s[58:59], 0, v[132:133]
	s_mov_b32 m0, s76
	s_nop 0
	global_load_lds_dwordx4 v[148:149], off
	v_lshl_add_u64 v[148:149], s[58:59], 0, v[128:129]
	s_add_i32 m0, s76, 0x2000
	s_nop 0
	global_load_lds_dwordx4 v[148:149], off
	v_lshl_add_u64 v[148:149], v[250:251], 0, s[74:75]
	s_mov_b32 m0, s69
	s_nop 0
	global_load_lds_dwordx4 v[148:149], off
	v_lshl_add_u64 v[148:149], v[224:225], 0, s[74:75]
	s_mov_b32 m0, s70
	s_nop 0
	global_load_lds_dwordx4 v[148:149], off
	s_waitcnt vmcnt(8)
	s_waitcnt lgkmcnt(0)
	s_barrier
	s_setprio 1
	s_waitcnt lgkmcnt(0)
	v_mfma_f32_16x16x32_bf16 v[60:63], v[144:147], v[210:213], v[60:63]
	v_mfma_f32_16x16x32_bf16 v[56:59], v[160:163], v[210:213], v[56:59]
	v_mfma_f32_16x16x32_bf16 v[44:47], v[144:147], v[218:221], v[44:47]
	v_mfma_f32_16x16x32_bf16 v[40:43], v[160:163], v[218:221], v[40:43]
	v_mfma_f32_16x16x32_bf16 v[28:31], v[144:147], v[232:235], v[28:31]
	v_mfma_f32_16x16x32_bf16 v[24:27], v[160:163], v[232:235], v[24:27]
	v_mfma_f32_16x16x32_bf16 v[12:15], v[144:147], v[240:243], v[12:15]
	v_mfma_f32_16x16x32_bf16 v[8:11], v[160:163], v[240:243], v[8:11]
	v_mfma_f32_16x16x32_bf16 v[60:63], v[156:159], v[214:217], v[60:63]
	v_mfma_f32_16x16x32_bf16 v[56:59], v[164:167], v[214:217], v[56:59]
	v_mfma_f32_16x16x32_bf16 v[44:47], v[156:159], v[228:231], v[44:47]
	v_mfma_f32_16x16x32_bf16 v[40:43], v[164:167], v[228:231], v[40:43]
	v_mfma_f32_16x16x32_bf16 v[28:31], v[156:159], v[236:239], v[28:31]
	v_mfma_f32_16x16x32_bf16 v[24:27], v[164:167], v[236:239], v[24:27]
	v_mfma_f32_16x16x32_bf16 v[12:15], v[156:159], v[244:247], v[12:15]
	v_mfma_f32_16x16x32_bf16 v[8:11], v[164:167], v[244:247], v[8:11]
	v_mfma_f32_16x16x32_bf16 v[52:55], v[168:171], v[210:213], v[52:55]
	v_mfma_f32_16x16x32_bf16 v[48:51], v[202:205], v[210:213], v[48:51]
	v_mfma_f32_16x16x32_bf16 v[36:39], v[168:171], v[218:221], v[36:39]
	v_mfma_f32_16x16x32_bf16 v[32:35], v[202:205], v[218:221], v[32:35]
	v_mfma_f32_16x16x32_bf16 v[20:23], v[168:171], v[232:235], v[20:23]
	v_mfma_f32_16x16x32_bf16 v[16:19], v[202:205], v[232:235], v[16:19]
	v_mfma_f32_16x16x32_bf16 v[4:7], v[168:171], v[240:243], v[4:7]
	v_mfma_f32_16x16x32_bf16 v[0:3], v[202:205], v[240:243], v[0:3]
	v_mfma_f32_16x16x32_bf16 v[52:55], v[198:201], v[214:217], v[52:55]
	v_mfma_f32_16x16x32_bf16 v[48:51], v[206:209], v[214:217], v[48:51]
	v_mfma_f32_16x16x32_bf16 v[36:39], v[198:201], v[228:231], v[36:39]
	v_mfma_f32_16x16x32_bf16 v[32:35], v[206:209], v[228:231], v[32:35]
	v_mfma_f32_16x16x32_bf16 v[20:23], v[198:201], v[236:239], v[20:23]
	v_mfma_f32_16x16x32_bf16 v[16:19], v[206:209], v[236:239], v[16:19]
	v_mfma_f32_16x16x32_bf16 v[4:7], v[198:201], v[244:247], v[4:7]
	v_mfma_f32_16x16x32_bf16 v[0:3], v[206:209], v[244:247], v[0:3]
	s_setprio 0
	s_barrier
	s_add_i32 s97, s97, 2
	s_add_u32 s51, s51, 0x100
	s_addc_u32 s64, s64, 0
	s_add_u32 s36, s36, 0x100
	s_addc_u32 s37, s37, 0
	s_cmp_gt_u32 s97, 29
	s_cbranch_scc0 .LBB0_457
	s_and_b64 vcc, exec, s[48:49]
	s_cbranch_vccz .LBB0_460
	s_barrier

; #define PG8_STAGE(bufoff, gbase, voff) do { _Pragma("unroll") for (int _i = 0; _i < 2; ++_i) \
;         __builtin_amdgcn_global_load_lds((const unsigned*)((const char*)(gbase) + (voff)[_i]), (LAS unsigned*)(lds + (bufoff) + ldsw + _i * 8192), 16, 0, 0); } while (0)
; #define PG8_LDA(dst, b, h) do { _Pragma("unroll") for (int m = 0; m < 4; ++m) _Pragma("unroll") for (int k = 0; k < 2; ++k) dst[m][k] = *(const LAS bf16x8*)(lds + PG8_SA(b, h) + aoff + m * 2048 + k * 1024); } while (0)
; #define PG8_LDB(dst, b, h) do { _Pragma("unroll") for (int n = 0; n < 2; ++n) _Pragma("unroll") for (int k = 0; k < 2; ++k) dst[n][k] = *(const LAS bf16x8*)(lds + PG8_SB(b, h) + boff + n * 2048 + k * 1024); } while (0)
; #define PG8_MMA(ai, bj, At, Bt) do { __builtin_amdgcn_s_setprio(1); _Pragma("unroll") for (int m = 0; m < 4; ++m) _Pragma("unroll") for (int n = 0; n < 2; ++n) _Pragma("unroll") for (int k = 0; k < 2; ++k) \
;         acc[ai][bj][m][n] = __builtin_amdgcn_mfma_f32_16x16x32_bf16(Bt[n][k], At[m][k], acc[ai][bj][m][n], 0, 0, 0); __builtin_amdgcn_s_setprio(0); } while (0)
; #define PG8_WAIT_V(n) asm volatile("s_waitcnt vmcnt(" #n ")" ::: "memory")
; #define PG8_WAIT_L(n) asm volatile("s_waitcnt lgkmcnt(" #n ")" ::: "memory")
; #define PG8_BAR __builtin_amdgcn_s_barrier()
; #define PG8_SCHED __builtin_amdgcn_sched_barrier(0)
; template <class Epi>
; __device__ __forceinline__ void gemm_phase(LAS unsigned char* lds, const Sched& S, const int K, const Epi& E) {
;     ...
;             const bool last = (t == nt - 2);
;             const char* a1 = cA + (size_t)(t + 1) * kstep;
;             const char* a2 = last ? nA : cA + (size_t)(t + 2) * kstep; const char* b2 = last ? nB : cB + (size_t)(t + 2) * kstep;
;             const char* a3 = a2 + kstep; const char* b3 = b2 + kstep;
;             PG8_LDB(B0, 0, 0); PG8_LDB(B1, 0, 1); PG8_SCHED; PG8_LDA(At, 0, 0); PG8_STAGE(PG8_SA(1, 1), a1 + hstepA, voffA);
;             PG8_WAIT_V(8); PG8_WAIT_L(0); PG8_BAR; PG8_MMA(0, 0, At, B0); PG8_MMA(0, 1, At, B1); PG8_BAR; PG8_SCHED;
;             PG8_LDA(At, 0, 1); PG8_STAGE(PG8_SB(0, 0), b2, voffB); PG8_STAGE(PG8_SB(0, 1), b2 + hstepB, voffB); PG8_STAGE(PG8_SA(0, 0), a2, voffA);
;             PG8_WAIT_V(8); PG8_WAIT_L(0); PG8_BAR; PG8_MMA(1, 0, At, B0); PG8_MMA(1, 1, At, B1); PG8_BAR; PG8_SCHED;
.LBB0_477:
	s_add_u32 s50, s48, 0xfff80080
	s_addc_u32 s51, s49, -1
	s_add_i32 s76, 0, 0x10000
	s_cmp_eq_u32 s92, 28
	s_cselect_b32 s53, s45, s51
	s_cselect_b32 s52, s44, s50
	s_cselect_b32 s51, s47, s73
	s_cselect_b32 s50, s46, s72
	s_add_i32 s77, 0, 0x14000
	v_add_u32_e32 v156, s76, v141
	v_add_u32_e32 v194, s77, v141
	ds_read_b128 v[144:147], v156
	ds_read_b128 v[148:151], v156 offset:1024
	ds_read_b128 v[152:155], v156 offset:2048
	ds_read_b128 v[156:159], v156 offset:3072
	ds_read_b128 v[160:163], v194
	ds_read_b128 v[164:167], v194 offset:1024
	ds_read_b128 v[168:171], v194 offset:2048
	ds_read_b128 v[198:201], v194 offset:3072
	v_lshl_add_u64 v[194:195], s[48:49], 0, v[136:137]
	s_add_i32 m0, s57, 0xc000
	ds_read_b128 v[202:205], v143
	ds_read_b128 v[206:209], v143 offset:1024
	ds_read_b128 v[210:213], v143 offset:2048
	ds_read_b128 v[214:217], v143 offset:3072
	ds_read_b128 v[218:221], v143 offset:4096
	ds_read_b128 v[228:231], v143 offset:5120
	ds_read_b128 v[232:235], v143 offset:6144
	ds_read_b128 v[236:239], v143 offset:7168
	global_load_lds_dwordx4 v[194:195], off
	v_lshl_add_u64 v[194:195], s[48:49], 0, v[138:139]
	s_add_i32 m0, s57, 0xe000
	s_nop 0
	global_load_lds_dwordx4 v[194:195], off
	s_waitcnt vmcnt(8)
	s_waitcnt lgkmcnt(0)
	s_barrier
	s_setprio 1
	s_waitcnt lgkmcnt(0)
	v_mfma_f32_16x16x32_bf16 v[124:127], v[144:147], v[202:205], v[124:127]
	v_mfma_f32_16x16x32_bf16 v[120:123], v[152:155], v[202:205], v[120:123]
	v_mfma_f32_16x16x32_bf16 v[112:115], v[144:147], v[210:213], v[112:115]
	v_mfma_f32_16x16x32_bf16 v[104:107], v[152:155], v[210:213], v[104:107]
	v_mfma_f32_16x16x32_bf16 v[96:99], v[144:147], v[218:221], v[96:99]
	v_mfma_f32_16x16x32_bf16 v[88:91], v[152:155], v[218:221], v[88:91]
	v_mfma_f32_16x16x32_bf16 v[80:83], v[144:147], v[232:235], v[80:83]
	v_mfma_f32_16x16x32_bf16 v[72:75], v[152:155], v[232:235], v[72:75]
	v_mfma_f32_16x16x32_bf16 v[124:127], v[148:151], v[206:209], v[124:127]
	v_mfma_f32_16x16x32_bf16 v[120:123], v[156:159], v[206:209], v[120:123]
	v_mfma_f32_16x16x32_bf16 v[112:115], v[148:151], v[214:217], v[112:115]
	v_mfma_f32_16x16x32_bf16 v[104:107], v[156:159], v[214:217], v[104:107]
	v_mfma_f32_16x16x32_bf16 v[96:99], v[148:151], v[228:231], v[96:99]
	v_mfma_f32_16x16x32_bf16 v[88:91], v[156:159], v[228:231], v[88:91]
	v_mfma_f32_16x16x32_bf16 v[80:83], v[148:151], v[236:239], v[80:83]
	v_mfma_f32_16x16x32_bf16 v[72:75], v[156:159], v[236:239], v[72:75]
	v_mfma_f32_16x16x32_bf16 v[116:119], v[160:163], v[202:205], v[116:119]
	v_mfma_f32_16x16x32_bf16 v[108:111], v[168:171], v[202:205], v[108:111]
	v_mfma_f32_16x16x32_bf16 v[100:103], v[160:163], v[210:213], v[100:103]
	v_mfma_f32_16x16x32_bf16 v[92:95], v[168:171], v[210:213], v[92:95]
	v_mfma_f32_16x16x32_bf16 v[84:87], v[160:163], v[218:221], v[84:87]
	v_mfma_f32_16x16x32_bf16 v[76:79], v[168:171], v[218:221], v[76:79]
	v_mfma_f32_16x16x32_bf16 v[68:71], v[160:163], v[232:235], v[68:71]
	v_mfma_f32_16x16x32_bf16 v[64:67], v[168:171], v[232:235], v[64:67]
	v_mfma_f32_16x16x32_bf16 v[116:119], v[164:167], v[206:209], v[116:119]
	v_mfma_f32_16x16x32_bf16 v[108:111], v[198:201], v[206:209], v[108:111]
	v_mfma_f32_16x16x32_bf16 v[100:103], v[164:167], v[214:217], v[100:103]
	v_mfma_f32_16x16x32_bf16 v[92:95], v[198:201], v[214:217], v[92:95]
	v_mfma_f32_16x16x32_bf16 v[84:87], v[164:167], v[228:231], v[84:87]
	v_mfma_f32_16x16x32_bf16 v[76:79], v[198:201], v[228:231], v[76:79]
	v_mfma_f32_16x16x32_bf16 v[68:71], v[164:167], v[236:239], v[68:71]
	v_mfma_f32_16x16x32_bf16 v[64:67], v[198:201], v[236:239], v[64:67]
	s_setprio 0
	s_barrier
	s_add_i32 s76, s76, s55
	v_lshl_add_u64 v[194:195], s[50:51], 0, v[132:133]
	s_mov_b32 m0, s76
	ds_read_b128 v[202:205], v143 offset:16384
	ds_read_b128 v[206:209], v143 offset:17408
	ds_read_b128 v[210:213], v143 offset:18432
	ds_read_b128 v[214:217], v143 offset:19456
	ds_read_b128 v[218:221], v143 offset:20480
	ds_read_b128 v[228:231], v143 offset:21504
	ds_read_b128 v[232:235], v143 offset:22528
	ds_read_b128 v[236:239], v143 offset:23552
	global_load_lds_dwordx4 v[194:195], off
	s_add_i32 m0, s76, 0x2000
	s_add_u32 s96, s50, 0x8000
	v_lshl_add_u64 v[224:225], s[50:51], 0, v[128:129]
	s_addc_u32 s97, s51, 0
	s_add_i32 s76, s77, s55
	global_load_lds_dwordx4 v[224:225], off
	v_lshl_add_u64 v[240:241], s[96:97], 0, v[132:133]
	s_mov_b32 m0, s76
	v_lshl_add_u64 v[242:243], s[52:53], 0, v[130:131]
	global_load_lds_dwordx4 v[240:241], off
	v_lshl_add_u64 v[240:241], s[96:97], 0, v[128:129]
	s_add_i32 m0, s76, 0x2000
	s_nop 0
	global_load_lds_dwordx4 v[240:241], off
	v_lshl_add_u64 v[240:241], s[52:53], 0, v[134:135]
	s_mov_b32 m0, s57
	s_nop 0
	global_load_lds_dwordx4 v[240:241], off
	s_mov_b32 m0, s58
	s_nop 0
	global_load_lds_dwordx4 v[242:243], off
	s_waitcnt vmcnt(8)
	s_waitcnt lgkmcnt(0)
	s_barrier
; #define PG8_STAGE(bufoff, gbase, voff) do { _Pragma("unroll") for (int _i = 0; _i < 2; ++_i) \
;         __builtin_amdgcn_global_load_lds((const unsigned*)((const char*)(gbase) + (voff)[_i]), (LAS unsigned*)(lds + (bufoff) + ldsw + _i * 8192), 16, 0, 0); } while (0)
; #define PG8_LDA(dst, b, h) do { _Pragma("unroll") for (int m = 0; m < 4; ++m) _Pragma("unroll") for (int k = 0; k < 2; ++k) dst[m][k] = *(const LAS bf16x8*)(lds + PG8_SA(b, h) + aoff + m * 2048 + k * 1024); } while (0)
; #define PG8_LDB(dst, b, h) do { _Pragma("unroll") for (int n = 0; n < 2; ++n) _Pragma("unroll") for (int k = 0; k < 2; ++k) dst[n][k] = *(const LAS bf16x8*)(lds + PG8_SB(b, h) + boff + n * 2048 + k * 1024); } while (0)
; #define PG8_MMA(ai, bj, At, Bt) do { __builtin_amdgcn_s_setprio(1); _Pragma("unroll") for (int m = 0; m < 4; ++m) _Pragma("unroll") for (int n = 0; n < 2; ++n) _Pragma("unroll") for (int k = 0; k < 2; ++k) \
;         acc[ai][bj][m][n] = __builtin_amdgcn_mfma_f32_16x16x32_bf16(Bt[n][k], At[m][k], acc[ai][bj][m][n], 0, 0, 0); __builtin_amdgcn_s_setprio(0); } while (0)
; #define PG8_WAIT_V(n) asm volatile("s_waitcnt vmcnt(" #n ")" ::: "memory")
; #define PG8_WAIT_L(n) asm volatile("s_waitcnt lgkmcnt(" #n ")" ::: "memory")
; #define PG8_BAR __builtin_amdgcn_s_barrier()
; #define PG8_SCHED __builtin_amdgcn_sched_barrier(0)
; template <class Epi>
; __device__ __forceinline__ void gemm_phase(LAS unsigned char* lds, const Sched& S, const int K, const Epi& E) {
;     ...
;             PG8_WAIT_V(8); PG8_WAIT_L(0); PG8_BAR; PG8_MMA(1, 0, At, B0); PG8_MMA(1, 1, At, B1); PG8_BAR; PG8_SCHED;
;             PG8_LDB(B0, 1, 0); PG8_LDB(B1, 1, 1); PG8_SCHED; PG8_LDA(At, 1, 0); PG8_STAGE(PG8_SA(0, 1), a2 + hstepA, voffA);
;             PG8_WAIT_V(8); PG8_WAIT_L(0); PG8_BAR; PG8_MMA(0, 0, At, B0); PG8_MMA(0, 1, At, B1); PG8_BAR; PG8_SCHED;
	s_setprio 1
	s_waitcnt lgkmcnt(0)
	v_mfma_f32_16x16x32_bf16 v[60:63], v[144:147], v[202:205], v[60:63]
	v_mfma_f32_16x16x32_bf16 v[56:59], v[152:155], v[202:205], v[56:59]
	v_mfma_f32_16x16x32_bf16 v[48:51], v[144:147], v[210:213], v[48:51]
	v_mfma_f32_16x16x32_bf16 v[40:43], v[152:155], v[210:213], v[40:43]
	v_mfma_f32_16x16x32_bf16 v[32:35], v[144:147], v[218:221], v[32:35]
	v_mfma_f32_16x16x32_bf16 v[24:27], v[152:155], v[218:221], v[24:27]
	v_mfma_f32_16x16x32_bf16 v[16:19], v[144:147], v[232:235], v[16:19]
	v_mfma_f32_16x16x32_bf16 v[8:11], v[152:155], v[232:235], v[8:11]
	v_mfma_f32_16x16x32_bf16 v[60:63], v[148:151], v[206:209], v[60:63]
	v_mfma_f32_16x16x32_bf16 v[56:59], v[156:159], v[206:209], v[56:59]
	v_mfma_f32_16x16x32_bf16 v[48:51], v[148:151], v[214:217], v[48:51]
	v_mfma_f32_16x16x32_bf16 v[40:43], v[156:159], v[214:217], v[40:43]
	v_mfma_f32_16x16x32_bf16 v[32:35], v[148:151], v[228:231], v[32:35]
	v_mfma_f32_16x16x32_bf16 v[24:27], v[156:159], v[228:231], v[24:27]
	v_mfma_f32_16x16x32_bf16 v[16:19], v[148:151], v[236:239], v[16:19]
	v_mfma_f32_16x16x32_bf16 v[8:11], v[156:159], v[236:239], v[8:11]
	v_mfma_f32_16x16x32_bf16 v[52:55], v[160:163], v[202:205], v[52:55]
	v_mfma_f32_16x16x32_bf16 v[44:47], v[168:171], v[202:205], v[44:47]
	v_mfma_f32_16x16x32_bf16 v[36:39], v[160:163], v[210:213], v[36:39]
	v_mfma_f32_16x16x32_bf16 v[28:31], v[168:171], v[210:213], v[28:31]
	v_mfma_f32_16x16x32_bf16 v[20:23], v[160:163], v[218:221], v[20:23]
	v_mfma_f32_16x16x32_bf16 v[12:15], v[168:171], v[218:221], v[12:15]
	v_mfma_f32_16x16x32_bf16 v[4:7], v[160:163], v[232:235], v[4:7]
	v_mfma_f32_16x16x32_bf16 v[0:3], v[168:171], v[232:235], v[0:3]
	v_mfma_f32_16x16x32_bf16 v[52:55], v[164:167], v[206:209], v[52:55]
	v_mfma_f32_16x16x32_bf16 v[44:47], v[198:201], v[206:209], v[44:47]
	v_mfma_f32_16x16x32_bf16 v[36:39], v[164:167], v[214:217], v[36:39]
	v_mfma_f32_16x16x32_bf16 v[28:31], v[198:201], v[214:217], v[28:31]
	v_mfma_f32_16x16x32_bf16 v[20:23], v[164:167], v[228:231], v[20:23]
	v_mfma_f32_16x16x32_bf16 v[12:15], v[198:201], v[228:231], v[12:15]
	v_mfma_f32_16x16x32_bf16 v[4:7], v[164:167], v[236:239], v[4:7]
	v_mfma_f32_16x16x32_bf16 v[0:3], v[198:201], v[236:239], v[0:3]
	s_setprio 0
	s_barrier
	s_add_i32 s76, 0, 0x18000
	s_add_i32 s77, 0, 0x1c000
	v_add_u32_e32 v156, s76, v141
	v_add_u32_e32 v198, s77, v141
	ds_read_b128 v[144:147], v156
	ds_read_b128 v[148:151], v156 offset:1024
	ds_read_b128 v[152:155], v156 offset:2048
	ds_read_b128 v[156:159], v156 offset:3072
	ds_read_b128 v[160:163], v198
	ds_read_b128 v[164:167], v198 offset:1024
	ds_read_b128 v[168:171], v198 offset:2048
	ds_read_b128 v[198:201], v198 offset:3072
	s_add_u32 s52, s52, 0x80000
	s_addc_u32 s53, s53, 0
	s_mov_b32 m0, s59
	v_lshl_add_u64 v[244:245], s[52:53], 0, v[134:135]
	ds_read_b128 v[202:205], v143 offset:32768
	ds_read_b128 v[206:209], v143 offset:33792
	ds_read_b128 v[210:213], v143 offset:34816
	ds_read_b128 v[214:217], v143 offset:35840
	ds_read_b128 v[218:221], v143 offset:36864
	ds_read_b128 v[228:231], v143 offset:37888
	ds_read_b128 v[232:235], v143 offset:38912
	ds_read_b128 v[236:239], v143 offset:39936
	global_load_lds_dwordx4 v[244:245], off
	v_lshl_add_u64 v[244:245], s[52:53], 0, v[130:131]
	s_mov_b32 m0, s60
	s_nop 0
	global_load_lds_dwordx4 v[244:245], off
	s_waitcnt vmcnt(8)
	s_waitcnt lgkmcnt(0)
	s_barrier
	s_setprio 1
	s_waitcnt lgkmcnt(0)
	v_mfma_f32_16x16x32_bf16 v[124:127], v[144:147], v[202:205], v[124:127]
	v_mfma_f32_16x16x32_bf16 v[120:123], v[152:155], v[202:205], v[120:123]
	v_mfma_f32_16x16x32_bf16 v[112:115], v[144:147], v[210:213], v[112:115]
	v_mfma_f32_16x16x32_bf16 v[104:107], v[152:155], v[210:213], v[104:107]
	v_mfma_f32_16x16x32_bf16 v[96:99], v[144:147], v[218:221], v[96:99]
	v_mfma_f32_16x16x32_bf16 v[88:91], v[152:155], v[218:221], v[88:91]
	v_mfma_f32_16x16x32_bf16 v[80:83], v[144:147], v[232:235], v[80:83]
	v_mfma_f32_16x16x32_bf16 v[72:75], v[152:155], v[232:235], v[72:75]
	v_mfma_f32_16x16x32_bf16 v[124:127], v[148:151], v[206:209], v[124:127]
	v_mfma_f32_16x16x32_bf16 v[120:123], v[156:159], v[206:209], v[120:123]
	v_mfma_f32_16x16x32_bf16 v[112:115], v[148:151], v[214:217], v[112:115]
	v_mfma_f32_16x16x32_bf16 v[104:107], v[156:159], v[214:217], v[104:107]
	v_mfma_f32_16x16x32_bf16 v[96:99], v[148:151], v[228:231], v[96:99]
	v_mfma_f32_16x16x32_bf16 v[88:91], v[156:159], v[228:231], v[88:91]
	v_mfma_f32_16x16x32_bf16 v[80:83], v[148:151], v[236:239], v[80:83]
	v_mfma_f32_16x16x32_bf16 v[72:75], v[156:159], v[236:239], v[72:75]
	v_mfma_f32_16x16x32_bf16 v[116:119], v[160:163], v[202:205], v[116:119]
	v_mfma_f32_16x16x32_bf16 v[108:111], v[168:171], v[202:205], v[108:111]
	v_mfma_f32_16x16x32_bf16 v[100:103], v[160:163], v[210:213], v[100:103]
	v_mfma_f32_16x16x32_bf16 v[92:95], v[168:171], v[210:213], v[92:95]
	v_mfma_f32_16x16x32_bf16 v[84:87], v[160:163], v[218:221], v[84:87]
	v_mfma_f32_16x16x32_bf16 v[76:79], v[168:171], v[218:221], v[76:79]
	v_mfma_f32_16x16x32_bf16 v[68:71], v[160:163], v[232:235], v[68:71]
	v_mfma_f32_16x16x32_bf16 v[64:67], v[168:171], v[232:235], v[64:67]
	v_mfma_f32_16x16x32_bf16 v[116:119], v[164:167], v[206:209], v[116:119]
	v_mfma_f32_16x16x32_bf16 v[108:111], v[198:201], v[206:209], v[108:111]
	v_mfma_f32_16x16x32_bf16 v[100:103], v[164:167], v[214:217], v[100:103]
	v_mfma_f32_16x16x32_bf16 v[92:95], v[198:201], v[214:217], v[92:95]
	v_mfma_f32_16x16x32_bf16 v[84:87], v[164:167], v[228:231], v[84:87]
	v_mfma_f32_16x16x32_bf16 v[76:79], v[198:201], v[228:231], v[76:79]
	v_mfma_f32_16x16x32_bf16 v[68:71], v[164:167], v[236:239], v[68:71]
	v_mfma_f32_16x16x32_bf16 v[64:67], v[198:201], v[236:239], v[64:67]
	s_setprio 0
	s_barrier
; #define PG8_STAGE(bufoff, gbase, voff) do { _Pragma("unroll") for (int _i = 0; _i < 2; ++_i) \
;         __builtin_amdgcn_global_load_lds((const unsigned*)((const char*)(gbase) + (voff)[_i]), (LAS unsigned*)(lds + (bufoff) + ldsw + _i * 8192), 16, 0, 0); } while (0)
; #define PG8_LDA(dst, b, h) do { _Pragma("unroll") for (int m = 0; m < 4; ++m) _Pragma("unroll") for (int k = 0; k < 2; ++k) dst[m][k] = *(const LAS bf16x8*)(lds + PG8_SA(b, h) + aoff + m * 2048 + k * 1024); } while (0)
; #define PG8_MMA(ai, bj, At, Bt) do { __builtin_amdgcn_s_setprio(1); _Pragma("unroll") for (int m = 0; m < 4; ++m) _Pragma("unroll") for (int n = 0; n < 2; ++n) _Pragma("unroll") for (int k = 0; k < 2; ++k) \
;         acc[ai][bj][m][n] = __builtin_amdgcn_mfma_f32_16x16x32_bf16(Bt[n][k], At[m][k], acc[ai][bj][m][n], 0, 0, 0); __builtin_amdgcn_s_setprio(0); } while (0)
; #define PG8_WAIT_V(n) asm volatile("s_waitcnt vmcnt(" #n ")" ::: "memory")
; #define PG8_WAIT_L(n) asm volatile("s_waitcnt lgkmcnt(" #n ")" ::: "memory")
; #define PG8_BAR __builtin_amdgcn_s_barrier()
; #define PG8_SCHED __builtin_amdgcn_sched_barrier(0)
; template <class Epi>
; __device__ __forceinline__ void gemm_phase(LAS unsigned char* lds, const Sched& S, const int K, const Epi& E) {
;     ...
;             PG8_LDA(At, 1, 1); PG8_STAGE(PG8_SB(1, 0), b3, voffB); PG8_STAGE(PG8_SB(1, 1), b3 + hstepB, voffB); PG8_STAGE(PG8_SA(1, 0), a3, voffA);
;             PG8_WAIT_V(8); PG8_WAIT_L(0); PG8_BAR; PG8_MMA(1, 0, At, B0); PG8_MMA(1, 1, At, B1); PG8_BAR; PG8_SCHED;
;         }
;         if (wr == 0) PG8_BAR;
	s_add_i32 s52, s76, s55
	v_lshl_add_u64 v[194:195], v[194:195], 0, s[74:75]
	s_mov_b32 m0, s52
	ds_read_b128 v[202:205], v143 offset:49152
	ds_read_b128 v[206:209], v143 offset:50176
	ds_read_b128 v[210:213], v143 offset:51200
	ds_read_b128 v[214:217], v143 offset:52224
	ds_read_b128 v[218:221], v143 offset:53248
	ds_read_b128 v[228:231], v143 offset:54272
	ds_read_b128 v[232:235], v143 offset:55296
	ds_read_b128 v[236:239], v143 offset:56320
	global_load_lds_dwordx4 v[194:195], off
	s_add_i32 m0, s52, 0x2000
	s_add_u32 s50, s50, 0x8080
	v_lshl_add_u64 v[194:195], v[224:225], 0, s[74:75]
	s_addc_u32 s51, s51, 0
	s_add_i32 s52, s77, s55
	global_load_lds_dwordx4 v[194:195], off
	v_lshl_add_u64 v[194:195], s[50:51], 0, v[132:133]
	s_mov_b32 m0, s52
	s_nop 0
	global_load_lds_dwordx4 v[194:195], off
	v_lshl_add_u64 v[194:195], s[50:51], 0, v[128:129]
	s_add_i32 m0, s52, 0x2000
	s_nop 0
	global_load_lds_dwordx4 v[194:195], off
	v_lshl_add_u64 v[194:195], v[240:241], 0, s[74:75]
	s_mov_b32 m0, s66
	s_nop 0
	global_load_lds_dwordx4 v[194:195], off
	v_lshl_add_u64 v[194:195], v[242:243], 0, s[74:75]
	s_mov_b32 m0, s67
	s_nop 0
	global_load_lds_dwordx4 v[194:195], off
	s_waitcnt vmcnt(8)
	s_waitcnt lgkmcnt(0)
	s_barrier
	s_setprio 1
	s_waitcnt lgkmcnt(0)
	v_mfma_f32_16x16x32_bf16 v[60:63], v[144:147], v[202:205], v[60:63]
	v_mfma_f32_16x16x32_bf16 v[56:59], v[152:155], v[202:205], v[56:59]
	v_mfma_f32_16x16x32_bf16 v[48:51], v[144:147], v[210:213], v[48:51]
	v_mfma_f32_16x16x32_bf16 v[40:43], v[152:155], v[210:213], v[40:43]
	v_mfma_f32_16x16x32_bf16 v[32:35], v[144:147], v[218:221], v[32:35]
	v_mfma_f32_16x16x32_bf16 v[24:27], v[152:155], v[218:221], v[24:27]
	v_mfma_f32_16x16x32_bf16 v[16:19], v[144:147], v[232:235], v[16:19]
	v_mfma_f32_16x16x32_bf16 v[8:11], v[152:155], v[232:235], v[8:11]
	v_mfma_f32_16x16x32_bf16 v[60:63], v[148:151], v[206:209], v[60:63]
	v_mfma_f32_16x16x32_bf16 v[56:59], v[156:159], v[206:209], v[56:59]
	v_mfma_f32_16x16x32_bf16 v[48:51], v[148:151], v[214:217], v[48:51]
	v_mfma_f32_16x16x32_bf16 v[40:43], v[156:159], v[214:217], v[40:43]
	v_mfma_f32_16x16x32_bf16 v[32:35], v[148:151], v[228:231], v[32:35]
	v_mfma_f32_16x16x32_bf16 v[24:27], v[156:159], v[228:231], v[24:27]
	v_mfma_f32_16x16x32_bf16 v[16:19], v[148:151], v[236:239], v[16:19]
	v_mfma_f32_16x16x32_bf16 v[8:11], v[156:159], v[236:239], v[8:11]
	v_mfma_f32_16x16x32_bf16 v[52:55], v[160:163], v[202:205], v[52:55]
	v_mfma_f32_16x16x32_bf16 v[44:47], v[168:171], v[202:205], v[44:47]
	v_mfma_f32_16x16x32_bf16 v[36:39], v[160:163], v[210:213], v[36:39]
	v_mfma_f32_16x16x32_bf16 v[28:31], v[168:171], v[210:213], v[28:31]
	v_mfma_f32_16x16x32_bf16 v[20:23], v[160:163], v[218:221], v[20:23]
	v_mfma_f32_16x16x32_bf16 v[12:15], v[168:171], v[218:221], v[12:15]
	v_mfma_f32_16x16x32_bf16 v[4:7], v[160:163], v[232:235], v[4:7]
	v_mfma_f32_16x16x32_bf16 v[0:3], v[168:171], v[232:235], v[0:3]
	v_mfma_f32_16x16x32_bf16 v[52:55], v[164:167], v[206:209], v[52:55]
	v_mfma_f32_16x16x32_bf16 v[44:47], v[198:201], v[206:209], v[44:47]
	v_mfma_f32_16x16x32_bf16 v[36:39], v[164:167], v[214:217], v[36:39]
	v_mfma_f32_16x16x32_bf16 v[28:31], v[198:201], v[214:217], v[28:31]
	v_mfma_f32_16x16x32_bf16 v[20:23], v[164:167], v[228:231], v[20:23]
	v_mfma_f32_16x16x32_bf16 v[12:15], v[198:201], v[228:231], v[12:15]
	v_mfma_f32_16x16x32_bf16 v[4:7], v[164:167], v[236:239], v[4:7]
	v_mfma_f32_16x16x32_bf16 v[0:3], v[198:201], v[236:239], v[0:3]
	s_setprio 0
	s_barrier
	s_add_i32 s92, s92, 2
	s_add_u32 s72, s72, 0x100
	s_addc_u32 s73, s73, 0
	s_add_u32 s48, s48, 0x100
	s_addc_u32 s49, s49, 0
	s_cmp_gt_u32 s92, 29
	s_cbranch_scc0 .LBB0_477
	s_and_b64 vcc, exec, s[36:37]
	s_cbranch_vccz .LBB0_480
	s_barrier

; #define PG8_STAGE(bufoff, gbase, voff) do { _Pragma("unroll") for (int _i = 0; _i < 2; ++_i) \
;         __builtin_amdgcn_global_load_lds((const unsigned*)((const char*)(gbase) + (voff)[_i]), (LAS unsigned*)(lds + (bufoff) + ldsw + _i * 8192), 16, 0, 0); } while (0)
; #define PG8_LDA(dst, b, h) do { _Pragma("unroll") for (int m = 0; m < 4; ++m) _Pragma("unroll") for (int k = 0; k < 2; ++k) dst[m][k] = *(const LAS bf16x8*)(lds + PG8_SA(b, h) + aoff + m * 2048 + k * 1024); } while (0)
; #define PG8_LDB(dst, b, h) do { _Pragma("unroll") for (int n = 0; n < 2; ++n) _Pragma("unroll") for (int k = 0; k < 2; ++k) dst[n][k] = *(const LAS bf16x8*)(lds + PG8_SB(b, h) + boff + n * 2048 + k * 1024); } while (0)
; #define PG8_MMA(ai, bj, At, Bt) do { __builtin_amdgcn_s_setprio(1); _Pragma("unroll") for (int m = 0; m < 4; ++m) _Pragma("unroll") for (int n = 0; n < 2; ++n) _Pragma("unroll") for (int k = 0; k < 2; ++k) \
;         acc[ai][bj][m][n] = __builtin_amdgcn_mfma_f32_16x16x32_bf16(Bt[n][k], At[m][k], acc[ai][bj][m][n], 0, 0, 0); __builtin_amdgcn_s_setprio(0); } while (0)
; #define PG8_WAIT_V(n) asm volatile("s_waitcnt vmcnt(" #n ")" ::: "memory")
; #define PG8_WAIT_L(n) asm volatile("s_waitcnt lgkmcnt(" #n ")" ::: "memory")
; #define PG8_BAR __builtin_amdgcn_s_barrier()
; #define PG8_SCHED __builtin_amdgcn_sched_barrier(0)
; template <class Epi>
; __device__ __forceinline__ void gemm_phase(LAS unsigned char* lds, const Sched& S, const int K, const Epi& E) {
;     ...
;             const bool last = (t == nt - 2);
;             const char* a1 = cA + (size_t)(t + 1) * kstep;
;             const char* a2 = last ? nA : cA + (size_t)(t + 2) * kstep; const char* b2 = last ? nB : cB + (size_t)(t + 2) * kstep;
;             const char* a3 = a2 + kstep; const char* b3 = b2 + kstep;
;             PG8_LDB(B0, 0, 0); PG8_LDB(B1, 0, 1); PG8_SCHED; PG8_LDA(At, 0, 0); PG8_STAGE(PG8_SA(1, 1), a1 + hstepA, voffA);
;             PG8_WAIT_V(8); PG8_WAIT_L(0); PG8_BAR; PG8_MMA(0, 0, At, B0); PG8_MMA(0, 1, At, B1); PG8_BAR; PG8_SCHED;
;             PG8_LDA(At, 0, 1); PG8_STAGE(PG8_SB(0, 0), b2, voffB); PG8_STAGE(PG8_SB(0, 1), b2 + hstepB, voffB); PG8_STAGE(PG8_SA(0, 0), a2, voffA);
;             PG8_WAIT_V(8); PG8_WAIT_L(0); PG8_BAR; PG8_MMA(1, 0, At, B0); PG8_MMA(1, 1, At, B1); PG8_BAR; PG8_SCHED;
.LBB0_582:
	s_add_u32 s58, s54, 0x100
	s_addc_u32 s59, s55, 0
	s_add_i32 s76, 0, 0x10000
	s_cmp_eq_u32 s73, 4
	s_cselect_b32 vcc_hi, s51, s59
	s_cselect_b32 vcc_lo, s50, s58
	v_add_u32_e32 v145, s76, v143
	s_cselect_b32 s93, s53, s72
	s_cselect_b32 s92, s52, s36
	s_add_i32 s77, 0, 0x14000
	ds_read_b128 v[146:149], v145
	ds_read_b128 v[150:153], v145 offset:1024
	ds_read_b128 v[154:157], v145 offset:2048
	ds_read_b128 v[158:161], v145 offset:3072
	v_add_u32_e32 v145, s77, v143
	ds_read_b128 v[162:165], v145
	ds_read_b128 v[166:169], v145 offset:1024
	ds_read_b128 v[198:201], v145 offset:2048
	ds_read_b128 v[202:205], v145 offset:3072
	v_lshl_add_u64 v[170:171], s[54:55], 0, v[138:139]
	s_add_i32 m0, s60, 0xc000
	ds_read_b128 v[206:209], v144
	ds_read_b128 v[210:213], v144 offset:1024
	ds_read_b128 v[214:217], v144 offset:2048
	ds_read_b128 v[218:221], v144 offset:3072
	ds_read_b128 v[228:231], v144 offset:4096
	ds_read_b128 v[232:235], v144 offset:5120
	ds_read_b128 v[236:239], v144 offset:6144
	ds_read_b128 v[240:243], v144 offset:7168
	global_load_lds_dwordx4 v[170:171], off
	v_lshl_add_u64 v[170:171], s[54:55], 0, v[140:141]
	s_add_i32 m0, s60, 0xe000
	s_nop 0
	global_load_lds_dwordx4 v[170:171], off
	s_waitcnt vmcnt(8)
	s_waitcnt lgkmcnt(0)
	s_barrier
	s_setprio 1
	s_waitcnt lgkmcnt(0)
	v_mfma_f32_16x16x32_bf16 v[124:127], v[146:149], v[206:209], v[124:127]
	v_mfma_f32_16x16x32_bf16 v[120:123], v[154:157], v[206:209], v[120:123]
	v_mfma_f32_16x16x32_bf16 v[116:119], v[146:149], v[214:217], v[116:119]
	v_mfma_f32_16x16x32_bf16 v[112:115], v[154:157], v[214:217], v[112:115]
	v_mfma_f32_16x16x32_bf16 v[108:111], v[146:149], v[228:231], v[108:111]
	v_mfma_f32_16x16x32_bf16 v[100:103], v[154:157], v[228:231], v[100:103]
	v_mfma_f32_16x16x32_bf16 v[92:95], v[146:149], v[236:239], v[92:95]
	v_mfma_f32_16x16x32_bf16 v[84:87], v[154:157], v[236:239], v[84:87]
	v_mfma_f32_16x16x32_bf16 v[124:127], v[150:153], v[210:213], v[124:127]
	v_mfma_f32_16x16x32_bf16 v[120:123], v[158:161], v[210:213], v[120:123]
	v_mfma_f32_16x16x32_bf16 v[116:119], v[150:153], v[218:221], v[116:119]
	v_mfma_f32_16x16x32_bf16 v[112:115], v[158:161], v[218:221], v[112:115]
	v_mfma_f32_16x16x32_bf16 v[108:111], v[150:153], v[232:235], v[108:111]
	v_mfma_f32_16x16x32_bf16 v[100:103], v[158:161], v[232:235], v[100:103]
	v_mfma_f32_16x16x32_bf16 v[92:95], v[150:153], v[240:243], v[92:95]
	v_mfma_f32_16x16x32_bf16 v[84:87], v[158:161], v[240:243], v[84:87]
	v_mfma_f32_16x16x32_bf16 v[104:107], v[162:165], v[206:209], v[104:107]
	v_mfma_f32_16x16x32_bf16 v[96:99], v[198:201], v[206:209], v[96:99]
	v_mfma_f32_16x16x32_bf16 v[88:91], v[162:165], v[214:217], v[88:91]
	v_mfma_f32_16x16x32_bf16 v[80:83], v[198:201], v[214:217], v[80:83]
	v_mfma_f32_16x16x32_bf16 v[76:79], v[162:165], v[228:231], v[76:79]
	v_mfma_f32_16x16x32_bf16 v[72:75], v[198:201], v[228:231], v[72:75]
	v_mfma_f32_16x16x32_bf16 v[68:71], v[162:165], v[236:239], v[68:71]
	v_mfma_f32_16x16x32_bf16 v[64:67], v[198:201], v[236:239], v[64:67]
	v_mfma_f32_16x16x32_bf16 v[104:107], v[166:169], v[210:213], v[104:107]
	v_mfma_f32_16x16x32_bf16 v[96:99], v[202:205], v[210:213], v[96:99]
	v_mfma_f32_16x16x32_bf16 v[88:91], v[166:169], v[218:221], v[88:91]
	v_mfma_f32_16x16x32_bf16 v[80:83], v[202:205], v[218:221], v[80:83]
	v_mfma_f32_16x16x32_bf16 v[76:79], v[166:169], v[232:235], v[76:79]
	v_mfma_f32_16x16x32_bf16 v[72:75], v[202:205], v[232:235], v[72:75]
	v_mfma_f32_16x16x32_bf16 v[68:71], v[166:169], v[240:243], v[68:71]
	v_mfma_f32_16x16x32_bf16 v[64:67], v[202:205], v[240:243], v[64:67]
	s_setprio 0
	s_barrier
	s_add_i32 s54, s76, s57
	v_lshl_add_u64 v[170:171], s[92:93], 0, v[132:133]
	s_mov_b32 m0, s54
	ds_read_b128 v[206:209], v144 offset:16384
	ds_read_b128 v[210:213], v144 offset:17408
	ds_read_b128 v[214:217], v144 offset:18432
	ds_read_b128 v[218:221], v144 offset:19456
	ds_read_b128 v[228:231], v144 offset:20480
	ds_read_b128 v[232:235], v144 offset:21504
	ds_read_b128 v[236:239], v144 offset:22528
	ds_read_b128 v[240:243], v144 offset:23552
	global_load_lds_dwordx4 v[170:171], off
	s_add_i32 m0, s54, 0x2000
	s_add_u32 s54, s92, 0x20000
	v_lshl_add_u64 v[194:195], s[92:93], 0, v[128:129]
	s_addc_u32 s55, s93, 0
	s_add_i32 s76, s77, s57
	global_load_lds_dwordx4 v[194:195], off
	v_lshl_add_u64 v[224:225], s[54:55], 0, v[132:133]
	s_mov_b32 m0, s76
	v_lshl_add_u64 v[244:245], vcc, 0, v[130:131]
	global_load_lds_dwordx4 v[224:225], off
	v_lshl_add_u64 v[224:225], s[54:55], 0, v[128:129]
	s_add_i32 m0, s76, 0x2000
	s_nop 0
	global_load_lds_dwordx4 v[224:225], off
	v_lshl_add_u64 v[224:225], vcc, 0, v[134:135]
	s_mov_b32 m0, s60
	s_nop 0
	global_load_lds_dwordx4 v[224:225], off
	s_mov_b32 m0, s61
	s_nop 0
	global_load_lds_dwordx4 v[244:245], off
	s_waitcnt vmcnt(8)
	s_waitcnt lgkmcnt(0)
	s_barrier
; #define PG8_STAGE(bufoff, gbase, voff) do { _Pragma("unroll") for (int _i = 0; _i < 2; ++_i) \
;         __builtin_amdgcn_global_load_lds((const unsigned*)((const char*)(gbase) + (voff)[_i]), (LAS unsigned*)(lds + (bufoff) + ldsw + _i * 8192), 16, 0, 0); } while (0)
; #define PG8_LDA(dst, b, h) do { _Pragma("unroll") for (int m = 0; m < 4; ++m) _Pragma("unroll") for (int k = 0; k < 2; ++k) dst[m][k] = *(const LAS bf16x8*)(lds + PG8_SA(b, h) + aoff + m * 2048 + k * 1024); } while (0)
; #define PG8_LDB(dst, b, h) do { _Pragma("unroll") for (int n = 0; n < 2; ++n) _Pragma("unroll") for (int k = 0; k < 2; ++k) dst[n][k] = *(const LAS bf16x8*)(lds + PG8_SB(b, h) + boff + n * 2048 + k * 1024); } while (0)
; #define PG8_MMA(ai, bj, At, Bt) do { __builtin_amdgcn_s_setprio(1); _Pragma("unroll") for (int m = 0; m < 4; ++m) _Pragma("unroll") for (int n = 0; n < 2; ++n) _Pragma("unroll") for (int k = 0; k < 2; ++k) \
;         acc[ai][bj][m][n] = __builtin_amdgcn_mfma_f32_16x16x32_bf16(Bt[n][k], At[m][k], acc[ai][bj][m][n], 0, 0, 0); __builtin_amdgcn_s_setprio(0); } while (0)
; #define PG8_WAIT_V(n) asm volatile("s_waitcnt vmcnt(" #n ")" ::: "memory")
; #define PG8_WAIT_L(n) asm volatile("s_waitcnt lgkmcnt(" #n ")" ::: "memory")
; #define PG8_BAR __builtin_amdgcn_s_barrier()
; #define PG8_SCHED __builtin_amdgcn_sched_barrier(0)
; template <class Epi>
; __device__ __forceinline__ void gemm_phase(LAS unsigned char* lds, const Sched& S, const int K, const Epi& E) {
;     ...
;             PG8_WAIT_V(8); PG8_WAIT_L(0); PG8_BAR; PG8_MMA(1, 0, At, B0); PG8_MMA(1, 1, At, B1); PG8_BAR; PG8_SCHED;
;             PG8_LDB(B0, 1, 0); PG8_LDB(B1, 1, 1); PG8_SCHED; PG8_LDA(At, 1, 0); PG8_STAGE(PG8_SA(0, 1), a2 + hstepA, voffA);
;             PG8_WAIT_V(8); PG8_WAIT_L(0); PG8_BAR; PG8_MMA(0, 0, At, B0); PG8_MMA(0, 1, At, B1); PG8_BAR; PG8_SCHED;
	s_setprio 1
	s_waitcnt lgkmcnt(0)
	v_mfma_f32_16x16x32_bf16 v[60:63], v[146:149], v[206:209], v[60:63]
	v_mfma_f32_16x16x32_bf16 v[56:59], v[154:157], v[206:209], v[56:59]
	v_mfma_f32_16x16x32_bf16 v[52:55], v[146:149], v[214:217], v[52:55]
	v_mfma_f32_16x16x32_bf16 v[48:51], v[154:157], v[214:217], v[48:51]
	v_mfma_f32_16x16x32_bf16 v[36:39], v[146:149], v[228:231], v[36:39]
	v_mfma_f32_16x16x32_bf16 v[32:35], v[154:157], v[228:231], v[32:35]
	v_mfma_f32_16x16x32_bf16 v[20:23], v[146:149], v[236:239], v[20:23]
	v_mfma_f32_16x16x32_bf16 v[16:19], v[154:157], v[236:239], v[16:19]
	v_mfma_f32_16x16x32_bf16 v[60:63], v[150:153], v[210:213], v[60:63]
	v_mfma_f32_16x16x32_bf16 v[56:59], v[158:161], v[210:213], v[56:59]
	v_mfma_f32_16x16x32_bf16 v[52:55], v[150:153], v[218:221], v[52:55]
	v_mfma_f32_16x16x32_bf16 v[48:51], v[158:161], v[218:221], v[48:51]
	v_mfma_f32_16x16x32_bf16 v[36:39], v[150:153], v[232:235], v[36:39]
	v_mfma_f32_16x16x32_bf16 v[32:35], v[158:161], v[232:235], v[32:35]
	v_mfma_f32_16x16x32_bf16 v[20:23], v[150:153], v[240:243], v[20:23]
	v_mfma_f32_16x16x32_bf16 v[16:19], v[158:161], v[240:243], v[16:19]
	v_mfma_f32_16x16x32_bf16 v[44:47], v[162:165], v[206:209], v[44:47]
	v_mfma_f32_16x16x32_bf16 v[40:43], v[198:201], v[206:209], v[40:43]
	v_mfma_f32_16x16x32_bf16 v[28:31], v[162:165], v[214:217], v[28:31]
	v_mfma_f32_16x16x32_bf16 v[24:27], v[198:201], v[214:217], v[24:27]
	v_mfma_f32_16x16x32_bf16 v[12:15], v[162:165], v[228:231], v[12:15]
	v_mfma_f32_16x16x32_bf16 v[8:11], v[198:201], v[228:231], v[8:11]
	v_mfma_f32_16x16x32_bf16 v[4:7], v[162:165], v[236:239], v[4:7]
	v_mfma_f32_16x16x32_bf16 v[0:3], v[198:201], v[236:239], v[0:3]
	v_mfma_f32_16x16x32_bf16 v[44:47], v[166:169], v[210:213], v[44:47]
	v_mfma_f32_16x16x32_bf16 v[40:43], v[202:205], v[210:213], v[40:43]
	v_mfma_f32_16x16x32_bf16 v[28:31], v[166:169], v[218:221], v[28:31]
	v_mfma_f32_16x16x32_bf16 v[24:27], v[202:205], v[218:221], v[24:27]
	v_mfma_f32_16x16x32_bf16 v[12:15], v[166:169], v[232:235], v[12:15]
	v_mfma_f32_16x16x32_bf16 v[8:11], v[202:205], v[232:235], v[8:11]
	v_mfma_f32_16x16x32_bf16 v[4:7], v[166:169], v[240:243], v[4:7]
	v_mfma_f32_16x16x32_bf16 v[0:3], v[202:205], v[240:243], v[0:3]
	s_setprio 0
	s_barrier
	s_add_i32 s76, 0, 0x18000
	v_add_u32_e32 v145, s76, v143
	s_add_i32 s77, 0, 0x1c000
	ds_read_b128 v[146:149], v145
	ds_read_b128 v[150:153], v145 offset:1024
	ds_read_b128 v[154:157], v145 offset:2048
	ds_read_b128 v[158:161], v145 offset:3072
	v_add_u32_e32 v145, s77, v143
	ds_read_b128 v[162:165], v145
	ds_read_b128 v[166:169], v145 offset:1024
	ds_read_b128 v[198:201], v145 offset:2048
	ds_read_b128 v[202:205], v145 offset:3072
	s_add_u32 s54, vcc_lo, 0x30000
	s_addc_u32 s55, vcc_hi, 0
	s_mov_b32 m0, s63
	v_lshl_add_u64 v[246:247], s[54:55], 0, v[134:135]
	ds_read_b128 v[206:209], v144 offset:32768
	ds_read_b128 v[210:213], v144 offset:33792
	ds_read_b128 v[214:217], v144 offset:34816
	ds_read_b128 v[218:221], v144 offset:35840
	ds_read_b128 v[228:231], v144 offset:36864
	ds_read_b128 v[232:235], v144 offset:37888
	ds_read_b128 v[236:239], v144 offset:38912
	ds_read_b128 v[240:243], v144 offset:39936
	global_load_lds_dwordx4 v[246:247], off
	v_lshl_add_u64 v[246:247], s[54:55], 0, v[130:131]
	s_mov_b32 m0, s67
	s_nop 0
	global_load_lds_dwordx4 v[246:247], off
	s_waitcnt vmcnt(8)
	s_waitcnt lgkmcnt(0)
	s_barrier
	s_setprio 1
	s_waitcnt lgkmcnt(0)
	v_mfma_f32_16x16x32_bf16 v[124:127], v[146:149], v[206:209], v[124:127]
	v_mfma_f32_16x16x32_bf16 v[120:123], v[154:157], v[206:209], v[120:123]
	v_mfma_f32_16x16x32_bf16 v[116:119], v[146:149], v[214:217], v[116:119]
	v_mfma_f32_16x16x32_bf16 v[112:115], v[154:157], v[214:217], v[112:115]
	v_mfma_f32_16x16x32_bf16 v[108:111], v[146:149], v[228:231], v[108:111]
	v_mfma_f32_16x16x32_bf16 v[100:103], v[154:157], v[228:231], v[100:103]
	v_mfma_f32_16x16x32_bf16 v[92:95], v[146:149], v[236:239], v[92:95]
	v_mfma_f32_16x16x32_bf16 v[84:87], v[154:157], v[236:239], v[84:87]
	v_mfma_f32_16x16x32_bf16 v[124:127], v[150:153], v[210:213], v[124:127]
	v_mfma_f32_16x16x32_bf16 v[120:123], v[158:161], v[210:213], v[120:123]
	v_mfma_f32_16x16x32_bf16 v[116:119], v[150:153], v[218:221], v[116:119]
	v_mfma_f32_16x16x32_bf16 v[112:115], v[158:161], v[218:221], v[112:115]
	v_mfma_f32_16x16x32_bf16 v[108:111], v[150:153], v[232:235], v[108:111]
	v_mfma_f32_16x16x32_bf16 v[100:103], v[158:161], v[232:235], v[100:103]
	v_mfma_f32_16x16x32_bf16 v[92:95], v[150:153], v[240:243], v[92:95]
	v_mfma_f32_16x16x32_bf16 v[84:87], v[158:161], v[240:243], v[84:87]
	v_mfma_f32_16x16x32_bf16 v[104:107], v[162:165], v[206:209], v[104:107]
	v_mfma_f32_16x16x32_bf16 v[96:99], v[198:201], v[206:209], v[96:99]
	v_mfma_f32_16x16x32_bf16 v[88:91], v[162:165], v[214:217], v[88:91]
	v_mfma_f32_16x16x32_bf16 v[80:83], v[198:201], v[214:217], v[80:83]
	v_mfma_f32_16x16x32_bf16 v[76:79], v[162:165], v[228:231], v[76:79]
	v_mfma_f32_16x16x32_bf16 v[72:75], v[198:201], v[228:231], v[72:75]
	v_mfma_f32_16x16x32_bf16 v[68:71], v[162:165], v[236:239], v[68:71]
	v_mfma_f32_16x16x32_bf16 v[64:67], v[198:201], v[236:239], v[64:67]
	v_mfma_f32_16x16x32_bf16 v[104:107], v[166:169], v[210:213], v[104:107]
	v_mfma_f32_16x16x32_bf16 v[96:99], v[202:205], v[210:213], v[96:99]
	v_mfma_f32_16x16x32_bf16 v[88:91], v[166:169], v[218:221], v[88:91]
	v_mfma_f32_16x16x32_bf16 v[80:83], v[202:205], v[218:221], v[80:83]
	v_mfma_f32_16x16x32_bf16 v[76:79], v[166:169], v[232:235], v[76:79]
	v_mfma_f32_16x16x32_bf16 v[72:75], v[202:205], v[232:235], v[72:75]
	v_mfma_f32_16x16x32_bf16 v[68:71], v[166:169], v[240:243], v[68:71]
	v_mfma_f32_16x16x32_bf16 v[64:67], v[202:205], v[240:243], v[64:67]
	s_setprio 0
	s_barrier
; #define PG8_STAGE(bufoff, gbase, voff) do { _Pragma("unroll") for (int _i = 0; _i < 2; ++_i) \
;         __builtin_amdgcn_global_load_lds((const unsigned*)((const char*)(gbase) + (voff)[_i]), (LAS unsigned*)(lds + (bufoff) + ldsw + _i * 8192), 16, 0, 0); } while (0)
; #define PG8_LDA(dst, b, h) do { _Pragma("unroll") for (int m = 0; m < 4; ++m) _Pragma("unroll") for (int k = 0; k < 2; ++k) dst[m][k] = *(const LAS bf16x8*)(lds + PG8_SA(b, h) + aoff + m * 2048 + k * 1024); } while (0)
; #define PG8_MMA(ai, bj, At, Bt) do { __builtin_amdgcn_s_setprio(1); _Pragma("unroll") for (int m = 0; m < 4; ++m) _Pragma("unroll") for (int n = 0; n < 2; ++n) _Pragma("unroll") for (int k = 0; k < 2; ++k) \
;         acc[ai][bj][m][n] = __builtin_amdgcn_mfma_f32_16x16x32_bf16(Bt[n][k], At[m][k], acc[ai][bj][m][n], 0, 0, 0); __builtin_amdgcn_s_setprio(0); } while (0)
; #define PG8_WAIT_V(n) asm volatile("s_waitcnt vmcnt(" #n ")" ::: "memory")
; #define PG8_WAIT_L(n) asm volatile("s_waitcnt lgkmcnt(" #n ")" ::: "memory")
; #define PG8_BAR __builtin_amdgcn_s_barrier()
; #define PG8_SCHED __builtin_amdgcn_sched_barrier(0)
; template <class Epi>
; __device__ __forceinline__ void gemm_phase(LAS unsigned char* lds, const Sched& S, const int K, const Epi& E) {
;     ...
;             PG8_LDA(At, 1, 1); PG8_STAGE(PG8_SB(1, 0), b3, voffB); PG8_STAGE(PG8_SB(1, 1), b3 + hstepB, voffB); PG8_STAGE(PG8_SA(1, 0), a3, voffA);
;             PG8_WAIT_V(8); PG8_WAIT_L(0); PG8_BAR; PG8_MMA(1, 0, At, B0); PG8_MMA(1, 1, At, B1); PG8_BAR; PG8_SCHED;
;         }
;         if (wr == 0) PG8_BAR;
	s_add_i32 s54, s76, s57
	v_lshl_add_u64 v[170:171], v[170:171], 0, s[74:75]
	s_mov_b32 m0, s54
	ds_read_b128 v[206:209], v144 offset:49152
	ds_read_b128 v[210:213], v144 offset:50176
	ds_read_b128 v[214:217], v144 offset:51200
	ds_read_b128 v[218:221], v144 offset:52224
	ds_read_b128 v[228:231], v144 offset:53248
	ds_read_b128 v[232:235], v144 offset:54272
	ds_read_b128 v[236:239], v144 offset:55296
	ds_read_b128 v[240:243], v144 offset:56320
	global_load_lds_dwordx4 v[170:171], off
	s_add_i32 m0, s54, 0x2000
	s_add_u32 s54, s92, 0x20080
	v_lshl_add_u64 v[170:171], v[194:195], 0, s[74:75]
	s_addc_u32 s55, s93, 0
	s_add_i32 s76, s77, s57
	global_load_lds_dwordx4 v[170:171], off
	v_lshl_add_u64 v[170:171], s[54:55], 0, v[132:133]
	s_mov_b32 m0, s76
	s_nop 0
	global_load_lds_dwordx4 v[170:171], off
	v_lshl_add_u64 v[170:171], s[54:55], 0, v[128:129]
	s_add_i32 m0, s76, 0x2000
	s_nop 0
	global_load_lds_dwordx4 v[170:171], off
	v_lshl_add_u64 v[170:171], v[224:225], 0, s[74:75]
	s_mov_b32 m0, s64
	s_nop 0
	global_load_lds_dwordx4 v[170:171], off
	v_lshl_add_u64 v[170:171], v[244:245], 0, s[74:75]
	s_mov_b32 m0, s68
	s_nop 0
	global_load_lds_dwordx4 v[170:171], off
	s_waitcnt vmcnt(8)
	s_waitcnt lgkmcnt(0)
	s_barrier
	s_setprio 1
	s_waitcnt lgkmcnt(0)
	v_mfma_f32_16x16x32_bf16 v[60:63], v[146:149], v[206:209], v[60:63]
	v_mfma_f32_16x16x32_bf16 v[56:59], v[154:157], v[206:209], v[56:59]
	v_mfma_f32_16x16x32_bf16 v[52:55], v[146:149], v[214:217], v[52:55]
	v_mfma_f32_16x16x32_bf16 v[48:51], v[154:157], v[214:217], v[48:51]
	v_mfma_f32_16x16x32_bf16 v[36:39], v[146:149], v[228:231], v[36:39]
	v_mfma_f32_16x16x32_bf16 v[32:35], v[154:157], v[228:231], v[32:35]
	v_mfma_f32_16x16x32_bf16 v[20:23], v[146:149], v[236:239], v[20:23]
	v_mfma_f32_16x16x32_bf16 v[16:19], v[154:157], v[236:239], v[16:19]
	v_mfma_f32_16x16x32_bf16 v[60:63], v[150:153], v[210:213], v[60:63]
	v_mfma_f32_16x16x32_bf16 v[56:59], v[158:161], v[210:213], v[56:59]
	v_mfma_f32_16x16x32_bf16 v[52:55], v[150:153], v[218:221], v[52:55]
	v_mfma_f32_16x16x32_bf16 v[48:51], v[158:161], v[218:221], v[48:51]
	v_mfma_f32_16x16x32_bf16 v[36:39], v[150:153], v[232:235], v[36:39]
	v_mfma_f32_16x16x32_bf16 v[32:35], v[158:161], v[232:235], v[32:35]
	v_mfma_f32_16x16x32_bf16 v[20:23], v[150:153], v[240:243], v[20:23]
	v_mfma_f32_16x16x32_bf16 v[16:19], v[158:161], v[240:243], v[16:19]
	v_mfma_f32_16x16x32_bf16 v[44:47], v[162:165], v[206:209], v[44:47]
	v_mfma_f32_16x16x32_bf16 v[40:43], v[198:201], v[206:209], v[40:43]
	v_mfma_f32_16x16x32_bf16 v[28:31], v[162:165], v[214:217], v[28:31]
	v_mfma_f32_16x16x32_bf16 v[24:27], v[198:201], v[214:217], v[24:27]
	v_mfma_f32_16x16x32_bf16 v[12:15], v[162:165], v[228:231], v[12:15]
	v_mfma_f32_16x16x32_bf16 v[8:11], v[198:201], v[228:231], v[8:11]
	v_mfma_f32_16x16x32_bf16 v[4:7], v[162:165], v[236:239], v[4:7]
	v_mfma_f32_16x16x32_bf16 v[0:3], v[198:201], v[236:239], v[0:3]
	v_mfma_f32_16x16x32_bf16 v[44:47], v[166:169], v[210:213], v[44:47]
	v_mfma_f32_16x16x32_bf16 v[40:43], v[202:205], v[210:213], v[40:43]
	v_mfma_f32_16x16x32_bf16 v[28:31], v[166:169], v[218:221], v[28:31]
	v_mfma_f32_16x16x32_bf16 v[24:27], v[202:205], v[218:221], v[24:27]
	v_mfma_f32_16x16x32_bf16 v[12:15], v[166:169], v[232:235], v[12:15]
	v_mfma_f32_16x16x32_bf16 v[8:11], v[202:205], v[232:235], v[8:11]
	v_mfma_f32_16x16x32_bf16 v[4:7], v[166:169], v[240:243], v[4:7]
	v_mfma_f32_16x16x32_bf16 v[0:3], v[202:205], v[240:243], v[0:3]
	s_setprio 0
	s_barrier
	s_add_i32 s73, s73, 2
	s_add_u32 s36, s36, 0x100
	s_addc_u32 s72, s72, 0
	s_cmp_gt_u32 s73, 5
	s_mov_b64 s[54:55], s[58:59]
	s_cbranch_scc0 .LBB0_582
	s_and_b64 vcc, exec, s[34:35]
	s_cbranch_vccz .LBB0_585
	s_barrier

; #define PG8_STAGE(bufoff, gbase, voff) do { _Pragma("unroll") for (int _i = 0; _i < 2; ++_i) \
;         __builtin_amdgcn_global_load_lds((const unsigned*)((const char*)(gbase) + (voff)[_i]), (LAS unsigned*)(lds + (bufoff) + ldsw + _i * 8192), 16, 0, 0); } while (0)
; #define PG8_LDA(dst, b, h) do { _Pragma("unroll") for (int m = 0; m < 4; ++m) _Pragma("unroll") for (int k = 0; k < 2; ++k) dst[m][k] = *(const LAS bf16x8*)(lds + PG8_SA(b, h) + aoff + m * 2048 + k * 1024); } while (0)
; #define PG8_LDB(dst, b, h) do { _Pragma("unroll") for (int n = 0; n < 2; ++n) _Pragma("unroll") for (int k = 0; k < 2; ++k) dst[n][k] = *(const LAS bf16x8*)(lds + PG8_SB(b, h) + boff + n * 2048 + k * 1024); } while (0)
; #define PG8_MMA(ai, bj, At, Bt) do { __builtin_amdgcn_s_setprio(1); _Pragma("unroll") for (int m = 0; m < 4; ++m) _Pragma("unroll") for (int n = 0; n < 2; ++n) _Pragma("unroll") for (int k = 0; k < 2; ++k) \
;         acc[ai][bj][m][n] = __builtin_amdgcn_mfma_f32_16x16x32_bf16(Bt[n][k], At[m][k], acc[ai][bj][m][n], 0, 0, 0); __builtin_amdgcn_s_setprio(0); } while (0)
; #define PG8_WAIT_V(n) asm volatile("s_waitcnt vmcnt(" #n ")" ::: "memory")
; #define PG8_WAIT_L(n) asm volatile("s_waitcnt lgkmcnt(" #n ")" ::: "memory")
; #define PG8_BAR __builtin_amdgcn_s_barrier()
; #define PG8_SCHED __builtin_amdgcn_sched_barrier(0)
; template <class Epi>
; __device__ __forceinline__ void gemm_phase(LAS unsigned char* lds, const Sched& S, const int K, const Epi& E) {
;     ...
;             const bool last = (t == nt - 2);
;             const char* a1 = cA + (size_t)(t + 1) * kstep;
;             const char* a2 = last ? nA : cA + (size_t)(t + 2) * kstep; const char* b2 = last ? nB : cB + (size_t)(t + 2) * kstep;
;             const char* a3 = a2 + kstep; const char* b3 = b2 + kstep;
;             PG8_LDB(B0, 0, 0); PG8_LDB(B1, 0, 1); PG8_SCHED; PG8_LDA(At, 0, 0); PG8_STAGE(PG8_SA(1, 1), a1 + hstepA, voffA);
;             PG8_WAIT_V(8); PG8_WAIT_L(0); PG8_BAR; PG8_MMA(0, 0, At, B0); PG8_MMA(0, 1, At, B1); PG8_BAR; PG8_SCHED;
;             PG8_LDA(At, 0, 1); PG8_STAGE(PG8_SB(0, 0), b2, voffB); PG8_STAGE(PG8_SB(0, 1), b2 + hstepB, voffB); PG8_STAGE(PG8_SA(0, 0), a2, voffA);
;             PG8_WAIT_V(8); PG8_WAIT_L(0); PG8_BAR; PG8_MMA(1, 0, At, B0); PG8_MMA(1, 1, At, B1); PG8_BAR; PG8_SCHED;
.LBB0_747:
	s_add_u32 s50, s48, 0xfffe0080
	s_addc_u32 s51, s49, -1
	s_add_i32 s69, 0, 0x10000
	s_cmp_eq_u32 s68, 4
	s_cselect_b32 s53, s35, s51
	s_cselect_b32 s52, s34, s50
	v_add_u32_e32 v140, s69, v142
	s_cselect_b32 s51, s47, s67
	s_cselect_b32 s50, s46, s43
	s_add_i32 s72, 0, 0x14000
	ds_read_b128 v[146:149], v140
	ds_read_b128 v[150:153], v140 offset:1024
	ds_read_b128 v[154:157], v140 offset:2048
	ds_read_b128 v[158:161], v140 offset:3072
	v_add_u32_e32 v140, s72, v142
	ds_read_b128 v[162:165], v140
	ds_read_b128 v[166:169], v140 offset:1024
	ds_read_b128 v[198:201], v140 offset:2048
	ds_read_b128 v[202:205], v140 offset:3072
	v_lshl_add_u64 v[140:141], s[48:49], 0, v[136:137]
	s_add_i32 m0, s55, 0xc000
	ds_read_b128 v[206:209], v145
	ds_read_b128 v[210:213], v145 offset:1024
	ds_read_b128 v[214:217], v145 offset:2048
	ds_read_b128 v[218:221], v145 offset:3072
	ds_read_b128 v[228:231], v145 offset:4096
	ds_read_b128 v[232:235], v145 offset:5120
	ds_read_b128 v[236:239], v145 offset:6144
	ds_read_b128 v[240:243], v145 offset:7168
	global_load_lds_dwordx4 v[140:141], off
	v_lshl_add_u64 v[140:141], s[48:49], 0, v[138:139]
	s_add_i32 m0, s55, 0xe000
	s_nop 0
	global_load_lds_dwordx4 v[140:141], off
	s_waitcnt vmcnt(8)
	s_waitcnt lgkmcnt(0)
	s_barrier
	s_setprio 1
	s_waitcnt lgkmcnt(0)
	v_mfma_f32_16x16x32_bf16 v[124:127], v[146:149], v[206:209], v[124:127]
	v_mfma_f32_16x16x32_bf16 v[120:123], v[154:157], v[206:209], v[120:123]
	v_mfma_f32_16x16x32_bf16 v[116:119], v[146:149], v[214:217], v[116:119]
	v_mfma_f32_16x16x32_bf16 v[108:111], v[154:157], v[214:217], v[108:111]
	v_mfma_f32_16x16x32_bf16 v[100:103], v[146:149], v[228:231], v[100:103]
	v_mfma_f32_16x16x32_bf16 v[92:95], v[154:157], v[228:231], v[92:95]
	v_mfma_f32_16x16x32_bf16 v[84:87], v[146:149], v[236:239], v[84:87]
	v_mfma_f32_16x16x32_bf16 v[76:79], v[154:157], v[236:239], v[76:79]
	v_mfma_f32_16x16x32_bf16 v[124:127], v[150:153], v[210:213], v[124:127]
	v_mfma_f32_16x16x32_bf16 v[120:123], v[158:161], v[210:213], v[120:123]
	v_mfma_f32_16x16x32_bf16 v[116:119], v[150:153], v[218:221], v[116:119]
	v_mfma_f32_16x16x32_bf16 v[108:111], v[158:161], v[218:221], v[108:111]
	v_mfma_f32_16x16x32_bf16 v[100:103], v[150:153], v[232:235], v[100:103]
	v_mfma_f32_16x16x32_bf16 v[92:95], v[158:161], v[232:235], v[92:95]
	v_mfma_f32_16x16x32_bf16 v[84:87], v[150:153], v[240:243], v[84:87]
	v_mfma_f32_16x16x32_bf16 v[76:79], v[158:161], v[240:243], v[76:79]
	v_mfma_f32_16x16x32_bf16 v[112:115], v[162:165], v[206:209], v[112:115]
	v_mfma_f32_16x16x32_bf16 v[104:107], v[198:201], v[206:209], v[104:107]
	v_mfma_f32_16x16x32_bf16 v[96:99], v[162:165], v[214:217], v[96:99]
	v_mfma_f32_16x16x32_bf16 v[88:91], v[198:201], v[214:217], v[88:91]
	v_mfma_f32_16x16x32_bf16 v[80:83], v[162:165], v[228:231], v[80:83]
	v_mfma_f32_16x16x32_bf16 v[72:75], v[198:201], v[228:231], v[72:75]
	v_mfma_f32_16x16x32_bf16 v[68:71], v[162:165], v[236:239], v[68:71]
	v_mfma_f32_16x16x32_bf16 v[64:67], v[198:201], v[236:239], v[64:67]
	v_mfma_f32_16x16x32_bf16 v[112:115], v[166:169], v[210:213], v[112:115]
	v_mfma_f32_16x16x32_bf16 v[104:107], v[202:205], v[210:213], v[104:107]
	v_mfma_f32_16x16x32_bf16 v[96:99], v[166:169], v[218:221], v[96:99]
	v_mfma_f32_16x16x32_bf16 v[88:91], v[202:205], v[218:221], v[88:91]
	v_mfma_f32_16x16x32_bf16 v[80:83], v[166:169], v[232:235], v[80:83]
	v_mfma_f32_16x16x32_bf16 v[72:75], v[202:205], v[232:235], v[72:75]
	v_mfma_f32_16x16x32_bf16 v[68:71], v[166:169], v[240:243], v[68:71]
	v_mfma_f32_16x16x32_bf16 v[64:67], v[202:205], v[240:243], v[64:67]
	s_setprio 0
	s_barrier
	s_add_i32 s69, s69, s54
	v_lshl_add_u64 v[140:141], s[50:51], 0, v[132:133]
	s_mov_b32 m0, s69
	ds_read_b128 v[206:209], v145 offset:16384
	ds_read_b128 v[210:213], v145 offset:17408
	ds_read_b128 v[214:217], v145 offset:18432
	ds_read_b128 v[218:221], v145 offset:19456
	ds_read_b128 v[228:231], v145 offset:20480
	ds_read_b128 v[232:235], v145 offset:21504
	ds_read_b128 v[236:239], v145 offset:22528
	ds_read_b128 v[240:243], v145 offset:23552
	global_load_lds_dwordx4 v[140:141], off
	s_add_i32 m0, s69, 0x2000
	s_add_u32 s70, s50, 0x20000
	v_lshl_add_u64 v[170:171], s[50:51], 0, v[128:129]
	s_addc_u32 s71, s51, 0
	s_add_i32 s69, s72, s54
	global_load_lds_dwordx4 v[170:171], off
	v_lshl_add_u64 v[194:195], s[70:71], 0, v[132:133]
	s_mov_b32 m0, s69
	v_lshl_add_u64 v[224:225], s[52:53], 0, v[130:131]
	global_load_lds_dwordx4 v[194:195], off
	v_lshl_add_u64 v[194:195], s[70:71], 0, v[128:129]
	s_add_i32 m0, s69, 0x2000
	s_nop 0
	global_load_lds_dwordx4 v[194:195], off
	v_lshl_add_u64 v[194:195], s[52:53], 0, v[134:135]
	s_mov_b32 m0, s55
	s_nop 0
	global_load_lds_dwordx4 v[194:195], off
	s_mov_b32 m0, s57
	s_nop 0
	global_load_lds_dwordx4 v[224:225], off
	s_waitcnt vmcnt(8)
	s_waitcnt lgkmcnt(0)
	s_barrier
; #define PG8_STAGE(bufoff, gbase, voff) do { _Pragma("unroll") for (int _i = 0; _i < 2; ++_i) \
;         __builtin_amdgcn_global_load_lds((const unsigned*)((const char*)(gbase) + (voff)[_i]), (LAS unsigned*)(lds + (bufoff) + ldsw + _i * 8192), 16, 0, 0); } while (0)
; #define PG8_LDA(dst, b, h) do { _Pragma("unroll") for (int m = 0; m < 4; ++m) _Pragma("unroll") for (int k = 0; k < 2; ++k) dst[m][k] = *(const LAS bf16x8*)(lds + PG8_SA(b, h) + aoff + m * 2048 + k * 1024); } while (0)
; #define PG8_LDB(dst, b, h) do { _Pragma("unroll") for (int n = 0; n < 2; ++n) _Pragma("unroll") for (int k = 0; k < 2; ++k) dst[n][k] = *(const LAS bf16x8*)(lds + PG8_SB(b, h) + boff + n * 2048 + k * 1024); } while (0)
; #define PG8_MMA(ai, bj, At, Bt) do { __builtin_amdgcn_s_setprio(1); _Pragma("unroll") for (int m = 0; m < 4; ++m) _Pragma("unroll") for (int n = 0; n < 2; ++n) _Pragma("unroll") for (int k = 0; k < 2; ++k) \
;         acc[ai][bj][m][n] = __builtin_amdgcn_mfma_f32_16x16x32_bf16(Bt[n][k], At[m][k], acc[ai][bj][m][n], 0, 0, 0); __builtin_amdgcn_s_setprio(0); } while (0)
; #define PG8_WAIT_V(n) asm volatile("s_waitcnt vmcnt(" #n ")" ::: "memory")
; #define PG8_WAIT_L(n) asm volatile("s_waitcnt lgkmcnt(" #n ")" ::: "memory")
; #define PG8_BAR __builtin_amdgcn_s_barrier()
; #define PG8_SCHED __builtin_amdgcn_sched_barrier(0)
; template <class Epi>
; __device__ __forceinline__ void gemm_phase(LAS unsigned char* lds, const Sched& S, const int K, const Epi& E) {
;     ...
;             PG8_WAIT_V(8); PG8_WAIT_L(0); PG8_BAR; PG8_MMA(1, 0, At, B0); PG8_MMA(1, 1, At, B1); PG8_BAR; PG8_SCHED;
;             PG8_LDB(B0, 1, 0); PG8_LDB(B1, 1, 1); PG8_SCHED; PG8_LDA(At, 1, 0); PG8_STAGE(PG8_SA(0, 1), a2 + hstepA, voffA);
;             PG8_WAIT_V(8); PG8_WAIT_L(0); PG8_BAR; PG8_MMA(0, 0, At, B0); PG8_MMA(0, 1, At, B1); PG8_BAR; PG8_SCHED;
	s_setprio 1
	s_waitcnt lgkmcnt(0)
	v_mfma_f32_16x16x32_bf16 v[60:63], v[146:149], v[206:209], v[60:63]
	v_mfma_f32_16x16x32_bf16 v[56:59], v[154:157], v[206:209], v[56:59]
	v_mfma_f32_16x16x32_bf16 v[52:55], v[146:149], v[214:217], v[52:55]
	v_mfma_f32_16x16x32_bf16 v[44:47], v[154:157], v[214:217], v[44:47]
	v_mfma_f32_16x16x32_bf16 v[36:39], v[146:149], v[228:231], v[36:39]
	v_mfma_f32_16x16x32_bf16 v[28:31], v[154:157], v[228:231], v[28:31]
	v_mfma_f32_16x16x32_bf16 v[20:23], v[146:149], v[236:239], v[20:23]
	v_mfma_f32_16x16x32_bf16 v[12:15], v[154:157], v[236:239], v[12:15]
	v_mfma_f32_16x16x32_bf16 v[60:63], v[150:153], v[210:213], v[60:63]
	v_mfma_f32_16x16x32_bf16 v[56:59], v[158:161], v[210:213], v[56:59]
	v_mfma_f32_16x16x32_bf16 v[52:55], v[150:153], v[218:221], v[52:55]
	v_mfma_f32_16x16x32_bf16 v[44:47], v[158:161], v[218:221], v[44:47]
	v_mfma_f32_16x16x32_bf16 v[36:39], v[150:153], v[232:235], v[36:39]
	v_mfma_f32_16x16x32_bf16 v[28:31], v[158:161], v[232:235], v[28:31]
	v_mfma_f32_16x16x32_bf16 v[20:23], v[150:153], v[240:243], v[20:23]
	v_mfma_f32_16x16x32_bf16 v[12:15], v[158:161], v[240:243], v[12:15]
	v_mfma_f32_16x16x32_bf16 v[48:51], v[162:165], v[206:209], v[48:51]
	v_mfma_f32_16x16x32_bf16 v[40:43], v[198:201], v[206:209], v[40:43]
	v_mfma_f32_16x16x32_bf16 v[32:35], v[162:165], v[214:217], v[32:35]
	v_mfma_f32_16x16x32_bf16 v[24:27], v[198:201], v[214:217], v[24:27]
	v_mfma_f32_16x16x32_bf16 v[16:19], v[162:165], v[228:231], v[16:19]
	v_mfma_f32_16x16x32_bf16 v[8:11], v[198:201], v[228:231], v[8:11]
	v_mfma_f32_16x16x32_bf16 v[4:7], v[162:165], v[236:239], v[4:7]
	v_mfma_f32_16x16x32_bf16 v[0:3], v[198:201], v[236:239], v[0:3]
	v_mfma_f32_16x16x32_bf16 v[48:51], v[166:169], v[210:213], v[48:51]
	v_mfma_f32_16x16x32_bf16 v[40:43], v[202:205], v[210:213], v[40:43]
	v_mfma_f32_16x16x32_bf16 v[32:35], v[166:169], v[218:221], v[32:35]
	v_mfma_f32_16x16x32_bf16 v[24:27], v[202:205], v[218:221], v[24:27]
	v_mfma_f32_16x16x32_bf16 v[16:19], v[166:169], v[232:235], v[16:19]
	v_mfma_f32_16x16x32_bf16 v[8:11], v[202:205], v[232:235], v[8:11]
	v_mfma_f32_16x16x32_bf16 v[4:7], v[166:169], v[240:243], v[4:7]
	v_mfma_f32_16x16x32_bf16 v[0:3], v[202:205], v[240:243], v[0:3]
	s_setprio 0
	s_barrier
	s_add_i32 s69, 0, 0x18000
	s_add_i32 s70, 0, 0x1c000
	v_add_u32_e32 v158, s69, v142
	v_add_u32_e32 v172, s70, v142
	ds_read_b128 v[146:149], v158
	ds_read_b128 v[150:153], v158 offset:1024
	ds_read_b128 v[154:157], v158 offset:2048
	ds_read_b128 v[158:161], v158 offset:3072
	ds_read_b128 v[162:165], v172
	ds_read_b128 v[166:169], v172 offset:1024
	ds_read_b128 v[198:201], v172 offset:2048
	ds_read_b128 v[202:205], v172 offset:3072
	s_add_u32 s52, s52, 0x20000
	s_addc_u32 s53, s53, 0
	s_mov_b32 m0, s58
	v_lshl_add_u64 v[244:245], s[52:53], 0, v[134:135]
	ds_read_b128 v[206:209], v145 offset:32768
	ds_read_b128 v[210:213], v145 offset:33792
	ds_read_b128 v[214:217], v145 offset:34816
	ds_read_b128 v[218:221], v145 offset:35840
	ds_read_b128 v[228:231], v145 offset:36864
	ds_read_b128 v[232:235], v145 offset:37888
	ds_read_b128 v[236:239], v145 offset:38912
	ds_read_b128 v[240:243], v145 offset:39936
	global_load_lds_dwordx4 v[244:245], off
	v_lshl_add_u64 v[244:245], s[52:53], 0, v[130:131]
	s_mov_b32 m0, s59
	s_nop 0
	global_load_lds_dwordx4 v[244:245], off
	s_waitcnt vmcnt(8)
	s_waitcnt lgkmcnt(0)
	s_barrier
	s_setprio 1
	s_waitcnt lgkmcnt(0)
	v_mfma_f32_16x16x32_bf16 v[124:127], v[146:149], v[206:209], v[124:127]
	v_mfma_f32_16x16x32_bf16 v[120:123], v[154:157], v[206:209], v[120:123]
	v_mfma_f32_16x16x32_bf16 v[116:119], v[146:149], v[214:217], v[116:119]
	v_mfma_f32_16x16x32_bf16 v[108:111], v[154:157], v[214:217], v[108:111]
	v_mfma_f32_16x16x32_bf16 v[100:103], v[146:149], v[228:231], v[100:103]
	v_mfma_f32_16x16x32_bf16 v[92:95], v[154:157], v[228:231], v[92:95]
	v_mfma_f32_16x16x32_bf16 v[84:87], v[146:149], v[236:239], v[84:87]
	v_mfma_f32_16x16x32_bf16 v[76:79], v[154:157], v[236:239], v[76:79]
	v_mfma_f32_16x16x32_bf16 v[124:127], v[150:153], v[210:213], v[124:127]
	v_mfma_f32_16x16x32_bf16 v[120:123], v[158:161], v[210:213], v[120:123]
	v_mfma_f32_16x16x32_bf16 v[116:119], v[150:153], v[218:221], v[116:119]
	v_mfma_f32_16x16x32_bf16 v[108:111], v[158:161], v[218:221], v[108:111]
	v_mfma_f32_16x16x32_bf16 v[100:103], v[150:153], v[232:235], v[100:103]
	v_mfma_f32_16x16x32_bf16 v[92:95], v[158:161], v[232:235], v[92:95]
	v_mfma_f32_16x16x32_bf16 v[84:87], v[150:153], v[240:243], v[84:87]
	v_mfma_f32_16x16x32_bf16 v[76:79], v[158:161], v[240:243], v[76:79]
	v_mfma_f32_16x16x32_bf16 v[112:115], v[162:165], v[206:209], v[112:115]
	v_mfma_f32_16x16x32_bf16 v[104:107], v[198:201], v[206:209], v[104:107]
	v_mfma_f32_16x16x32_bf16 v[96:99], v[162:165], v[214:217], v[96:99]
	v_mfma_f32_16x16x32_bf16 v[88:91], v[198:201], v[214:217], v[88:91]
	v_mfma_f32_16x16x32_bf16 v[80:83], v[162:165], v[228:231], v[80:83]
	v_mfma_f32_16x16x32_bf16 v[72:75], v[198:201], v[228:231], v[72:75]
	v_mfma_f32_16x16x32_bf16 v[68:71], v[162:165], v[236:239], v[68:71]
	v_mfma_f32_16x16x32_bf16 v[64:67], v[198:201], v[236:239], v[64:67]
	v_mfma_f32_16x16x32_bf16 v[112:115], v[166:169], v[210:213], v[112:115]
	v_mfma_f32_16x16x32_bf16 v[104:107], v[202:205], v[210:213], v[104:107]
	v_mfma_f32_16x16x32_bf16 v[96:99], v[166:169], v[218:221], v[96:99]
	v_mfma_f32_16x16x32_bf16 v[88:91], v[202:205], v[218:221], v[88:91]
	v_mfma_f32_16x16x32_bf16 v[80:83], v[166:169], v[232:235], v[80:83]
	v_mfma_f32_16x16x32_bf16 v[72:75], v[202:205], v[232:235], v[72:75]
	v_mfma_f32_16x16x32_bf16 v[68:71], v[166:169], v[240:243], v[68:71]
	v_mfma_f32_16x16x32_bf16 v[64:67], v[202:205], v[240:243], v[64:67]
	s_setprio 0
	s_barrier
; #define PG8_STAGE(bufoff, gbase, voff) do { _Pragma("unroll") for (int _i = 0; _i < 2; ++_i) \
;         __builtin_amdgcn_global_load_lds((const unsigned*)((const char*)(gbase) + (voff)[_i]), (LAS unsigned*)(lds + (bufoff) + ldsw + _i * 8192), 16, 0, 0); } while (0)
; #define PG8_LDA(dst, b, h) do { _Pragma("unroll") for (int m = 0; m < 4; ++m) _Pragma("unroll") for (int k = 0; k < 2; ++k) dst[m][k] = *(const LAS bf16x8*)(lds + PG8_SA(b, h) + aoff + m * 2048 + k * 1024); } while (0)
; #define PG8_MMA(ai, bj, At, Bt) do { __builtin_amdgcn_s_setprio(1); _Pragma("unroll") for (int m = 0; m < 4; ++m) _Pragma("unroll") for (int n = 0; n < 2; ++n) _Pragma("unroll") for (int k = 0; k < 2; ++k) \
;         acc[ai][bj][m][n] = __builtin_amdgcn_mfma_f32_16x16x32_bf16(Bt[n][k], At[m][k], acc[ai][bj][m][n], 0, 0, 0); __builtin_amdgcn_s_setprio(0); } while (0)
; #define PG8_WAIT_V(n) asm volatile("s_waitcnt vmcnt(" #n ")" ::: "memory")
; #define PG8_WAIT_L(n) asm volatile("s_waitcnt lgkmcnt(" #n ")" ::: "memory")
; #define PG8_BAR __builtin_amdgcn_s_barrier()
; #define PG8_SCHED __builtin_amdgcn_sched_barrier(0)
; template <class Epi>
; __device__ __forceinline__ void gemm_phase(LAS unsigned char* lds, const Sched& S, const int K, const Epi& E) {
;     ...
;             PG8_LDA(At, 1, 1); PG8_STAGE(PG8_SB(1, 0), b3, voffB); PG8_STAGE(PG8_SB(1, 1), b3 + hstepB, voffB); PG8_STAGE(PG8_SA(1, 0), a3, voffA);
;             PG8_WAIT_V(8); PG8_WAIT_L(0); PG8_BAR; PG8_MMA(1, 0, At, B0); PG8_MMA(1, 1, At, B1); PG8_BAR; PG8_SCHED;
;         }
;         if (wr == 0) PG8_BAR;
	s_add_i32 s52, s69, s54
	v_lshl_add_u64 v[140:141], v[140:141], 0, s[74:75]
	s_mov_b32 m0, s52
	ds_read_b128 v[206:209], v145 offset:49152
	ds_read_b128 v[210:213], v145 offset:50176
	ds_read_b128 v[214:217], v145 offset:51200
	ds_read_b128 v[218:221], v145 offset:52224
	ds_read_b128 v[228:231], v145 offset:53248
	ds_read_b128 v[232:235], v145 offset:54272
	ds_read_b128 v[236:239], v145 offset:55296
	ds_read_b128 v[240:243], v145 offset:56320
	global_load_lds_dwordx4 v[140:141], off
	s_add_i32 m0, s52, 0x2000
	s_add_u32 s50, s50, 0x20080
	v_lshl_add_u64 v[140:141], v[170:171], 0, s[74:75]
	s_addc_u32 s51, s51, 0
	s_add_i32 s52, s70, s54
	global_load_lds_dwordx4 v[140:141], off
	v_lshl_add_u64 v[140:141], s[50:51], 0, v[132:133]
	s_mov_b32 m0, s52
	s_nop 0
	global_load_lds_dwordx4 v[140:141], off
	v_lshl_add_u64 v[140:141], s[50:51], 0, v[128:129]
	s_add_i32 m0, s52, 0x2000
	s_nop 0
	global_load_lds_dwordx4 v[140:141], off
	v_lshl_add_u64 v[140:141], v[194:195], 0, s[74:75]
	s_mov_b32 m0, s60
	s_nop 0
	global_load_lds_dwordx4 v[140:141], off
	v_lshl_add_u64 v[140:141], v[224:225], 0, s[74:75]
	s_mov_b32 m0, s61
	s_nop 0
	global_load_lds_dwordx4 v[140:141], off
	s_waitcnt vmcnt(8)
	s_waitcnt lgkmcnt(0)
	s_barrier
	s_setprio 1
	s_waitcnt lgkmcnt(0)
	v_mfma_f32_16x16x32_bf16 v[60:63], v[146:149], v[206:209], v[60:63]
	v_mfma_f32_16x16x32_bf16 v[56:59], v[154:157], v[206:209], v[56:59]
	v_mfma_f32_16x16x32_bf16 v[52:55], v[146:149], v[214:217], v[52:55]
	v_mfma_f32_16x16x32_bf16 v[44:47], v[154:157], v[214:217], v[44:47]
	v_mfma_f32_16x16x32_bf16 v[36:39], v[146:149], v[228:231], v[36:39]
	v_mfma_f32_16x16x32_bf16 v[28:31], v[154:157], v[228:231], v[28:31]
	v_mfma_f32_16x16x32_bf16 v[20:23], v[146:149], v[236:239], v[20:23]
	v_mfma_f32_16x16x32_bf16 v[12:15], v[154:157], v[236:239], v[12:15]
	v_mfma_f32_16x16x32_bf16 v[60:63], v[150:153], v[210:213], v[60:63]
	v_mfma_f32_16x16x32_bf16 v[56:59], v[158:161], v[210:213], v[56:59]
	v_mfma_f32_16x16x32_bf16 v[52:55], v[150:153], v[218:221], v[52:55]
	v_mfma_f32_16x16x32_bf16 v[44:47], v[158:161], v[218:221], v[44:47]
	v_mfma_f32_16x16x32_bf16 v[36:39], v[150:153], v[232:235], v[36:39]
	v_mfma_f32_16x16x32_bf16 v[28:31], v[158:161], v[232:235], v[28:31]
	v_mfma_f32_16x16x32_bf16 v[20:23], v[150:153], v[240:243], v[20:23]
	v_mfma_f32_16x16x32_bf16 v[12:15], v[158:161], v[240:243], v[12:15]
	v_mfma_f32_16x16x32_bf16 v[48:51], v[162:165], v[206:209], v[48:51]
	v_mfma_f32_16x16x32_bf16 v[40:43], v[198:201], v[206:209], v[40:43]
	v_mfma_f32_16x16x32_bf16 v[32:35], v[162:165], v[214:217], v[32:35]
	v_mfma_f32_16x16x32_bf16 v[24:27], v[198:201], v[214:217], v[24:27]
	v_mfma_f32_16x16x32_bf16 v[16:19], v[162:165], v[228:231], v[16:19]
	v_mfma_f32_16x16x32_bf16 v[8:11], v[198:201], v[228:231], v[8:11]
	v_mfma_f32_16x16x32_bf16 v[4:7], v[162:165], v[236:239], v[4:7]
	v_mfma_f32_16x16x32_bf16 v[0:3], v[198:201], v[236:239], v[0:3]
	v_mfma_f32_16x16x32_bf16 v[48:51], v[166:169], v[210:213], v[48:51]
	v_mfma_f32_16x16x32_bf16 v[40:43], v[202:205], v[210:213], v[40:43]
	v_mfma_f32_16x16x32_bf16 v[32:35], v[166:169], v[218:221], v[32:35]
	v_mfma_f32_16x16x32_bf16 v[24:27], v[202:205], v[218:221], v[24:27]
	v_mfma_f32_16x16x32_bf16 v[16:19], v[166:169], v[232:235], v[16:19]
	v_mfma_f32_16x16x32_bf16 v[8:11], v[202:205], v[232:235], v[8:11]
	v_mfma_f32_16x16x32_bf16 v[4:7], v[166:169], v[240:243], v[4:7]
	v_mfma_f32_16x16x32_bf16 v[0:3], v[202:205], v[240:243], v[0:3]
	s_setprio 0
	s_barrier
	s_add_i32 s68, s68, 2
	s_add_u32 s43, s43, 0x100
	s_addc_u32 s67, s67, 0
	s_add_u32 s48, s48, 0x100
	s_addc_u32 s49, s49, 0
	s_cmp_gt_u32 s68, 5
	s_cbranch_scc0 .LBB0_747
	s_and_b64 vcc, exec, s[40:41]
	s_cbranch_vccz .LBB0_750
	s_barrier

; #define PG8_STAGE(bufoff, gbase, voff) do { _Pragma("unroll") for (int _i = 0; _i < 2; ++_i) \
;         __builtin_amdgcn_global_load_lds((const unsigned*)((const char*)(gbase) + (voff)[_i]), (LAS unsigned*)(lds + (bufoff) + ldsw + _i * 8192), 16, 0, 0); } while (0)
; #define PG8_LDA(dst, b, h) do { _Pragma("unroll") for (int m = 0; m < 4; ++m) _Pragma("unroll") for (int k = 0; k < 2; ++k) dst[m][k] = *(const LAS bf16x8*)(lds + PG8_SA(b, h) + aoff + m * 2048 + k * 1024); } while (0)
; #define PG8_LDB(dst, b, h) do { _Pragma("unroll") for (int n = 0; n < 2; ++n) _Pragma("unroll") for (int k = 0; k < 2; ++k) dst[n][k] = *(const LAS bf16x8*)(lds + PG8_SB(b, h) + boff + n * 2048 + k * 1024); } while (0)
; #define PG8_MMA(ai, bj, At, Bt) do { __builtin_amdgcn_s_setprio(1); _Pragma("unroll") for (int m = 0; m < 4; ++m) _Pragma("unroll") for (int n = 0; n < 2; ++n) _Pragma("unroll") for (int k = 0; k < 2; ++k) \
;         acc[ai][bj][m][n] = __builtin_amdgcn_mfma_f32_16x16x32_bf16(Bt[n][k], At[m][k], acc[ai][bj][m][n], 0, 0, 0); __builtin_amdgcn_s_setprio(0); } while (0)
; #define PG8_WAIT_V(n) asm volatile("s_waitcnt vmcnt(" #n ")" ::: "memory")
; #define PG8_WAIT_L(n) asm volatile("s_waitcnt lgkmcnt(" #n ")" ::: "memory")
; #define PG8_BAR __builtin_amdgcn_s_barrier()
; #define PG8_SCHED __builtin_amdgcn_sched_barrier(0)
; template <class Epi>
; __device__ __forceinline__ void gemm_phase(LAS unsigned char* lds, const Sched& S, const int K, const Epi& E) {
;     ...
;             const bool last = (t == nt - 2);
;             const char* a1 = cA + (size_t)(t + 1) * kstep;
;             const char* a2 = last ? nA : cA + (size_t)(t + 2) * kstep; const char* b2 = last ? nB : cB + (size_t)(t + 2) * kstep;
;             const char* a3 = a2 + kstep; const char* b3 = b2 + kstep;
;             PG8_LDB(B0, 0, 0); PG8_LDB(B1, 0, 1); PG8_SCHED; PG8_LDA(At, 0, 0); PG8_STAGE(PG8_SA(1, 1), a1 + hstepA, voffA);
;             PG8_WAIT_V(8); PG8_WAIT_L(0); PG8_BAR; PG8_MMA(0, 0, At, B0); PG8_MMA(0, 1, At, B1); PG8_BAR; PG8_SCHED;
;             PG8_LDA(At, 0, 1); PG8_STAGE(PG8_SB(0, 0), b2, voffB); PG8_STAGE(PG8_SB(0, 1), b2 + hstepB, voffB); PG8_STAGE(PG8_SA(0, 0), a2, voffA);
;             PG8_WAIT_V(8); PG8_WAIT_L(0); PG8_BAR; PG8_MMA(1, 0, At, B0); PG8_MMA(1, 1, At, B1); PG8_BAR; PG8_SCHED;
.LBB0_834:
	s_add_u32 s52, s36, 0x100
	s_addc_u32 s53, s37, 0
	s_add_i32 s76, 0, 0x10000
	s_cmp_eq_u32 s96, 8
	s_cselect_b32 s59, s29, s53
	s_cselect_b32 s58, s28, s52
	s_cselect_b32 s55, s35, vcc_hi
	s_cselect_b32 s54, s34, vcc_lo
	s_add_i32 s77, 0, 0x14000
	v_add_u32_e32 v156, s76, v140
	v_add_u32_e32 v194, s77, v140
	ds_read_b128 v[144:147], v156
	ds_read_b128 v[148:151], v156 offset:1024
	ds_read_b128 v[152:155], v156 offset:2048
	ds_read_b128 v[156:159], v156 offset:3072
	ds_read_b128 v[160:163], v194
	ds_read_b128 v[164:167], v194 offset:1024
	ds_read_b128 v[168:171], v194 offset:2048
	ds_read_b128 v[198:201], v194 offset:3072
	v_lshl_add_u64 v[194:195], s[36:37], 0, v[136:137]
	s_add_i32 m0, s67, 0xc000
	ds_read_b128 v[202:205], v143
	ds_read_b128 v[206:209], v143 offset:1024
	ds_read_b128 v[210:213], v143 offset:2048
	ds_read_b128 v[214:217], v143 offset:3072
	ds_read_b128 v[218:221], v143 offset:4096
	ds_read_b128 v[228:231], v143 offset:5120
	ds_read_b128 v[232:235], v143 offset:6144
	ds_read_b128 v[236:239], v143 offset:7168
	global_load_lds_dwordx4 v[194:195], off
	v_lshl_add_u64 v[194:195], s[36:37], 0, v[138:139]
	s_add_i32 m0, s67, 0xe000
	s_nop 0
	global_load_lds_dwordx4 v[194:195], off
	s_waitcnt vmcnt(8)
	s_waitcnt lgkmcnt(0)
	s_barrier
	s_setprio 1
	s_waitcnt lgkmcnt(0)
	v_mfma_f32_16x16x32_bf16 v[124:127], v[144:147], v[202:205], v[124:127]
	v_mfma_f32_16x16x32_bf16 v[120:123], v[152:155], v[202:205], v[120:123]
	v_mfma_f32_16x16x32_bf16 v[108:111], v[144:147], v[210:213], v[108:111]
	v_mfma_f32_16x16x32_bf16 v[104:107], v[152:155], v[210:213], v[104:107]
	v_mfma_f32_16x16x32_bf16 v[92:95], v[144:147], v[218:221], v[92:95]
	v_mfma_f32_16x16x32_bf16 v[88:91], v[152:155], v[218:221], v[88:91]
	v_mfma_f32_16x16x32_bf16 v[76:79], v[144:147], v[232:235], v[76:79]
	v_mfma_f32_16x16x32_bf16 v[72:75], v[152:155], v[232:235], v[72:75]
	v_mfma_f32_16x16x32_bf16 v[124:127], v[148:151], v[206:209], v[124:127]
	v_mfma_f32_16x16x32_bf16 v[120:123], v[156:159], v[206:209], v[120:123]
	v_mfma_f32_16x16x32_bf16 v[108:111], v[148:151], v[214:217], v[108:111]
	v_mfma_f32_16x16x32_bf16 v[104:107], v[156:159], v[214:217], v[104:107]
	v_mfma_f32_16x16x32_bf16 v[92:95], v[148:151], v[228:231], v[92:95]
	v_mfma_f32_16x16x32_bf16 v[88:91], v[156:159], v[228:231], v[88:91]
	v_mfma_f32_16x16x32_bf16 v[76:79], v[148:151], v[236:239], v[76:79]
	v_mfma_f32_16x16x32_bf16 v[72:75], v[156:159], v[236:239], v[72:75]
	v_mfma_f32_16x16x32_bf16 v[116:119], v[160:163], v[202:205], v[116:119]
	v_mfma_f32_16x16x32_bf16 v[112:115], v[168:171], v[202:205], v[112:115]
	v_mfma_f32_16x16x32_bf16 v[100:103], v[160:163], v[210:213], v[100:103]
	v_mfma_f32_16x16x32_bf16 v[96:99], v[168:171], v[210:213], v[96:99]
	v_mfma_f32_16x16x32_bf16 v[84:87], v[160:163], v[218:221], v[84:87]
	v_mfma_f32_16x16x32_bf16 v[80:83], v[168:171], v[218:221], v[80:83]
	v_mfma_f32_16x16x32_bf16 v[68:71], v[160:163], v[232:235], v[68:71]
	v_mfma_f32_16x16x32_bf16 v[64:67], v[168:171], v[232:235], v[64:67]
	v_mfma_f32_16x16x32_bf16 v[116:119], v[164:167], v[206:209], v[116:119]
	v_mfma_f32_16x16x32_bf16 v[112:115], v[198:201], v[206:209], v[112:115]
	v_mfma_f32_16x16x32_bf16 v[100:103], v[164:167], v[214:217], v[100:103]
	v_mfma_f32_16x16x32_bf16 v[96:99], v[198:201], v[214:217], v[96:99]
	v_mfma_f32_16x16x32_bf16 v[84:87], v[164:167], v[228:231], v[84:87]
	v_mfma_f32_16x16x32_bf16 v[80:83], v[198:201], v[228:231], v[80:83]
	v_mfma_f32_16x16x32_bf16 v[68:71], v[164:167], v[236:239], v[68:71]
	v_mfma_f32_16x16x32_bf16 v[64:67], v[198:201], v[236:239], v[64:67]
	s_setprio 0
	s_barrier
	s_add_i32 s36, s76, s66
	v_lshl_add_u64 v[194:195], s[54:55], 0, v[132:133]
	s_mov_b32 m0, s36
	ds_read_b128 v[202:205], v143 offset:16384
	ds_read_b128 v[206:209], v143 offset:17408
	ds_read_b128 v[210:213], v143 offset:18432
	ds_read_b128 v[214:217], v143 offset:19456
	ds_read_b128 v[218:221], v143 offset:20480
	ds_read_b128 v[228:231], v143 offset:21504
	ds_read_b128 v[232:235], v143 offset:22528
	ds_read_b128 v[236:239], v143 offset:23552
	global_load_lds_dwordx4 v[194:195], off
	s_add_i32 m0, s36, 0x2000
	s_add_u32 s36, s54, 0x30000
	v_lshl_add_u64 v[224:225], s[54:55], 0, v[128:129]
	s_addc_u32 s37, s55, 0
	s_add_i32 s76, s77, s66
	global_load_lds_dwordx4 v[224:225], off
	v_lshl_add_u64 v[240:241], s[36:37], 0, v[132:133]
	s_mov_b32 m0, s76
	v_lshl_add_u64 v[242:243], s[58:59], 0, v[130:131]
	global_load_lds_dwordx4 v[240:241], off
	v_lshl_add_u64 v[240:241], s[36:37], 0, v[128:129]
	s_add_i32 m0, s76, 0x2000
	s_nop 0
	global_load_lds_dwordx4 v[240:241], off
	v_lshl_add_u64 v[240:241], s[58:59], 0, v[134:135]
	s_mov_b32 m0, s67
	s_nop 0
	global_load_lds_dwordx4 v[240:241], off
	s_mov_b32 m0, s68
	s_nop 0
	global_load_lds_dwordx4 v[242:243], off
	s_waitcnt vmcnt(8)
	s_waitcnt lgkmcnt(0)
	s_barrier
; #define PG8_STAGE(bufoff, gbase, voff) do { _Pragma("unroll") for (int _i = 0; _i < 2; ++_i) \
;         __builtin_amdgcn_global_load_lds((const unsigned*)((const char*)(gbase) + (voff)[_i]), (LAS unsigned*)(lds + (bufoff) + ldsw + _i * 8192), 16, 0, 0); } while (0)
; #define PG8_LDA(dst, b, h) do { _Pragma("unroll") for (int m = 0; m < 4; ++m) _Pragma("unroll") for (int k = 0; k < 2; ++k) dst[m][k] = *(const LAS bf16x8*)(lds + PG8_SA(b, h) + aoff + m * 2048 + k * 1024); } while (0)
; #define PG8_LDB(dst, b, h) do { _Pragma("unroll") for (int n = 0; n < 2; ++n) _Pragma("unroll") for (int k = 0; k < 2; ++k) dst[n][k] = *(const LAS bf16x8*)(lds + PG8_SB(b, h) + boff + n * 2048 + k * 1024); } while (0)
; #define PG8_MMA(ai, bj, At, Bt) do { __builtin_amdgcn_s_setprio(1); _Pragma("unroll") for (int m = 0; m < 4; ++m) _Pragma("unroll") for (int n = 0; n < 2; ++n) _Pragma("unroll") for (int k = 0; k < 2; ++k) \
;         acc[ai][bj][m][n] = __builtin_amdgcn_mfma_f32_16x16x32_bf16(Bt[n][k], At[m][k], acc[ai][bj][m][n], 0, 0, 0); __builtin_amdgcn_s_setprio(0); } while (0)
; #define PG8_WAIT_V(n) asm volatile("s_waitcnt vmcnt(" #n ")" ::: "memory")
; #define PG8_WAIT_L(n) asm volatile("s_waitcnt lgkmcnt(" #n ")" ::: "memory")
; #define PG8_BAR __builtin_amdgcn_s_barrier()
; #define PG8_SCHED __builtin_amdgcn_sched_barrier(0)
; template <class Epi>
; __device__ __forceinline__ void gemm_phase(LAS unsigned char* lds, const Sched& S, const int K, const Epi& E) {
;     ...
;             PG8_WAIT_V(8); PG8_WAIT_L(0); PG8_BAR; PG8_MMA(1, 0, At, B0); PG8_MMA(1, 1, At, B1); PG8_BAR; PG8_SCHED;
;             PG8_LDB(B0, 1, 0); PG8_LDB(B1, 1, 1); PG8_SCHED; PG8_LDA(At, 1, 0); PG8_STAGE(PG8_SA(0, 1), a2 + hstepA, voffA);
;             PG8_WAIT_V(8); PG8_WAIT_L(0); PG8_BAR; PG8_MMA(0, 0, At, B0); PG8_MMA(0, 1, At, B1); PG8_BAR; PG8_SCHED;
	s_setprio 1
	s_waitcnt lgkmcnt(0)
	v_mfma_f32_16x16x32_bf16 v[60:63], v[144:147], v[202:205], v[60:63]
	v_mfma_f32_16x16x32_bf16 v[56:59], v[152:155], v[202:205], v[56:59]
	v_mfma_f32_16x16x32_bf16 v[44:47], v[144:147], v[210:213], v[44:47]
	v_mfma_f32_16x16x32_bf16 v[40:43], v[152:155], v[210:213], v[40:43]
	v_mfma_f32_16x16x32_bf16 v[28:31], v[144:147], v[218:221], v[28:31]
	v_mfma_f32_16x16x32_bf16 v[24:27], v[152:155], v[218:221], v[24:27]
	v_mfma_f32_16x16x32_bf16 v[12:15], v[144:147], v[232:235], v[12:15]
	v_mfma_f32_16x16x32_bf16 v[8:11], v[152:155], v[232:235], v[8:11]
	v_mfma_f32_16x16x32_bf16 v[60:63], v[148:151], v[206:209], v[60:63]
	v_mfma_f32_16x16x32_bf16 v[56:59], v[156:159], v[206:209], v[56:59]
	v_mfma_f32_16x16x32_bf16 v[44:47], v[148:151], v[214:217], v[44:47]
	v_mfma_f32_16x16x32_bf16 v[40:43], v[156:159], v[214:217], v[40:43]
	v_mfma_f32_16x16x32_bf16 v[28:31], v[148:151], v[228:231], v[28:31]
	v_mfma_f32_16x16x32_bf16 v[24:27], v[156:159], v[228:231], v[24:27]
	v_mfma_f32_16x16x32_bf16 v[12:15], v[148:151], v[236:239], v[12:15]
	v_mfma_f32_16x16x32_bf16 v[8:11], v[156:159], v[236:239], v[8:11]
	v_mfma_f32_16x16x32_bf16 v[52:55], v[160:163], v[202:205], v[52:55]
	v_mfma_f32_16x16x32_bf16 v[48:51], v[168:171], v[202:205], v[48:51]
	v_mfma_f32_16x16x32_bf16 v[36:39], v[160:163], v[210:213], v[36:39]
	v_mfma_f32_16x16x32_bf16 v[32:35], v[168:171], v[210:213], v[32:35]
	v_mfma_f32_16x16x32_bf16 v[20:23], v[160:163], v[218:221], v[20:23]
	v_mfma_f32_16x16x32_bf16 v[16:19], v[168:171], v[218:221], v[16:19]
	v_mfma_f32_16x16x32_bf16 v[4:7], v[160:163], v[232:235], v[4:7]
	v_mfma_f32_16x16x32_bf16 v[0:3], v[168:171], v[232:235], v[0:3]
	v_mfma_f32_16x16x32_bf16 v[52:55], v[164:167], v[206:209], v[52:55]
	v_mfma_f32_16x16x32_bf16 v[48:51], v[198:201], v[206:209], v[48:51]
	v_mfma_f32_16x16x32_bf16 v[36:39], v[164:167], v[214:217], v[36:39]
	v_mfma_f32_16x16x32_bf16 v[32:35], v[198:201], v[214:217], v[32:35]
	v_mfma_f32_16x16x32_bf16 v[20:23], v[164:167], v[228:231], v[20:23]
	v_mfma_f32_16x16x32_bf16 v[16:19], v[198:201], v[228:231], v[16:19]
	v_mfma_f32_16x16x32_bf16 v[4:7], v[164:167], v[236:239], v[4:7]
	v_mfma_f32_16x16x32_bf16 v[0:3], v[198:201], v[236:239], v[0:3]
	s_setprio 0
	s_barrier
	s_add_i32 s76, 0, 0x18000
	s_add_i32 s77, 0, 0x1c000
	v_add_u32_e32 v156, s76, v140
	v_add_u32_e32 v198, s77, v140
	ds_read_b128 v[144:147], v156
	ds_read_b128 v[148:151], v156 offset:1024
	ds_read_b128 v[152:155], v156 offset:2048
	ds_read_b128 v[156:159], v156 offset:3072
	ds_read_b128 v[160:163], v198
	ds_read_b128 v[164:167], v198 offset:1024
	ds_read_b128 v[168:171], v198 offset:2048
	ds_read_b128 v[198:201], v198 offset:3072
	s_add_u32 s36, s58, 0x30000
	s_addc_u32 s37, s59, 0
	s_mov_b32 m0, s69
	v_lshl_add_u64 v[244:245], s[36:37], 0, v[134:135]
	ds_read_b128 v[202:205], v143 offset:32768
	ds_read_b128 v[206:209], v143 offset:33792
	ds_read_b128 v[210:213], v143 offset:34816
	ds_read_b128 v[214:217], v143 offset:35840
	ds_read_b128 v[218:221], v143 offset:36864
	ds_read_b128 v[228:231], v143 offset:37888
	ds_read_b128 v[232:235], v143 offset:38912
	ds_read_b128 v[236:239], v143 offset:39936
	global_load_lds_dwordx4 v[244:245], off
	v_lshl_add_u64 v[244:245], s[36:37], 0, v[130:131]
	s_mov_b32 m0, s70
	s_nop 0
	global_load_lds_dwordx4 v[244:245], off
	s_waitcnt vmcnt(8)
	s_waitcnt lgkmcnt(0)
	s_barrier
	s_setprio 1
	s_waitcnt lgkmcnt(0)
	v_mfma_f32_16x16x32_bf16 v[124:127], v[144:147], v[202:205], v[124:127]
	v_mfma_f32_16x16x32_bf16 v[120:123], v[152:155], v[202:205], v[120:123]
	v_mfma_f32_16x16x32_bf16 v[108:111], v[144:147], v[210:213], v[108:111]
	v_mfma_f32_16x16x32_bf16 v[104:107], v[152:155], v[210:213], v[104:107]
	v_mfma_f32_16x16x32_bf16 v[92:95], v[144:147], v[218:221], v[92:95]
	v_mfma_f32_16x16x32_bf16 v[88:91], v[152:155], v[218:221], v[88:91]
	v_mfma_f32_16x16x32_bf16 v[76:79], v[144:147], v[232:235], v[76:79]
	v_mfma_f32_16x16x32_bf16 v[72:75], v[152:155], v[232:235], v[72:75]
	v_mfma_f32_16x16x32_bf16 v[124:127], v[148:151], v[206:209], v[124:127]
	v_mfma_f32_16x16x32_bf16 v[120:123], v[156:159], v[206:209], v[120:123]
	v_mfma_f32_16x16x32_bf16 v[108:111], v[148:151], v[214:217], v[108:111]
	v_mfma_f32_16x16x32_bf16 v[104:107], v[156:159], v[214:217], v[104:107]
	v_mfma_f32_16x16x32_bf16 v[92:95], v[148:151], v[228:231], v[92:95]
	v_mfma_f32_16x16x32_bf16 v[88:91], v[156:159], v[228:231], v[88:91]
	v_mfma_f32_16x16x32_bf16 v[76:79], v[148:151], v[236:239], v[76:79]
	v_mfma_f32_16x16x32_bf16 v[72:75], v[156:159], v[236:239], v[72:75]
	v_mfma_f32_16x16x32_bf16 v[116:119], v[160:163], v[202:205], v[116:119]
	v_mfma_f32_16x16x32_bf16 v[112:115], v[168:171], v[202:205], v[112:115]
	v_mfma_f32_16x16x32_bf16 v[100:103], v[160:163], v[210:213], v[100:103]
	v_mfma_f32_16x16x32_bf16 v[96:99], v[168:171], v[210:213], v[96:99]
	v_mfma_f32_16x16x32_bf16 v[84:87], v[160:163], v[218:221], v[84:87]
	v_mfma_f32_16x16x32_bf16 v[80:83], v[168:171], v[218:221], v[80:83]
	v_mfma_f32_16x16x32_bf16 v[68:71], v[160:163], v[232:235], v[68:71]
	v_mfma_f32_16x16x32_bf16 v[64:67], v[168:171], v[232:235], v[64:67]
	v_mfma_f32_16x16x32_bf16 v[116:119], v[164:167], v[206:209], v[116:119]
	v_mfma_f32_16x16x32_bf16 v[112:115], v[198:201], v[206:209], v[112:115]
	v_mfma_f32_16x16x32_bf16 v[100:103], v[164:167], v[214:217], v[100:103]
	v_mfma_f32_16x16x32_bf16 v[96:99], v[198:201], v[214:217], v[96:99]
	v_mfma_f32_16x16x32_bf16 v[84:87], v[164:167], v[228:231], v[84:87]
	v_mfma_f32_16x16x32_bf16 v[80:83], v[198:201], v[228:231], v[80:83]
	v_mfma_f32_16x16x32_bf16 v[68:71], v[164:167], v[236:239], v[68:71]
	v_mfma_f32_16x16x32_bf16 v[64:67], v[198:201], v[236:239], v[64:67]
	s_setprio 0
	s_barrier
; #define PG8_STAGE(bufoff, gbase, voff) do { _Pragma("unroll") for (int _i = 0; _i < 2; ++_i) \
;         __builtin_amdgcn_global_load_lds((const unsigned*)((const char*)(gbase) + (voff)[_i]), (LAS unsigned*)(lds + (bufoff) + ldsw + _i * 8192), 16, 0, 0); } while (0)
; #define PG8_LDA(dst, b, h) do { _Pragma("unroll") for (int m = 0; m < 4; ++m) _Pragma("unroll") for (int k = 0; k < 2; ++k) dst[m][k] = *(const LAS bf16x8*)(lds + PG8_SA(b, h) + aoff + m * 2048 + k * 1024); } while (0)
; #define PG8_MMA(ai, bj, At, Bt) do { __builtin_amdgcn_s_setprio(1); _Pragma("unroll") for (int m = 0; m < 4; ++m) _Pragma("unroll") for (int n = 0; n < 2; ++n) _Pragma("unroll") for (int k = 0; k < 2; ++k) \
;         acc[ai][bj][m][n] = __builtin_amdgcn_mfma_f32_16x16x32_bf16(Bt[n][k], At[m][k], acc[ai][bj][m][n], 0, 0, 0); __builtin_amdgcn_s_setprio(0); } while (0)
; #define PG8_WAIT_V(n) asm volatile("s_waitcnt vmcnt(" #n ")" ::: "memory")
; #define PG8_WAIT_L(n) asm volatile("s_waitcnt lgkmcnt(" #n ")" ::: "memory")
; #define PG8_BAR __builtin_amdgcn_s_barrier()
; #define PG8_SCHED __builtin_amdgcn_sched_barrier(0)
; template <class Epi>
; __device__ __forceinline__ void gemm_phase(LAS unsigned char* lds, const Sched& S, const int K, const Epi& E) {
;     ...
;             PG8_LDA(At, 1, 1); PG8_STAGE(PG8_SB(1, 0), b3, voffB); PG8_STAGE(PG8_SB(1, 1), b3 + hstepB, voffB); PG8_STAGE(PG8_SA(1, 0), a3, voffA);
;             PG8_WAIT_V(8); PG8_WAIT_L(0); PG8_BAR; PG8_MMA(1, 0, At, B0); PG8_MMA(1, 1, At, B1); PG8_BAR; PG8_SCHED;
;         }
;         if (wr == 0) PG8_BAR;
	s_add_i32 s36, s76, s66
	v_lshl_add_u64 v[194:195], v[194:195], 0, s[74:75]
	s_mov_b32 m0, s36
	ds_read_b128 v[202:205], v143 offset:49152
	ds_read_b128 v[206:209], v143 offset:50176
	ds_read_b128 v[210:213], v143 offset:51200
	ds_read_b128 v[214:217], v143 offset:52224
	ds_read_b128 v[218:221], v143 offset:53248
	ds_read_b128 v[228:231], v143 offset:54272
	ds_read_b128 v[232:235], v143 offset:55296
	ds_read_b128 v[236:239], v143 offset:56320
	global_load_lds_dwordx4 v[194:195], off
	s_add_i32 m0, s36, 0x2000
	s_add_u32 s36, s54, 0x30080
	v_lshl_add_u64 v[194:195], v[224:225], 0, s[74:75]
	s_addc_u32 s37, s55, 0
	s_add_i32 s54, s77, s66
	global_load_lds_dwordx4 v[194:195], off
	v_lshl_add_u64 v[194:195], s[36:37], 0, v[132:133]
	s_mov_b32 m0, s54
	s_nop 0
	global_load_lds_dwordx4 v[194:195], off
	v_lshl_add_u64 v[194:195], s[36:37], 0, v[128:129]
	s_add_i32 m0, s54, 0x2000
	s_nop 0
	global_load_lds_dwordx4 v[194:195], off
	v_lshl_add_u64 v[194:195], v[240:241], 0, s[74:75]
	s_mov_b32 m0, s71
	s_nop 0
	global_load_lds_dwordx4 v[194:195], off
	v_lshl_add_u64 v[194:195], v[242:243], 0, s[74:75]
	s_mov_b32 m0, s72
	s_nop 0
	global_load_lds_dwordx4 v[194:195], off
	s_waitcnt vmcnt(8)
	s_waitcnt lgkmcnt(0)
	s_barrier
	s_setprio 1
	s_waitcnt lgkmcnt(0)
	v_mfma_f32_16x16x32_bf16 v[60:63], v[144:147], v[202:205], v[60:63]
	v_mfma_f32_16x16x32_bf16 v[56:59], v[152:155], v[202:205], v[56:59]
	v_mfma_f32_16x16x32_bf16 v[44:47], v[144:147], v[210:213], v[44:47]
	v_mfma_f32_16x16x32_bf16 v[40:43], v[152:155], v[210:213], v[40:43]
	v_mfma_f32_16x16x32_bf16 v[28:31], v[144:147], v[218:221], v[28:31]
	v_mfma_f32_16x16x32_bf16 v[24:27], v[152:155], v[218:221], v[24:27]
	v_mfma_f32_16x16x32_bf16 v[12:15], v[144:147], v[232:235], v[12:15]
	v_mfma_f32_16x16x32_bf16 v[8:11], v[152:155], v[232:235], v[8:11]
	v_mfma_f32_16x16x32_bf16 v[60:63], v[148:151], v[206:209], v[60:63]
	v_mfma_f32_16x16x32_bf16 v[56:59], v[156:159], v[206:209], v[56:59]
	v_mfma_f32_16x16x32_bf16 v[44:47], v[148:151], v[214:217], v[44:47]
	v_mfma_f32_16x16x32_bf16 v[40:43], v[156:159], v[214:217], v[40:43]
	v_mfma_f32_16x16x32_bf16 v[28:31], v[148:151], v[228:231], v[28:31]
	v_mfma_f32_16x16x32_bf16 v[24:27], v[156:159], v[228:231], v[24:27]
	v_mfma_f32_16x16x32_bf16 v[12:15], v[148:151], v[236:239], v[12:15]
	v_mfma_f32_16x16x32_bf16 v[8:11], v[156:159], v[236:239], v[8:11]
	v_mfma_f32_16x16x32_bf16 v[52:55], v[160:163], v[202:205], v[52:55]
	v_mfma_f32_16x16x32_bf16 v[48:51], v[168:171], v[202:205], v[48:51]
	v_mfma_f32_16x16x32_bf16 v[36:39], v[160:163], v[210:213], v[36:39]
	v_mfma_f32_16x16x32_bf16 v[32:35], v[168:171], v[210:213], v[32:35]
	v_mfma_f32_16x16x32_bf16 v[20:23], v[160:163], v[218:221], v[20:23]
	v_mfma_f32_16x16x32_bf16 v[16:19], v[168:171], v[218:221], v[16:19]
	v_mfma_f32_16x16x32_bf16 v[4:7], v[160:163], v[232:235], v[4:7]
	v_mfma_f32_16x16x32_bf16 v[0:3], v[168:171], v[232:235], v[0:3]
	v_mfma_f32_16x16x32_bf16 v[52:55], v[164:167], v[206:209], v[52:55]
	v_mfma_f32_16x16x32_bf16 v[48:51], v[198:201], v[206:209], v[48:51]
	v_mfma_f32_16x16x32_bf16 v[36:39], v[164:167], v[214:217], v[36:39]
	v_mfma_f32_16x16x32_bf16 v[32:35], v[198:201], v[214:217], v[32:35]
	v_mfma_f32_16x16x32_bf16 v[20:23], v[164:167], v[228:231], v[20:23]
	v_mfma_f32_16x16x32_bf16 v[16:19], v[198:201], v[228:231], v[16:19]
	v_mfma_f32_16x16x32_bf16 v[4:7], v[164:167], v[236:239], v[4:7]
	v_mfma_f32_16x16x32_bf16 v[0:3], v[198:201], v[236:239], v[0:3]
	s_setprio 0
	s_barrier
	s_add_i32 s96, s96, 2
	s_add_u32 vcc_lo, vcc_lo, 0x100
	s_addc_u32 vcc_hi, vcc_hi, 0
	s_cmp_gt_u32 s96, 9
	s_mov_b64 s[36:37], s[52:53]
	s_cbranch_scc0 .LBB0_834
	s_and_b64 vcc, exec, s[46:47]
	s_cbranch_vccz .LBB0_837
	s_barrier

; #define PG8_STAGE(bufoff, gbase, voff) do { _Pragma("unroll") for (int _i = 0; _i < 2; ++_i) \
;         __builtin_amdgcn_global_load_lds((const unsigned*)((const char*)(gbase) + (voff)[_i]), (LAS unsigned*)(lds + (bufoff) + ldsw + _i * 8192), 16, 0, 0); } while (0)
; #define PG8_LDA(dst, b, h) do { _Pragma("unroll") for (int m = 0; m < 4; ++m) _Pragma("unroll") for (int k = 0; k < 2; ++k) dst[m][k] = *(const LAS bf16x8*)(lds + PG8_SA(b, h) + aoff + m * 2048 + k * 1024); } while (0)
; #define PG8_LDB(dst, b, h) do { _Pragma("unroll") for (int n = 0; n < 2; ++n) _Pragma("unroll") for (int k = 0; k < 2; ++k) dst[n][k] = *(const LAS bf16x8*)(lds + PG8_SB(b, h) + boff + n * 2048 + k * 1024); } while (0)
; #define PG8_MMA(ai, bj, At, Bt) do { __builtin_amdgcn_s_setprio(1); _Pragma("unroll") for (int m = 0; m < 4; ++m) _Pragma("unroll") for (int n = 0; n < 2; ++n) _Pragma("unroll") for (int k = 0; k < 2; ++k) \
;         acc[ai][bj][m][n] = __builtin_amdgcn_mfma_f32_16x16x32_bf16(Bt[n][k], At[m][k], acc[ai][bj][m][n], 0, 0, 0); __builtin_amdgcn_s_setprio(0); } while (0)
; #define PG8_WAIT_V(n) asm volatile("s_waitcnt vmcnt(" #n ")" ::: "memory")
; #define PG8_WAIT_L(n) asm volatile("s_waitcnt lgkmcnt(" #n ")" ::: "memory")
; #define PG8_BAR __builtin_amdgcn_s_barrier()
; #define PG8_SCHED __builtin_amdgcn_sched_barrier(0)
; template <class Epi>
; __device__ __forceinline__ void gemm_phase(LAS unsigned char* lds, const Sched& S, const int K, const Epi& E) {
;     ...
;             const bool last = (t == nt - 2);
;             const char* a1 = cA + (size_t)(t + 1) * kstep;
;             const char* a2 = last ? nA : cA + (size_t)(t + 2) * kstep; const char* b2 = last ? nB : cB + (size_t)(t + 2) * kstep;
;             const char* a3 = a2 + kstep; const char* b3 = b2 + kstep;
;             PG8_LDB(B0, 0, 0); PG8_LDB(B1, 0, 1); PG8_SCHED; PG8_LDA(At, 0, 0); PG8_STAGE(PG8_SA(1, 1), a1 + hstepA, voffA);
;             PG8_WAIT_V(8); PG8_WAIT_L(0); PG8_BAR; PG8_MMA(0, 0, At, B0); PG8_MMA(0, 1, At, B1); PG8_BAR; PG8_SCHED;
;             PG8_LDA(At, 0, 1); PG8_STAGE(PG8_SB(0, 0), b2, voffB); PG8_STAGE(PG8_SB(0, 1), b2 + hstepB, voffB); PG8_STAGE(PG8_SA(0, 0), a2, voffA);
;             PG8_WAIT_V(8); PG8_WAIT_L(0); PG8_BAR; PG8_MMA(1, 0, At, B0); PG8_MMA(1, 1, At, B1); PG8_BAR; PG8_SCHED;
.LBB0_993:
	s_add_u32 s58, s36, 0x100
	s_addc_u32 s59, s37, 0
	s_add_i32 s76, 0, 0x10000
	s_cmp_eq_u32 s96, 8
	s_cselect_b32 vcc_hi, s29, s59
	s_cselect_b32 vcc_lo, s28, s58
	s_cselect_b32 s93, s35, s97
	s_cselect_b32 s92, s34, s64
	s_add_i32 s77, 0, 0x14000
	v_add_u32_e32 v52, s76, v229
	v_add_u32_e32 v140, s77, v229
	ds_read_b128 v[32:35], v52
	ds_read_b128 v[36:39], v52 offset:1024
	ds_read_b128 v[48:51], v52 offset:2048
	ds_read_b128 v[52:55], v52 offset:3072
	ds_read_b128 v[104:107], v140
	ds_read_b128 v[116:119], v140 offset:1024
	ds_read_b128 v[128:131], v140 offset:2048
	ds_read_b128 v[140:143], v140 offset:3072
	v_lshl_add_u64 v[194:195], s[36:37], 0, v[204:205]
	s_add_i32 m0, s69, 0xc000
	ds_read_b128 v[144:147], v231
	ds_read_b128 v[156:159], v231 offset:1024
	ds_read_b128 v[160:163], v231 offset:2048
	ds_read_b128 v[208:211], v231 offset:3072
	ds_read_b128 v[212:215], v231 offset:4096
	ds_read_b128 v[216:219], v231 offset:5120
	ds_read_b128 v[232:235], v231 offset:6144
	ds_read_b128 v[236:239], v231 offset:7168
	global_load_lds_dwordx4 v[194:195], off
	v_lshl_add_u64 v[194:195], s[36:37], 0, v[206:207]
	s_add_i32 m0, s69, 0xe000
	s_nop 0
	global_load_lds_dwordx4 v[194:195], off
	s_waitcnt vmcnt(8)
	s_waitcnt lgkmcnt(0)
	s_barrier
	s_setprio 1
	s_waitcnt lgkmcnt(0)
	v_mfma_f32_16x16x32_bf16 v[168:171], v[32:35], v[144:147], v[168:171]
	v_mfma_f32_16x16x32_bf16 v[164:167], v[48:51], v[144:147], v[164:167]
	v_mfma_f32_16x16x32_bf16 v[136:139], v[32:35], v[160:163], v[136:139]
	v_mfma_f32_16x16x32_bf16 v[132:135], v[48:51], v[160:163], v[132:135]
	v_mfma_f32_16x16x32_bf16 v[112:115], v[32:35], v[212:215], v[112:115]
	v_mfma_f32_16x16x32_bf16 v[108:111], v[48:51], v[212:215], v[108:111]
	v_mfma_f32_16x16x32_bf16 v[92:95], v[32:35], v[232:235], v[92:95]
	v_mfma_f32_16x16x32_bf16 v[88:91], v[48:51], v[232:235], v[88:91]
	v_mfma_f32_16x16x32_bf16 v[168:171], v[36:39], v[156:159], v[168:171]
	v_mfma_f32_16x16x32_bf16 v[164:167], v[52:55], v[156:159], v[164:167]
	v_mfma_f32_16x16x32_bf16 v[136:139], v[36:39], v[208:211], v[136:139]
	v_mfma_f32_16x16x32_bf16 v[132:135], v[52:55], v[208:211], v[132:135]
	v_mfma_f32_16x16x32_bf16 v[112:115], v[36:39], v[216:219], v[112:115]
	v_mfma_f32_16x16x32_bf16 v[108:111], v[52:55], v[216:219], v[108:111]
	v_mfma_f32_16x16x32_bf16 v[92:95], v[36:39], v[236:239], v[92:95]
	v_mfma_f32_16x16x32_bf16 v[88:91], v[52:55], v[236:239], v[88:91]
	v_mfma_f32_16x16x32_bf16 v[152:155], v[104:107], v[144:147], v[152:155]
	v_mfma_f32_16x16x32_bf16 v[124:127], v[104:107], v[160:163], v[124:127]
	v_mfma_f32_16x16x32_bf16 v[120:123], v[128:131], v[160:163], v[120:123]
	v_mfma_f32_16x16x32_bf16 v[100:103], v[104:107], v[212:215], v[100:103]
	v_mfma_f32_16x16x32_bf16 v[96:99], v[128:131], v[212:215], v[96:99]
	v_mfma_f32_16x16x32_bf16 v[84:87], v[104:107], v[232:235], v[84:87]
	v_mfma_f32_16x16x32_bf16 v[80:83], v[128:131], v[232:235], v[80:83]
	v_mfma_f32_16x16x32_bf16 v[152:155], v[116:119], v[156:159], v[152:155]
	v_mfma_f32_16x16x32_bf16 v[144:147], v[128:131], v[144:147], v[148:151]
	v_mfma_f32_16x16x32_bf16 v[124:127], v[116:119], v[208:211], v[124:127]
	v_mfma_f32_16x16x32_bf16 v[120:123], v[140:143], v[208:211], v[120:123]
	v_mfma_f32_16x16x32_bf16 v[100:103], v[116:119], v[216:219], v[100:103]
	v_mfma_f32_16x16x32_bf16 v[96:99], v[140:143], v[216:219], v[96:99]
	v_mfma_f32_16x16x32_bf16 v[84:87], v[116:119], v[236:239], v[84:87]
	v_mfma_f32_16x16x32_bf16 v[80:83], v[140:143], v[236:239], v[80:83]
	v_mfma_f32_16x16x32_bf16 v[144:147], v[140:143], v[156:159], v[144:147]
	s_setprio 0
	s_barrier
	s_add_i32 s36, s76, s68
	v_lshl_add_u64 v[194:195], s[92:93], 0, v[172:173]
	s_mov_b32 m0, s36
	ds_read_b128 v[148:151], v231 offset:16384
	ds_read_b128 v[156:159], v231 offset:17408
	ds_read_b128 v[160:163], v231 offset:18432
	ds_read_b128 v[208:211], v231 offset:19456
	ds_read_b128 v[212:215], v231 offset:20480
	ds_read_b128 v[216:219], v231 offset:21504
	ds_read_b128 v[232:235], v231 offset:22528
	ds_read_b128 v[236:239], v231 offset:23552
	global_load_lds_dwordx4 v[194:195], off
	s_add_i32 m0, s36, 0x2000
	s_add_u32 s36, s92, 0x30000
	v_lshl_add_u64 v[220:221], s[92:93], 0, v[198:199]
	s_addc_u32 s37, s93, 0
	s_add_i32 s76, s77, s68
	global_load_lds_dwordx4 v[220:221], off
	v_lshl_add_u64 v[224:225], s[36:37], 0, v[172:173]
	s_mov_b32 m0, s76
	v_lshl_add_u64 v[240:241], vcc, 0, v[200:201]
	global_load_lds_dwordx4 v[224:225], off
	v_lshl_add_u64 v[224:225], s[36:37], 0, v[198:199]
	s_add_i32 m0, s76, 0x2000
	s_nop 0
	global_load_lds_dwordx4 v[224:225], off
	v_lshl_add_u64 v[224:225], vcc, 0, v[202:203]
	s_mov_b32 m0, s69
	s_nop 0
	global_load_lds_dwordx4 v[224:225], off
	s_mov_b32 m0, s70
	s_nop 0
	global_load_lds_dwordx4 v[240:241], off
	s_waitcnt vmcnt(8)
	s_waitcnt lgkmcnt(0)
	s_barrier
; #define PG8_STAGE(bufoff, gbase, voff) do { _Pragma("unroll") for (int _i = 0; _i < 2; ++_i) \
;         __builtin_amdgcn_global_load_lds((const unsigned*)((const char*)(gbase) + (voff)[_i]), (LAS unsigned*)(lds + (bufoff) + ldsw + _i * 8192), 16, 0, 0); } while (0)
; #define PG8_LDA(dst, b, h) do { _Pragma("unroll") for (int m = 0; m < 4; ++m) _Pragma("unroll") for (int k = 0; k < 2; ++k) dst[m][k] = *(const LAS bf16x8*)(lds + PG8_SA(b, h) + aoff + m * 2048 + k * 1024); } while (0)
; #define PG8_LDB(dst, b, h) do { _Pragma("unroll") for (int n = 0; n < 2; ++n) _Pragma("unroll") for (int k = 0; k < 2; ++k) dst[n][k] = *(const LAS bf16x8*)(lds + PG8_SB(b, h) + boff + n * 2048 + k * 1024); } while (0)
; #define PG8_MMA(ai, bj, At, Bt) do { __builtin_amdgcn_s_setprio(1); _Pragma("unroll") for (int m = 0; m < 4; ++m) _Pragma("unroll") for (int n = 0; n < 2; ++n) _Pragma("unroll") for (int k = 0; k < 2; ++k) \
;         acc[ai][bj][m][n] = __builtin_amdgcn_mfma_f32_16x16x32_bf16(Bt[n][k], At[m][k], acc[ai][bj][m][n], 0, 0, 0); __builtin_amdgcn_s_setprio(0); } while (0)
; #define PG8_WAIT_V(n) asm volatile("s_waitcnt vmcnt(" #n ")" ::: "memory")
; #define PG8_WAIT_L(n) asm volatile("s_waitcnt lgkmcnt(" #n ")" ::: "memory")
; #define PG8_BAR __builtin_amdgcn_s_barrier()
; #define PG8_SCHED __builtin_amdgcn_sched_barrier(0)
; template <class Epi>
; __device__ __forceinline__ void gemm_phase(LAS unsigned char* lds, const Sched& S, const int K, const Epi& E) {
;     ...
;             PG8_WAIT_V(8); PG8_WAIT_L(0); PG8_BAR; PG8_MMA(1, 0, At, B0); PG8_MMA(1, 1, At, B1); PG8_BAR; PG8_SCHED;
;             PG8_LDB(B0, 1, 0); PG8_LDB(B1, 1, 1); PG8_SCHED; PG8_LDA(At, 1, 0); PG8_STAGE(PG8_SA(0, 1), a2 + hstepA, voffA);
;             PG8_WAIT_V(8); PG8_WAIT_L(0); PG8_BAR; PG8_MMA(0, 0, At, B0); PG8_MMA(0, 1, At, B1); PG8_BAR; PG8_SCHED;
	s_setprio 1
	s_waitcnt lgkmcnt(0)
	v_mfma_f32_16x16x32_bf16 v[76:79], v[32:35], v[148:151], v[76:79]
	v_mfma_f32_16x16x32_bf16 v[72:75], v[48:51], v[148:151], v[72:75]
	v_mfma_f32_16x16x32_bf16 v[60:63], v[32:35], v[160:163], v[60:63]
	v_mfma_f32_16x16x32_bf16 v[56:59], v[48:51], v[160:163], v[56:59]
	v_mfma_f32_16x16x32_bf16 v[28:31], v[32:35], v[212:215], v[28:31]
	v_mfma_f32_16x16x32_bf16 v[24:27], v[48:51], v[212:215], v[24:27]
	v_mfma_f32_16x16x32_bf16 v[12:15], v[32:35], v[232:235], v[12:15]
	v_mfma_f32_16x16x32_bf16 v[8:11], v[48:51], v[232:235], v[8:11]
	v_mfma_f32_16x16x32_bf16 v[76:79], v[36:39], v[156:159], v[76:79]
	v_mfma_f32_16x16x32_bf16 v[72:75], v[52:55], v[156:159], v[72:75]
	v_mfma_f32_16x16x32_bf16 v[60:63], v[36:39], v[208:211], v[60:63]
	v_mfma_f32_16x16x32_bf16 v[56:59], v[52:55], v[208:211], v[56:59]
	v_mfma_f32_16x16x32_bf16 v[28:31], v[36:39], v[216:219], v[28:31]
	v_mfma_f32_16x16x32_bf16 v[24:27], v[52:55], v[216:219], v[24:27]
	v_mfma_f32_16x16x32_bf16 v[12:15], v[36:39], v[236:239], v[12:15]
	v_mfma_f32_16x16x32_bf16 v[8:11], v[52:55], v[236:239], v[8:11]
	v_mfma_f32_16x16x32_bf16 v[44:47], v[104:107], v[160:163], v[44:47]
	v_mfma_f32_16x16x32_bf16 v[40:43], v[128:131], v[160:163], v[40:43]
	v_mfma_f32_16x16x32_bf16 v[20:23], v[104:107], v[212:215], v[20:23]
	v_mfma_f32_16x16x32_bf16 v[16:19], v[128:131], v[212:215], v[16:19]
	v_mfma_f32_16x16x32_bf16 v[4:7], v[104:107], v[232:235], v[4:7]
	v_mfma_f32_16x16x32_bf16 v[0:3], v[128:131], v[232:235], v[0:3]
	v_mfma_f32_16x16x32_bf16 v[32:35], v[104:107], v[148:151], v[68:71]
	v_mfma_f32_16x16x32_bf16 v[36:39], v[128:131], v[148:151], v[64:67]
	v_mfma_f32_16x16x32_bf16 v[44:47], v[116:119], v[208:211], v[44:47]
	v_mfma_f32_16x16x32_bf16 v[40:43], v[140:143], v[208:211], v[40:43]
	v_mfma_f32_16x16x32_bf16 v[20:23], v[116:119], v[216:219], v[20:23]
	v_mfma_f32_16x16x32_bf16 v[16:19], v[140:143], v[216:219], v[16:19]
	v_mfma_f32_16x16x32_bf16 v[4:7], v[116:119], v[236:239], v[4:7]
	v_mfma_f32_16x16x32_bf16 v[0:3], v[140:143], v[236:239], v[0:3]
	v_mfma_f32_16x16x32_bf16 v[32:35], v[116:119], v[156:159], v[32:35]
	v_mfma_f32_16x16x32_bf16 v[36:39], v[140:143], v[156:159], v[36:39]
	s_setprio 0
	s_barrier
	s_add_i32 s76, 0, 0x18000
	s_add_i32 s77, 0, 0x1c000
	v_add_u32_e32 v68, s76, v229
	v_add_u32_e32 v140, s77, v229
	ds_read_b128 v[48:51], v68
	ds_read_b128 v[52:55], v68 offset:1024
	ds_read_b128 v[64:67], v68 offset:2048
	ds_read_b128 v[68:71], v68 offset:3072
	ds_read_b128 v[104:107], v140
	ds_read_b128 v[116:119], v140 offset:1024
	ds_read_b128 v[128:131], v140 offset:2048
	ds_read_b128 v[140:143], v140 offset:3072
	s_add_u32 s36, vcc_lo, 0x30000
	s_addc_u32 s37, vcc_hi, 0
	s_mov_b32 m0, s71
	v_lshl_add_u64 v[242:243], s[36:37], 0, v[202:203]
	ds_read_b128 v[148:151], v231 offset:32768
	ds_read_b128 v[156:159], v231 offset:33792
	ds_read_b128 v[160:163], v231 offset:34816
	ds_read_b128 v[208:211], v231 offset:35840
	ds_read_b128 v[212:215], v231 offset:36864
	ds_read_b128 v[216:219], v231 offset:37888
	ds_read_b128 v[232:235], v231 offset:38912
	ds_read_b128 v[236:239], v231 offset:39936
	global_load_lds_dwordx4 v[242:243], off
	v_lshl_add_u64 v[242:243], s[36:37], 0, v[200:201]
	s_mov_b32 m0, s72
	s_nop 0
	global_load_lds_dwordx4 v[242:243], off
	s_waitcnt vmcnt(8)
	s_waitcnt lgkmcnt(0)
	s_barrier
	s_setprio 1
	s_waitcnt lgkmcnt(0)
	v_mfma_f32_16x16x32_bf16 v[168:171], v[48:51], v[148:151], v[168:171]
	v_mfma_f32_16x16x32_bf16 v[164:167], v[64:67], v[148:151], v[164:167]
	v_mfma_f32_16x16x32_bf16 v[136:139], v[48:51], v[160:163], v[136:139]
	v_mfma_f32_16x16x32_bf16 v[132:135], v[64:67], v[160:163], v[132:135]
	v_mfma_f32_16x16x32_bf16 v[112:115], v[48:51], v[212:215], v[112:115]
	v_mfma_f32_16x16x32_bf16 v[108:111], v[64:67], v[212:215], v[108:111]
	v_mfma_f32_16x16x32_bf16 v[92:95], v[48:51], v[232:235], v[92:95]
	v_mfma_f32_16x16x32_bf16 v[88:91], v[64:67], v[232:235], v[88:91]
	v_mfma_f32_16x16x32_bf16 v[168:171], v[52:55], v[156:159], v[168:171]
	v_mfma_f32_16x16x32_bf16 v[164:167], v[68:71], v[156:159], v[164:167]
	v_mfma_f32_16x16x32_bf16 v[136:139], v[52:55], v[208:211], v[136:139]
	v_mfma_f32_16x16x32_bf16 v[132:135], v[68:71], v[208:211], v[132:135]
	v_mfma_f32_16x16x32_bf16 v[112:115], v[52:55], v[216:219], v[112:115]
	v_mfma_f32_16x16x32_bf16 v[108:111], v[68:71], v[216:219], v[108:111]
	v_mfma_f32_16x16x32_bf16 v[92:95], v[52:55], v[236:239], v[92:95]
	v_mfma_f32_16x16x32_bf16 v[88:91], v[68:71], v[236:239], v[88:91]
	v_mfma_f32_16x16x32_bf16 v[152:155], v[104:107], v[148:151], v[152:155]
	v_mfma_f32_16x16x32_bf16 v[144:147], v[128:131], v[148:151], v[144:147]
	v_mfma_f32_16x16x32_bf16 v[124:127], v[104:107], v[160:163], v[124:127]
	v_mfma_f32_16x16x32_bf16 v[120:123], v[128:131], v[160:163], v[120:123]
	v_mfma_f32_16x16x32_bf16 v[100:103], v[104:107], v[212:215], v[100:103]
	v_mfma_f32_16x16x32_bf16 v[96:99], v[128:131], v[212:215], v[96:99]
	v_mfma_f32_16x16x32_bf16 v[84:87], v[104:107], v[232:235], v[84:87]
	v_mfma_f32_16x16x32_bf16 v[80:83], v[128:131], v[232:235], v[80:83]
	v_mfma_f32_16x16x32_bf16 v[152:155], v[116:119], v[156:159], v[152:155]
	v_mfma_f32_16x16x32_bf16 v[148:151], v[140:143], v[156:159], v[144:147]
	v_mfma_f32_16x16x32_bf16 v[124:127], v[116:119], v[208:211], v[124:127]
	v_mfma_f32_16x16x32_bf16 v[120:123], v[140:143], v[208:211], v[120:123]
	v_mfma_f32_16x16x32_bf16 v[100:103], v[116:119], v[216:219], v[100:103]
	v_mfma_f32_16x16x32_bf16 v[96:99], v[140:143], v[216:219], v[96:99]
	v_mfma_f32_16x16x32_bf16 v[84:87], v[116:119], v[236:239], v[84:87]
	v_mfma_f32_16x16x32_bf16 v[80:83], v[140:143], v[236:239], v[80:83]
	s_setprio 0
	s_barrier
; #define PG8_STAGE(bufoff, gbase, voff) do { _Pragma("unroll") for (int _i = 0; _i < 2; ++_i) \
;         __builtin_amdgcn_global_load_lds((const unsigned*)((const char*)(gbase) + (voff)[_i]), (LAS unsigned*)(lds + (bufoff) + ldsw + _i * 8192), 16, 0, 0); } while (0)
; #define PG8_LDA(dst, b, h) do { _Pragma("unroll") for (int m = 0; m < 4; ++m) _Pragma("unroll") for (int k = 0; k < 2; ++k) dst[m][k] = *(const LAS bf16x8*)(lds + PG8_SA(b, h) + aoff + m * 2048 + k * 1024); } while (0)
; #define PG8_MMA(ai, bj, At, Bt) do { __builtin_amdgcn_s_setprio(1); _Pragma("unroll") for (int m = 0; m < 4; ++m) _Pragma("unroll") for (int n = 0; n < 2; ++n) _Pragma("unroll") for (int k = 0; k < 2; ++k) \
;         acc[ai][bj][m][n] = __builtin_amdgcn_mfma_f32_16x16x32_bf16(Bt[n][k], At[m][k], acc[ai][bj][m][n], 0, 0, 0); __builtin_amdgcn_s_setprio(0); } while (0)
; #define PG8_WAIT_V(n) asm volatile("s_waitcnt vmcnt(" #n ")" ::: "memory")
; #define PG8_WAIT_L(n) asm volatile("s_waitcnt lgkmcnt(" #n ")" ::: "memory")
; #define PG8_BAR __builtin_amdgcn_s_barrier()
; #define PG8_SCHED __builtin_amdgcn_sched_barrier(0)
; template <class Epi>
; __device__ __forceinline__ void gemm_phase(LAS unsigned char* lds, const Sched& S, const int K, const Epi& E) {
;     ...
;             PG8_LDA(At, 1, 1); PG8_STAGE(PG8_SB(1, 0), b3, voffB); PG8_STAGE(PG8_SB(1, 1), b3 + hstepB, voffB); PG8_STAGE(PG8_SA(1, 0), a3, voffA);
;             PG8_WAIT_V(8); PG8_WAIT_L(0); PG8_BAR; PG8_MMA(1, 0, At, B0); PG8_MMA(1, 1, At, B1); PG8_BAR; PG8_SCHED;
;         }
;         if (wr == 0) PG8_BAR;
	s_add_i32 s36, s76, s68
	v_lshl_add_u64 v[194:195], v[194:195], 0, s[74:75]
	s_mov_b32 m0, s36
	ds_read_b128 v[144:147], v231 offset:49152
	ds_read_b128 v[156:159], v231 offset:50176
	ds_read_b128 v[160:163], v231 offset:51200
	ds_read_b128 v[208:211], v231 offset:52224
	ds_read_b128 v[212:215], v231 offset:53248
	ds_read_b128 v[216:219], v231 offset:54272
	ds_read_b128 v[232:235], v231 offset:55296
	ds_read_b128 v[236:239], v231 offset:56320
	global_load_lds_dwordx4 v[194:195], off
	s_add_i32 m0, s36, 0x2000
	s_add_u32 s36, s92, 0x30080
	v_lshl_add_u64 v[194:195], v[220:221], 0, s[74:75]
	s_addc_u32 s37, s93, 0
	s_add_i32 s76, s77, s68
	global_load_lds_dwordx4 v[194:195], off
	v_lshl_add_u64 v[194:195], s[36:37], 0, v[172:173]
	s_mov_b32 m0, s76
	s_nop 0
	global_load_lds_dwordx4 v[194:195], off
	v_lshl_add_u64 v[194:195], s[36:37], 0, v[198:199]
	s_add_i32 m0, s76, 0x2000
	s_nop 0
	global_load_lds_dwordx4 v[194:195], off
	v_lshl_add_u64 v[194:195], v[224:225], 0, s[74:75]
	s_mov_b32 m0, s2
	s_nop 0
	global_load_lds_dwordx4 v[194:195], off
	v_lshl_add_u64 v[194:195], v[240:241], 0, s[74:75]
	s_mov_b32 m0, s73
	s_nop 0
	global_load_lds_dwordx4 v[194:195], off
	s_waitcnt vmcnt(8)
	s_waitcnt lgkmcnt(0)
	s_barrier
	s_setprio 1
	s_waitcnt lgkmcnt(0)
	v_mfma_f32_16x16x32_bf16 v[76:79], v[48:51], v[144:147], v[76:79]
	v_mfma_f32_16x16x32_bf16 v[72:75], v[64:67], v[144:147], v[72:75]
	v_mfma_f32_16x16x32_bf16 v[60:63], v[48:51], v[160:163], v[60:63]
	v_mfma_f32_16x16x32_bf16 v[56:59], v[64:67], v[160:163], v[56:59]
	v_mfma_f32_16x16x32_bf16 v[28:31], v[48:51], v[212:215], v[28:31]
	v_mfma_f32_16x16x32_bf16 v[24:27], v[64:67], v[212:215], v[24:27]
	v_mfma_f32_16x16x32_bf16 v[12:15], v[48:51], v[232:235], v[12:15]
	v_mfma_f32_16x16x32_bf16 v[8:11], v[64:67], v[232:235], v[8:11]
	v_mfma_f32_16x16x32_bf16 v[76:79], v[52:55], v[156:159], v[76:79]
	v_mfma_f32_16x16x32_bf16 v[72:75], v[68:71], v[156:159], v[72:75]
	v_mfma_f32_16x16x32_bf16 v[60:63], v[52:55], v[208:211], v[60:63]
	v_mfma_f32_16x16x32_bf16 v[56:59], v[68:71], v[208:211], v[56:59]
	v_mfma_f32_16x16x32_bf16 v[28:31], v[52:55], v[216:219], v[28:31]
	v_mfma_f32_16x16x32_bf16 v[24:27], v[68:71], v[216:219], v[24:27]
	v_mfma_f32_16x16x32_bf16 v[12:15], v[52:55], v[236:239], v[12:15]
	v_mfma_f32_16x16x32_bf16 v[8:11], v[68:71], v[236:239], v[8:11]
	v_mfma_f32_16x16x32_bf16 v[32:35], v[104:107], v[144:147], v[32:35]
	v_mfma_f32_16x16x32_bf16 v[68:71], v[116:119], v[156:159], v[32:35]
	v_mfma_f32_16x16x32_bf16 v[32:35], v[128:131], v[144:147], v[36:39]
	v_mfma_f32_16x16x32_bf16 v[64:67], v[140:143], v[156:159], v[32:35]
	v_mfma_f32_16x16x32_bf16 v[32:35], v[104:107], v[160:163], v[44:47]
	v_mfma_f32_16x16x32_bf16 v[44:47], v[116:119], v[208:211], v[32:35]
	v_mfma_f32_16x16x32_bf16 v[32:35], v[128:131], v[160:163], v[40:43]
	v_mfma_f32_16x16x32_bf16 v[20:23], v[104:107], v[212:215], v[20:23]
	v_mfma_f32_16x16x32_bf16 v[16:19], v[128:131], v[212:215], v[16:19]
	v_mfma_f32_16x16x32_bf16 v[4:7], v[104:107], v[232:235], v[4:7]
	v_mfma_f32_16x16x32_bf16 v[0:3], v[128:131], v[232:235], v[0:3]
	v_mfma_f32_16x16x32_bf16 v[40:43], v[140:143], v[208:211], v[32:35]
	v_mfma_f32_16x16x32_bf16 v[20:23], v[116:119], v[216:219], v[20:23]
	v_mfma_f32_16x16x32_bf16 v[16:19], v[140:143], v[216:219], v[16:19]
	v_mfma_f32_16x16x32_bf16 v[4:7], v[116:119], v[236:239], v[4:7]
	v_mfma_f32_16x16x32_bf16 v[0:3], v[140:143], v[236:239], v[0:3]
	s_setprio 0
	s_barrier
	s_add_i32 s96, s96, 2
	s_add_u32 s64, s64, 0x100
	s_addc_u32 s97, s97, 0
	s_cmp_gt_u32 s96, 9
	s_mov_b64 s[36:37], s[58:59]
	s_cbranch_scc0 .LBB0_993
	s_and_b64 vcc, exec, s[50:51]
	s_cbranch_vccz .LBB0_996
	s_barrier

; #define PG8_STAGE(bufoff, gbase, voff) do { _Pragma("unroll") for (int _i = 0; _i < 2; ++_i) \
;         __builtin_amdgcn_global_load_lds((const unsigned*)((const char*)(gbase) + (voff)[_i]), (LAS unsigned*)(lds + (bufoff) + ldsw + _i * 8192), 16, 0, 0); } while (0)
; #define PG8_LDA(dst, b, h) do { _Pragma("unroll") for (int m = 0; m < 4; ++m) _Pragma("unroll") for (int k = 0; k < 2; ++k) dst[m][k] = *(const LAS bf16x8*)(lds + PG8_SA(b, h) + aoff + m * 2048 + k * 1024); } while (0)
; #define PG8_LDB(dst, b, h) do { _Pragma("unroll") for (int n = 0; n < 2; ++n) _Pragma("unroll") for (int k = 0; k < 2; ++k) dst[n][k] = *(const LAS bf16x8*)(lds + PG8_SB(b, h) + boff + n * 2048 + k * 1024); } while (0)
; #define PG8_MMA(ai, bj, At, Bt) do { __builtin_amdgcn_s_setprio(1); _Pragma("unroll") for (int m = 0; m < 4; ++m) _Pragma("unroll") for (int n = 0; n < 2; ++n) _Pragma("unroll") for (int k = 0; k < 2; ++k) \
;         acc[ai][bj][m][n] = __builtin_amdgcn_mfma_f32_16x16x32_bf16(Bt[n][k], At[m][k], acc[ai][bj][m][n], 0, 0, 0); __builtin_amdgcn_s_setprio(0); } while (0)
; #define PG8_WAIT_V(n) asm volatile("s_waitcnt vmcnt(" #n ")" ::: "memory")
; #define PG8_WAIT_L(n) asm volatile("s_waitcnt lgkmcnt(" #n ")" ::: "memory")
; #define PG8_BAR __builtin_amdgcn_s_barrier()
; #define PG8_SCHED __builtin_amdgcn_sched_barrier(0)
; template <class Epi>
; __device__ __forceinline__ void gemm_phase(LAS unsigned char* lds, const Sched& S, const int K, const Epi& E) {
;     ...
;             const bool last = (t == nt - 2);
;             const char* a1 = cA + (size_t)(t + 1) * kstep;
;             const char* a2 = last ? nA : cA + (size_t)(t + 2) * kstep; const char* b2 = last ? nB : cB + (size_t)(t + 2) * kstep;
;             const char* a3 = a2 + kstep; const char* b3 = b2 + kstep;
;             PG8_LDB(B0, 0, 0); PG8_LDB(B1, 0, 1); PG8_SCHED; PG8_LDA(At, 0, 0); PG8_STAGE(PG8_SA(1, 1), a1 + hstepA, voffA);
;             PG8_WAIT_V(8); PG8_WAIT_L(0); PG8_BAR; PG8_MMA(0, 0, At, B0); PG8_MMA(0, 1, At, B1); PG8_BAR; PG8_SCHED;
;             PG8_LDA(At, 0, 1); PG8_STAGE(PG8_SB(0, 0), b2, voffB); PG8_STAGE(PG8_SB(0, 1), b2 + hstepB, voffB); PG8_STAGE(PG8_SA(0, 0), a2, voffA);
;             PG8_WAIT_V(8); PG8_WAIT_L(0); PG8_BAR; PG8_MMA(1, 0, At, B0); PG8_MMA(1, 1, At, B1); PG8_BAR; PG8_SCHED;
.LBB0_1239:
	s_add_u32 s52, s36, 0xfff80080
	s_addc_u32 s53, s37, -1
	s_add_i32 s76, 0, 0x10000
	s_cmp_eq_u32 vcc_lo, 28
	s_cselect_b32 s55, s29, s53
	s_cselect_b32 s54, s28, s52
	s_cselect_b32 s53, s35, s97
	s_cselect_b32 s52, s34, s47
	s_add_i32 s78, 0, 0x14000
	v_add_u32_e32 v140, s76, v165
	v_add_u32_e32 v162, s78, v165
	ds_read_b128 v[128:131], v140
	ds_read_b128 v[132:135], v140 offset:1024
	ds_read_b128 v[136:139], v140 offset:2048
	ds_read_b128 v[140:143], v140 offset:3072
	ds_read_b128 v[144:147], v162
	ds_read_b128 v[148:151], v162 offset:1024
	ds_read_b128 v[152:155], v162 offset:2048
	ds_read_b128 v[168:171], v162 offset:3072
	v_lshl_add_u64 v[162:163], s[36:37], 0, v[160:161]
	s_add_i32 m0, s60, 0xc000
	ds_read_b128 v[198:201], v167
	ds_read_b128 v[202:205], v167 offset:1024
	ds_read_b128 v[206:209], v167 offset:2048
	ds_read_b128 v[210:213], v167 offset:3072
	ds_read_b128 v[214:217], v167 offset:4096
	ds_read_b128 v[218:221], v167 offset:5120
	ds_read_b128 v[228:231], v167 offset:6144
	ds_read_b128 v[232:235], v167 offset:7168
	global_load_lds_dwordx4 v[162:163], off
	v_lshl_add_u64 v[162:163], s[36:37], 0, v[158:159]
	s_add_i32 m0, s60, 0xe000
	s_nop 0
	global_load_lds_dwordx4 v[162:163], off
	s_waitcnt vmcnt(8)
	s_waitcnt lgkmcnt(0)
	s_barrier
	s_setprio 1
	s_waitcnt lgkmcnt(0)
	v_mfma_f32_16x16x32_bf16 v[124:127], v[128:131], v[198:201], v[124:127]
	v_mfma_f32_16x16x32_bf16 v[120:123], v[136:139], v[198:201], v[120:123]
	v_mfma_f32_16x16x32_bf16 v[116:119], v[128:131], v[206:209], v[116:119]
	v_mfma_f32_16x16x32_bf16 v[104:107], v[136:139], v[206:209], v[104:107]
	v_mfma_f32_16x16x32_bf16 v[100:103], v[128:131], v[214:217], v[100:103]
	v_mfma_f32_16x16x32_bf16 v[88:91], v[136:139], v[214:217], v[88:91]
	v_mfma_f32_16x16x32_bf16 v[84:87], v[128:131], v[228:231], v[84:87]
	v_mfma_f32_16x16x32_bf16 v[72:75], v[136:139], v[228:231], v[72:75]
	v_mfma_f32_16x16x32_bf16 v[124:127], v[132:135], v[202:205], v[124:127]
	v_mfma_f32_16x16x32_bf16 v[120:123], v[140:143], v[202:205], v[120:123]
	v_mfma_f32_16x16x32_bf16 v[116:119], v[132:135], v[210:213], v[116:119]
	v_mfma_f32_16x16x32_bf16 v[104:107], v[140:143], v[210:213], v[104:107]
	v_mfma_f32_16x16x32_bf16 v[100:103], v[132:135], v[218:221], v[100:103]
	v_mfma_f32_16x16x32_bf16 v[88:91], v[140:143], v[218:221], v[88:91]
	v_mfma_f32_16x16x32_bf16 v[84:87], v[132:135], v[232:235], v[84:87]
	v_mfma_f32_16x16x32_bf16 v[72:75], v[140:143], v[232:235], v[72:75]
	v_mfma_f32_16x16x32_bf16 v[112:115], v[144:147], v[198:201], v[112:115]
	v_mfma_f32_16x16x32_bf16 v[108:111], v[152:155], v[198:201], v[108:111]
	v_mfma_f32_16x16x32_bf16 v[96:99], v[144:147], v[206:209], v[96:99]
	v_mfma_f32_16x16x32_bf16 v[92:95], v[152:155], v[206:209], v[92:95]
	v_mfma_f32_16x16x32_bf16 v[80:83], v[144:147], v[214:217], v[80:83]
	v_mfma_f32_16x16x32_bf16 v[76:79], v[152:155], v[214:217], v[76:79]
	v_mfma_f32_16x16x32_bf16 v[68:71], v[144:147], v[228:231], v[68:71]
	v_mfma_f32_16x16x32_bf16 v[64:67], v[152:155], v[228:231], v[64:67]
	v_mfma_f32_16x16x32_bf16 v[112:115], v[148:151], v[202:205], v[112:115]
	v_mfma_f32_16x16x32_bf16 v[108:111], v[168:171], v[202:205], v[108:111]
	v_mfma_f32_16x16x32_bf16 v[96:99], v[148:151], v[210:213], v[96:99]
	v_mfma_f32_16x16x32_bf16 v[92:95], v[168:171], v[210:213], v[92:95]
	v_mfma_f32_16x16x32_bf16 v[80:83], v[148:151], v[218:221], v[80:83]
	v_mfma_f32_16x16x32_bf16 v[76:79], v[168:171], v[218:221], v[76:79]
	v_mfma_f32_16x16x32_bf16 v[68:71], v[148:151], v[232:235], v[68:71]
	v_mfma_f32_16x16x32_bf16 v[64:67], v[168:171], v[232:235], v[64:67]
	s_setprio 0
	s_barrier
	s_add_i32 s76, s76, s59
	v_lshl_add_u64 v[162:163], s[52:53], 0, v[172:173]
	s_mov_b32 m0, s76
	ds_read_b128 v[198:201], v167 offset:16384
	ds_read_b128 v[202:205], v167 offset:17408
	ds_read_b128 v[206:209], v167 offset:18432
	ds_read_b128 v[210:213], v167 offset:19456
	ds_read_b128 v[214:217], v167 offset:20480
	ds_read_b128 v[218:221], v167 offset:21504
	ds_read_b128 v[228:231], v167 offset:22528
	ds_read_b128 v[232:235], v167 offset:23552
	global_load_lds_dwordx4 v[162:163], off
	s_add_i32 m0, s76, 0x2000
	s_add_u32 s76, s52, 0x80000
	v_lshl_add_u64 v[194:195], s[52:53], 0, v[156:157]
	s_addc_u32 s77, s53, 0
	s_add_i32 s78, s78, s59
	global_load_lds_dwordx4 v[194:195], off
	v_lshl_add_u64 v[224:225], s[76:77], 0, v[172:173]
	s_mov_b32 m0, s78
	v_lshl_add_u64 v[236:237], s[54:55], 0, v[156:157]
	global_load_lds_dwordx4 v[224:225], off
	v_lshl_add_u64 v[224:225], s[76:77], 0, v[156:157]
	s_add_i32 m0, s78, 0x2000
	s_nop 0
	global_load_lds_dwordx4 v[224:225], off
	v_lshl_add_u64 v[224:225], s[54:55], 0, v[172:173]
	s_mov_b32 m0, s60
	s_nop 0
	global_load_lds_dwordx4 v[224:225], off
	s_mov_b32 m0, s63
	s_nop 0
	global_load_lds_dwordx4 v[236:237], off
	s_waitcnt vmcnt(8)
	s_waitcnt lgkmcnt(0)
	s_barrier
; #define PG8_STAGE(bufoff, gbase, voff) do { _Pragma("unroll") for (int _i = 0; _i < 2; ++_i) \
;         __builtin_amdgcn_global_load_lds((const unsigned*)((const char*)(gbase) + (voff)[_i]), (LAS unsigned*)(lds + (bufoff) + ldsw + _i * 8192), 16, 0, 0); } while (0)
; #define PG8_LDA(dst, b, h) do { _Pragma("unroll") for (int m = 0; m < 4; ++m) _Pragma("unroll") for (int k = 0; k < 2; ++k) dst[m][k] = *(const LAS bf16x8*)(lds + PG8_SA(b, h) + aoff + m * 2048 + k * 1024); } while (0)
; #define PG8_LDB(dst, b, h) do { _Pragma("unroll") for (int n = 0; n < 2; ++n) _Pragma("unroll") for (int k = 0; k < 2; ++k) dst[n][k] = *(const LAS bf16x8*)(lds + PG8_SB(b, h) + boff + n * 2048 + k * 1024); } while (0)
; #define PG8_MMA(ai, bj, At, Bt) do { __builtin_amdgcn_s_setprio(1); _Pragma("unroll") for (int m = 0; m < 4; ++m) _Pragma("unroll") for (int n = 0; n < 2; ++n) _Pragma("unroll") for (int k = 0; k < 2; ++k) \
;         acc[ai][bj][m][n] = __builtin_amdgcn_mfma_f32_16x16x32_bf16(Bt[n][k], At[m][k], acc[ai][bj][m][n], 0, 0, 0); __builtin_amdgcn_s_setprio(0); } while (0)
; #define PG8_WAIT_V(n) asm volatile("s_waitcnt vmcnt(" #n ")" ::: "memory")
; #define PG8_WAIT_L(n) asm volatile("s_waitcnt lgkmcnt(" #n ")" ::: "memory")
; #define PG8_BAR __builtin_amdgcn_s_barrier()
; #define PG8_SCHED __builtin_amdgcn_sched_barrier(0)
; template <class Epi>
; __device__ __forceinline__ void gemm_phase(LAS unsigned char* lds, const Sched& S, const int K, const Epi& E) {
;     ...
;             PG8_WAIT_V(8); PG8_WAIT_L(0); PG8_BAR; PG8_MMA(1, 0, At, B0); PG8_MMA(1, 1, At, B1); PG8_BAR; PG8_SCHED;
;             PG8_LDB(B0, 1, 0); PG8_LDB(B1, 1, 1); PG8_SCHED; PG8_LDA(At, 1, 0); PG8_STAGE(PG8_SA(0, 1), a2 + hstepA, voffA);
;             PG8_WAIT_V(8); PG8_WAIT_L(0); PG8_BAR; PG8_MMA(0, 0, At, B0); PG8_MMA(0, 1, At, B1); PG8_BAR; PG8_SCHED;
	s_setprio 1
	s_waitcnt lgkmcnt(0)
	v_mfma_f32_16x16x32_bf16 v[60:63], v[128:131], v[198:201], v[60:63]
	v_mfma_f32_16x16x32_bf16 v[56:59], v[136:139], v[198:201], v[56:59]
	v_mfma_f32_16x16x32_bf16 v[52:55], v[128:131], v[206:209], v[52:55]
	v_mfma_f32_16x16x32_bf16 v[40:43], v[136:139], v[206:209], v[40:43]
	v_mfma_f32_16x16x32_bf16 v[36:39], v[128:131], v[214:217], v[36:39]
	v_mfma_f32_16x16x32_bf16 v[24:27], v[136:139], v[214:217], v[24:27]
	v_mfma_f32_16x16x32_bf16 v[16:19], v[128:131], v[228:231], v[16:19]
	v_mfma_f32_16x16x32_bf16 v[8:11], v[136:139], v[228:231], v[8:11]
	v_mfma_f32_16x16x32_bf16 v[60:63], v[132:135], v[202:205], v[60:63]
	v_mfma_f32_16x16x32_bf16 v[56:59], v[140:143], v[202:205], v[56:59]
	v_mfma_f32_16x16x32_bf16 v[52:55], v[132:135], v[210:213], v[52:55]
	v_mfma_f32_16x16x32_bf16 v[40:43], v[140:143], v[210:213], v[40:43]
	v_mfma_f32_16x16x32_bf16 v[36:39], v[132:135], v[218:221], v[36:39]
	v_mfma_f32_16x16x32_bf16 v[24:27], v[140:143], v[218:221], v[24:27]
	v_mfma_f32_16x16x32_bf16 v[16:19], v[132:135], v[232:235], v[16:19]
	v_mfma_f32_16x16x32_bf16 v[8:11], v[140:143], v[232:235], v[8:11]
	v_mfma_f32_16x16x32_bf16 v[48:51], v[144:147], v[198:201], v[48:51]
	v_mfma_f32_16x16x32_bf16 v[44:47], v[152:155], v[198:201], v[44:47]
	v_mfma_f32_16x16x32_bf16 v[32:35], v[144:147], v[206:209], v[32:35]
	v_mfma_f32_16x16x32_bf16 v[28:31], v[152:155], v[206:209], v[28:31]
	v_mfma_f32_16x16x32_bf16 v[20:23], v[144:147], v[214:217], v[20:23]
	v_mfma_f32_16x16x32_bf16 v[12:15], v[152:155], v[214:217], v[12:15]
	v_mfma_f32_16x16x32_bf16 v[4:7], v[144:147], v[228:231], v[4:7]
	v_mfma_f32_16x16x32_bf16 v[0:3], v[152:155], v[228:231], v[0:3]
	v_mfma_f32_16x16x32_bf16 v[48:51], v[148:151], v[202:205], v[48:51]
	v_mfma_f32_16x16x32_bf16 v[44:47], v[168:171], v[202:205], v[44:47]
	v_mfma_f32_16x16x32_bf16 v[32:35], v[148:151], v[210:213], v[32:35]
	v_mfma_f32_16x16x32_bf16 v[28:31], v[168:171], v[210:213], v[28:31]
	v_mfma_f32_16x16x32_bf16 v[20:23], v[148:151], v[218:221], v[20:23]
	v_mfma_f32_16x16x32_bf16 v[12:15], v[168:171], v[218:221], v[12:15]
	v_mfma_f32_16x16x32_bf16 v[4:7], v[148:151], v[232:235], v[4:7]
	v_mfma_f32_16x16x32_bf16 v[0:3], v[168:171], v[232:235], v[0:3]
	s_setprio 0
	s_barrier
	s_add_i32 s76, 0, 0x18000
	s_add_i32 s77, 0, 0x1c000
	v_add_u32_e32 v140, s76, v165
	v_add_u32_e32 v168, s77, v165
	ds_read_b128 v[128:131], v140
	ds_read_b128 v[132:135], v140 offset:1024
	ds_read_b128 v[136:139], v140 offset:2048
	ds_read_b128 v[140:143], v140 offset:3072
	ds_read_b128 v[144:147], v168
	ds_read_b128 v[148:151], v168 offset:1024
	ds_read_b128 v[152:155], v168 offset:2048
	ds_read_b128 v[168:171], v168 offset:3072
	s_add_u32 s54, s54, 0x80000
	s_addc_u32 s55, s55, 0
	s_mov_b32 m0, s65
	v_lshl_add_u64 v[238:239], s[54:55], 0, v[172:173]
	ds_read_b128 v[198:201], v167 offset:32768
	ds_read_b128 v[202:205], v167 offset:33792
	ds_read_b128 v[206:209], v167 offset:34816
	ds_read_b128 v[210:213], v167 offset:35840
	ds_read_b128 v[214:217], v167 offset:36864
	ds_read_b128 v[218:221], v167 offset:37888
	ds_read_b128 v[228:231], v167 offset:38912
	ds_read_b128 v[232:235], v167 offset:39936
	global_load_lds_dwordx4 v[238:239], off
	v_lshl_add_u64 v[238:239], s[54:55], 0, v[156:157]
	s_mov_b32 m0, s66
	s_nop 0
	global_load_lds_dwordx4 v[238:239], off
	s_waitcnt vmcnt(8)
	s_waitcnt lgkmcnt(0)
	s_barrier
	s_setprio 1
	s_waitcnt lgkmcnt(0)
	v_mfma_f32_16x16x32_bf16 v[124:127], v[128:131], v[198:201], v[124:127]
	v_mfma_f32_16x16x32_bf16 v[120:123], v[136:139], v[198:201], v[120:123]
	v_mfma_f32_16x16x32_bf16 v[116:119], v[128:131], v[206:209], v[116:119]
	v_mfma_f32_16x16x32_bf16 v[104:107], v[136:139], v[206:209], v[104:107]
	v_mfma_f32_16x16x32_bf16 v[100:103], v[128:131], v[214:217], v[100:103]
	v_mfma_f32_16x16x32_bf16 v[88:91], v[136:139], v[214:217], v[88:91]
	v_mfma_f32_16x16x32_bf16 v[84:87], v[128:131], v[228:231], v[84:87]
	v_mfma_f32_16x16x32_bf16 v[72:75], v[136:139], v[228:231], v[72:75]
	v_mfma_f32_16x16x32_bf16 v[124:127], v[132:135], v[202:205], v[124:127]
	v_mfma_f32_16x16x32_bf16 v[120:123], v[140:143], v[202:205], v[120:123]
	v_mfma_f32_16x16x32_bf16 v[116:119], v[132:135], v[210:213], v[116:119]
	v_mfma_f32_16x16x32_bf16 v[104:107], v[140:143], v[210:213], v[104:107]
	v_mfma_f32_16x16x32_bf16 v[100:103], v[132:135], v[218:221], v[100:103]
	v_mfma_f32_16x16x32_bf16 v[88:91], v[140:143], v[218:221], v[88:91]
	v_mfma_f32_16x16x32_bf16 v[84:87], v[132:135], v[232:235], v[84:87]
	v_mfma_f32_16x16x32_bf16 v[72:75], v[140:143], v[232:235], v[72:75]
	v_mfma_f32_16x16x32_bf16 v[112:115], v[144:147], v[198:201], v[112:115]
	v_mfma_f32_16x16x32_bf16 v[108:111], v[152:155], v[198:201], v[108:111]
	v_mfma_f32_16x16x32_bf16 v[96:99], v[144:147], v[206:209], v[96:99]
	v_mfma_f32_16x16x32_bf16 v[92:95], v[152:155], v[206:209], v[92:95]
	v_mfma_f32_16x16x32_bf16 v[80:83], v[144:147], v[214:217], v[80:83]
	v_mfma_f32_16x16x32_bf16 v[76:79], v[152:155], v[214:217], v[76:79]
	v_mfma_f32_16x16x32_bf16 v[68:71], v[144:147], v[228:231], v[68:71]
	v_mfma_f32_16x16x32_bf16 v[64:67], v[152:155], v[228:231], v[64:67]
	v_mfma_f32_16x16x32_bf16 v[112:115], v[148:151], v[202:205], v[112:115]
	v_mfma_f32_16x16x32_bf16 v[108:111], v[168:171], v[202:205], v[108:111]
	v_mfma_f32_16x16x32_bf16 v[96:99], v[148:151], v[210:213], v[96:99]
	v_mfma_f32_16x16x32_bf16 v[92:95], v[168:171], v[210:213], v[92:95]
	v_mfma_f32_16x16x32_bf16 v[80:83], v[148:151], v[218:221], v[80:83]
	v_mfma_f32_16x16x32_bf16 v[76:79], v[168:171], v[218:221], v[76:79]
	v_mfma_f32_16x16x32_bf16 v[68:71], v[148:151], v[232:235], v[68:71]
	v_mfma_f32_16x16x32_bf16 v[64:67], v[168:171], v[232:235], v[64:67]
	s_setprio 0
	s_barrier
; #define PG8_STAGE(bufoff, gbase, voff) do { _Pragma("unroll") for (int _i = 0; _i < 2; ++_i) \
;         __builtin_amdgcn_global_load_lds((const unsigned*)((const char*)(gbase) + (voff)[_i]), (LAS unsigned*)(lds + (bufoff) + ldsw + _i * 8192), 16, 0, 0); } while (0)
; #define PG8_LDA(dst, b, h) do { _Pragma("unroll") for (int m = 0; m < 4; ++m) _Pragma("unroll") for (int k = 0; k < 2; ++k) dst[m][k] = *(const LAS bf16x8*)(lds + PG8_SA(b, h) + aoff + m * 2048 + k * 1024); } while (0)
; #define PG8_MMA(ai, bj, At, Bt) do { __builtin_amdgcn_s_setprio(1); _Pragma("unroll") for (int m = 0; m < 4; ++m) _Pragma("unroll") for (int n = 0; n < 2; ++n) _Pragma("unroll") for (int k = 0; k < 2; ++k) \
;         acc[ai][bj][m][n] = __builtin_amdgcn_mfma_f32_16x16x32_bf16(Bt[n][k], At[m][k], acc[ai][bj][m][n], 0, 0, 0); __builtin_amdgcn_s_setprio(0); } while (0)
; #define PG8_WAIT_V(n) asm volatile("s_waitcnt vmcnt(" #n ")" ::: "memory")
; #define PG8_WAIT_L(n) asm volatile("s_waitcnt lgkmcnt(" #n ")" ::: "memory")
; #define PG8_BAR __builtin_amdgcn_s_barrier()
; #define PG8_SCHED __builtin_amdgcn_sched_barrier(0)
; template <class Epi>
; __device__ __forceinline__ void gemm_phase(LAS unsigned char* lds, const Sched& S, const int K, const Epi& E) {
;     ...
;             PG8_LDA(At, 1, 1); PG8_STAGE(PG8_SB(1, 0), b3, voffB); PG8_STAGE(PG8_SB(1, 1), b3 + hstepB, voffB); PG8_STAGE(PG8_SA(1, 0), a3, voffA);
;             PG8_WAIT_V(8); PG8_WAIT_L(0); PG8_BAR; PG8_MMA(1, 0, At, B0); PG8_MMA(1, 1, At, B1); PG8_BAR; PG8_SCHED;
;         }
;         if (wr == 0) PG8_BAR;
	s_add_i32 s54, s76, s59
	v_lshl_add_u64 v[162:163], v[162:163], 0, s[74:75]
	s_mov_b32 m0, s54
	ds_read_b128 v[198:201], v167 offset:49152
	ds_read_b128 v[202:205], v167 offset:50176
	ds_read_b128 v[206:209], v167 offset:51200
	ds_read_b128 v[210:213], v167 offset:52224
	ds_read_b128 v[214:217], v167 offset:53248
	ds_read_b128 v[218:221], v167 offset:54272
	ds_read_b128 v[228:231], v167 offset:55296
	ds_read_b128 v[232:235], v167 offset:56320
	global_load_lds_dwordx4 v[162:163], off
	s_add_i32 m0, s54, 0x2000
	s_add_u32 s52, s52, 0x80080
	v_lshl_add_u64 v[162:163], v[194:195], 0, s[74:75]
	s_addc_u32 s53, s53, 0
	s_add_i32 s54, s77, s59
	global_load_lds_dwordx4 v[162:163], off
	v_lshl_add_u64 v[162:163], s[52:53], 0, v[172:173]
	s_mov_b32 m0, s54
	s_nop 0
	global_load_lds_dwordx4 v[162:163], off
	v_lshl_add_u64 v[162:163], s[52:53], 0, v[156:157]
	s_add_i32 m0, s54, 0x2000
	s_nop 0
	global_load_lds_dwordx4 v[162:163], off
	v_lshl_add_u64 v[162:163], v[224:225], 0, s[74:75]
	s_mov_b32 m0, s71
	s_nop 0
	global_load_lds_dwordx4 v[162:163], off
	v_lshl_add_u64 v[162:163], v[236:237], 0, s[74:75]
	s_mov_b32 m0, s72
	s_nop 0
	global_load_lds_dwordx4 v[162:163], off
	s_waitcnt vmcnt(8)
	s_waitcnt lgkmcnt(0)
	s_barrier
	s_setprio 1
	s_waitcnt lgkmcnt(0)
	v_mfma_f32_16x16x32_bf16 v[60:63], v[128:131], v[198:201], v[60:63]
	v_mfma_f32_16x16x32_bf16 v[56:59], v[136:139], v[198:201], v[56:59]
	v_mfma_f32_16x16x32_bf16 v[52:55], v[128:131], v[206:209], v[52:55]
	v_mfma_f32_16x16x32_bf16 v[40:43], v[136:139], v[206:209], v[40:43]
	v_mfma_f32_16x16x32_bf16 v[36:39], v[128:131], v[214:217], v[36:39]
	v_mfma_f32_16x16x32_bf16 v[24:27], v[136:139], v[214:217], v[24:27]
	v_mfma_f32_16x16x32_bf16 v[16:19], v[128:131], v[228:231], v[16:19]
	v_mfma_f32_16x16x32_bf16 v[8:11], v[136:139], v[228:231], v[8:11]
	v_mfma_f32_16x16x32_bf16 v[60:63], v[132:135], v[202:205], v[60:63]
	v_mfma_f32_16x16x32_bf16 v[56:59], v[140:143], v[202:205], v[56:59]
	v_mfma_f32_16x16x32_bf16 v[52:55], v[132:135], v[210:213], v[52:55]
	v_mfma_f32_16x16x32_bf16 v[40:43], v[140:143], v[210:213], v[40:43]
	v_mfma_f32_16x16x32_bf16 v[36:39], v[132:135], v[218:221], v[36:39]
	v_mfma_f32_16x16x32_bf16 v[24:27], v[140:143], v[218:221], v[24:27]
	v_mfma_f32_16x16x32_bf16 v[16:19], v[132:135], v[232:235], v[16:19]
	v_mfma_f32_16x16x32_bf16 v[8:11], v[140:143], v[232:235], v[8:11]
	v_mfma_f32_16x16x32_bf16 v[48:51], v[144:147], v[198:201], v[48:51]
	v_mfma_f32_16x16x32_bf16 v[44:47], v[152:155], v[198:201], v[44:47]
	v_mfma_f32_16x16x32_bf16 v[32:35], v[144:147], v[206:209], v[32:35]
	v_mfma_f32_16x16x32_bf16 v[28:31], v[152:155], v[206:209], v[28:31]
	v_mfma_f32_16x16x32_bf16 v[20:23], v[144:147], v[214:217], v[20:23]
	v_mfma_f32_16x16x32_bf16 v[12:15], v[152:155], v[214:217], v[12:15]
	v_mfma_f32_16x16x32_bf16 v[4:7], v[144:147], v[228:231], v[4:7]
	v_mfma_f32_16x16x32_bf16 v[0:3], v[152:155], v[228:231], v[0:3]
	v_mfma_f32_16x16x32_bf16 v[48:51], v[148:151], v[202:205], v[48:51]
	v_mfma_f32_16x16x32_bf16 v[44:47], v[168:171], v[202:205], v[44:47]
	v_mfma_f32_16x16x32_bf16 v[32:35], v[148:151], v[210:213], v[32:35]
	v_mfma_f32_16x16x32_bf16 v[28:31], v[168:171], v[210:213], v[28:31]
	v_mfma_f32_16x16x32_bf16 v[20:23], v[148:151], v[218:221], v[20:23]
	v_mfma_f32_16x16x32_bf16 v[12:15], v[168:171], v[218:221], v[12:15]
	v_mfma_f32_16x16x32_bf16 v[4:7], v[148:151], v[232:235], v[4:7]
	v_mfma_f32_16x16x32_bf16 v[0:3], v[168:171], v[232:235], v[0:3]
	s_setprio 0
	s_barrier
	s_add_i32 vcc_lo, vcc_lo, 2
	s_add_u32 s47, s47, 0x100
	s_addc_u32 s97, s97, 0
	s_add_u32 s36, s36, 0x100
	s_addc_u32 s37, s37, 0
	s_cmp_gt_u32 vcc_lo, 29
	s_cbranch_scc0 .LBB0_1239
	s_and_b64 vcc, exec, s[44:45]
	s_cbranch_vccz .LBB0_1242
	s_barrier

; #define PG8_STAGE(bufoff, gbase, voff) do { _Pragma("unroll") for (int _i = 0; _i < 2; ++_i) \
;         __builtin_amdgcn_global_load_lds((const unsigned*)((const char*)(gbase) + (voff)[_i]), (LAS unsigned*)(lds + (bufoff) + ldsw + _i * 8192), 16, 0, 0); } while (0)
; #define PG8_LDA(dst, b, h) do { _Pragma("unroll") for (int m = 0; m < 4; ++m) _Pragma("unroll") for (int k = 0; k < 2; ++k) dst[m][k] = *(const LAS bf16x8*)(lds + PG8_SA(b, h) + aoff + m * 2048 + k * 1024); } while (0)
; #define PG8_LDB(dst, b, h) do { _Pragma("unroll") for (int n = 0; n < 2; ++n) _Pragma("unroll") for (int k = 0; k < 2; ++k) dst[n][k] = *(const LAS bf16x8*)(lds + PG8_SB(b, h) + boff + n * 2048 + k * 1024); } while (0)
; #define PG8_MMA(ai, bj, At, Bt) do { __builtin_amdgcn_s_setprio(1); _Pragma("unroll") for (int m = 0; m < 4; ++m) _Pragma("unroll") for (int n = 0; n < 2; ++n) _Pragma("unroll") for (int k = 0; k < 2; ++k) \
;         acc[ai][bj][m][n] = __builtin_amdgcn_mfma_f32_16x16x32_bf16(Bt[n][k], At[m][k], acc[ai][bj][m][n], 0, 0, 0); __builtin_amdgcn_s_setprio(0); } while (0)
; #define PG8_WAIT_V(n) asm volatile("s_waitcnt vmcnt(" #n ")" ::: "memory")
; #define PG8_WAIT_L(n) asm volatile("s_waitcnt lgkmcnt(" #n ")" ::: "memory")
; #define PG8_BAR __builtin_amdgcn_s_barrier()
; #define PG8_SCHED __builtin_amdgcn_sched_barrier(0)
; template <class Epi>
; __device__ __forceinline__ void gemm_phase(LAS unsigned char* lds, const Sched& S, const int K, const Epi& E) {
;     ...
;             const bool last = (t == nt - 2);
;             const char* a1 = cA + (size_t)(t + 1) * kstep;
;             const char* a2 = last ? nA : cA + (size_t)(t + 2) * kstep; const char* b2 = last ? nB : cB + (size_t)(t + 2) * kstep;
;             const char* a3 = a2 + kstep; const char* b3 = b2 + kstep;
;             PG8_LDB(B0, 0, 0); PG8_LDB(B1, 0, 1); PG8_SCHED; PG8_LDA(At, 0, 0); PG8_STAGE(PG8_SA(1, 1), a1 + hstepA, voffA);
;             PG8_WAIT_V(8); PG8_WAIT_L(0); PG8_BAR; PG8_MMA(0, 0, At, B0); PG8_MMA(0, 1, At, B1); PG8_BAR; PG8_SCHED;
;             PG8_LDA(At, 0, 1); PG8_STAGE(PG8_SB(0, 0), b2, voffB); PG8_STAGE(PG8_SB(0, 1), b2 + hstepB, voffB); PG8_STAGE(PG8_SA(0, 0), a2, voffA);
;             PG8_WAIT_V(8); PG8_WAIT_L(0); PG8_BAR; PG8_MMA(1, 0, At, B0); PG8_MMA(1, 1, At, B1); PG8_BAR; PG8_SCHED;
.LBB0_1400:
	s_add_u32 s50, s36, 0xfff80080
	s_addc_u32 s51, s37, -1
	s_add_i32 s73, 0, 0x10000
	s_cmp_eq_u32 s72, 28
	s_cselect_b32 s53, s29, s51
	s_cselect_b32 s52, s28, s50
	s_cselect_b32 s51, s35, s71
	s_cselect_b32 s50, s34, s45
	s_add_i32 s78, 0, 0x14000
	v_add_u32_e32 v154, s73, v139
	v_add_u32_e32 v170, s78, v139
	ds_read_b128 v[142:145], v154
	ds_read_b128 v[146:149], v154 offset:1024
	ds_read_b128 v[150:153], v154 offset:2048
	ds_read_b128 v[154:157], v154 offset:3072
	ds_read_b128 v[158:161], v170
	ds_read_b128 v[162:165], v170 offset:1024
	ds_read_b128 v[166:169], v170 offset:2048
	ds_read_b128 v[198:201], v170 offset:3072
	v_lshl_add_u64 v[170:171], s[36:37], 0, v[134:135]
	s_add_i32 m0, s59, 0xc000
	ds_read_b128 v[202:205], v141
	ds_read_b128 v[206:209], v141 offset:1024
	ds_read_b128 v[210:213], v141 offset:2048
	ds_read_b128 v[214:217], v141 offset:3072
	ds_read_b128 v[218:221], v141 offset:4096
	ds_read_b128 v[228:231], v141 offset:5120
	ds_read_b128 v[232:235], v141 offset:6144
	ds_read_b128 v[236:239], v141 offset:7168
	global_load_lds_dwordx4 v[170:171], off
	v_lshl_add_u64 v[170:171], s[36:37], 0, v[136:137]
	s_add_i32 m0, s59, 0xe000
	s_nop 0
	global_load_lds_dwordx4 v[170:171], off
	s_waitcnt vmcnt(8)
	s_waitcnt lgkmcnt(0)
	s_barrier
	s_setprio 1
	s_waitcnt lgkmcnt(0)
	v_mfma_f32_16x16x32_bf16 v[124:127], v[142:145], v[202:205], v[124:127]
	v_mfma_f32_16x16x32_bf16 v[116:119], v[150:153], v[202:205], v[116:119]
	v_mfma_f32_16x16x32_bf16 v[108:111], v[142:145], v[210:213], v[108:111]
	v_mfma_f32_16x16x32_bf16 v[100:103], v[150:153], v[210:213], v[100:103]
	v_mfma_f32_16x16x32_bf16 v[92:95], v[142:145], v[218:221], v[92:95]
	v_mfma_f32_16x16x32_bf16 v[84:87], v[150:153], v[218:221], v[84:87]
	v_mfma_f32_16x16x32_bf16 v[76:79], v[142:145], v[232:235], v[76:79]
	v_mfma_f32_16x16x32_bf16 v[68:71], v[150:153], v[232:235], v[68:71]
	v_mfma_f32_16x16x32_bf16 v[124:127], v[146:149], v[206:209], v[124:127]
	v_mfma_f32_16x16x32_bf16 v[116:119], v[154:157], v[206:209], v[116:119]
	v_mfma_f32_16x16x32_bf16 v[108:111], v[146:149], v[214:217], v[108:111]
	v_mfma_f32_16x16x32_bf16 v[100:103], v[154:157], v[214:217], v[100:103]
	v_mfma_f32_16x16x32_bf16 v[92:95], v[146:149], v[228:231], v[92:95]
	v_mfma_f32_16x16x32_bf16 v[84:87], v[154:157], v[228:231], v[84:87]
	v_mfma_f32_16x16x32_bf16 v[76:79], v[146:149], v[236:239], v[76:79]
	v_mfma_f32_16x16x32_bf16 v[68:71], v[154:157], v[236:239], v[68:71]
	v_mfma_f32_16x16x32_bf16 v[120:123], v[158:161], v[202:205], v[120:123]
	v_mfma_f32_16x16x32_bf16 v[112:115], v[166:169], v[202:205], v[112:115]
	v_mfma_f32_16x16x32_bf16 v[104:107], v[158:161], v[210:213], v[104:107]
	v_mfma_f32_16x16x32_bf16 v[96:99], v[166:169], v[210:213], v[96:99]
	v_mfma_f32_16x16x32_bf16 v[88:91], v[158:161], v[218:221], v[88:91]
	v_mfma_f32_16x16x32_bf16 v[80:83], v[166:169], v[218:221], v[80:83]
	v_mfma_f32_16x16x32_bf16 v[72:75], v[158:161], v[232:235], v[72:75]
	v_mfma_f32_16x16x32_bf16 v[64:67], v[166:169], v[232:235], v[64:67]
	v_mfma_f32_16x16x32_bf16 v[120:123], v[162:165], v[206:209], v[120:123]
	v_mfma_f32_16x16x32_bf16 v[112:115], v[198:201], v[206:209], v[112:115]
	v_mfma_f32_16x16x32_bf16 v[104:107], v[162:165], v[214:217], v[104:107]
	v_mfma_f32_16x16x32_bf16 v[96:99], v[198:201], v[214:217], v[96:99]
	v_mfma_f32_16x16x32_bf16 v[88:91], v[162:165], v[228:231], v[88:91]
	v_mfma_f32_16x16x32_bf16 v[80:83], v[198:201], v[228:231], v[80:83]
	v_mfma_f32_16x16x32_bf16 v[72:75], v[162:165], v[236:239], v[72:75]
	v_mfma_f32_16x16x32_bf16 v[64:67], v[198:201], v[236:239], v[64:67]
	s_setprio 0
	s_barrier
	s_add_i32 s73, s73, s58
	v_lshl_add_u64 v[170:171], s[50:51], 0, v[172:173]
	s_mov_b32 m0, s73
	ds_read_b128 v[202:205], v141 offset:16384
	ds_read_b128 v[206:209], v141 offset:17408
	ds_read_b128 v[210:213], v141 offset:18432
	ds_read_b128 v[214:217], v141 offset:19456
	ds_read_b128 v[218:221], v141 offset:20480
	ds_read_b128 v[228:231], v141 offset:21504
	ds_read_b128 v[232:235], v141 offset:22528
	ds_read_b128 v[236:239], v141 offset:23552
	global_load_lds_dwordx4 v[170:171], off
	s_add_i32 m0, s73, 0x2000
	s_add_u32 s76, s50, 0x80000
	v_lshl_add_u64 v[194:195], s[50:51], 0, v[128:129]
	s_addc_u32 s77, s51, 0
	s_add_i32 s73, s78, s58
	global_load_lds_dwordx4 v[194:195], off
	v_lshl_add_u64 v[224:225], s[76:77], 0, v[172:173]
	s_mov_b32 m0, s73
	v_lshl_add_u64 v[240:241], s[52:53], 0, v[130:131]
	global_load_lds_dwordx4 v[224:225], off
	v_lshl_add_u64 v[224:225], s[76:77], 0, v[128:129]
	s_add_i32 m0, s73, 0x2000
	s_nop 0
	global_load_lds_dwordx4 v[224:225], off
	v_lshl_add_u64 v[224:225], s[52:53], 0, v[132:133]
	s_mov_b32 m0, s59
	s_nop 0
	global_load_lds_dwordx4 v[224:225], off
	s_mov_b32 m0, s60
	s_nop 0
	global_load_lds_dwordx4 v[240:241], off
	s_waitcnt vmcnt(8)
	s_waitcnt lgkmcnt(0)
	s_barrier
; #define PG8_STAGE(bufoff, gbase, voff) do { _Pragma("unroll") for (int _i = 0; _i < 2; ++_i) \
;         __builtin_amdgcn_global_load_lds((const unsigned*)((const char*)(gbase) + (voff)[_i]), (LAS unsigned*)(lds + (bufoff) + ldsw + _i * 8192), 16, 0, 0); } while (0)
; #define PG8_LDA(dst, b, h) do { _Pragma("unroll") for (int m = 0; m < 4; ++m) _Pragma("unroll") for (int k = 0; k < 2; ++k) dst[m][k] = *(const LAS bf16x8*)(lds + PG8_SA(b, h) + aoff + m * 2048 + k * 1024); } while (0)
; #define PG8_LDB(dst, b, h) do { _Pragma("unroll") for (int n = 0; n < 2; ++n) _Pragma("unroll") for (int k = 0; k < 2; ++k) dst[n][k] = *(const LAS bf16x8*)(lds + PG8_SB(b, h) + boff + n * 2048 + k * 1024); } while (0)
; #define PG8_MMA(ai, bj, At, Bt) do { __builtin_amdgcn_s_setprio(1); _Pragma("unroll") for (int m = 0; m < 4; ++m) _Pragma("unroll") for (int n = 0; n < 2; ++n) _Pragma("unroll") for (int k = 0; k < 2; ++k) \
;         acc[ai][bj][m][n] = __builtin_amdgcn_mfma_f32_16x16x32_bf16(Bt[n][k], At[m][k], acc[ai][bj][m][n], 0, 0, 0); __builtin_amdgcn_s_setprio(0); } while (0)
; #define PG8_WAIT_V(n) asm volatile("s_waitcnt vmcnt(" #n ")" ::: "memory")
; #define PG8_WAIT_L(n) asm volatile("s_waitcnt lgkmcnt(" #n ")" ::: "memory")
; #define PG8_BAR __builtin_amdgcn_s_barrier()
; #define PG8_SCHED __builtin_amdgcn_sched_barrier(0)
; template <class Epi>
; __device__ __forceinline__ void gemm_phase(LAS unsigned char* lds, const Sched& S, const int K, const Epi& E) {
;     ...
;             PG8_WAIT_V(8); PG8_WAIT_L(0); PG8_BAR; PG8_MMA(1, 0, At, B0); PG8_MMA(1, 1, At, B1); PG8_BAR; PG8_SCHED;
;             PG8_LDB(B0, 1, 0); PG8_LDB(B1, 1, 1); PG8_SCHED; PG8_LDA(At, 1, 0); PG8_STAGE(PG8_SA(0, 1), a2 + hstepA, voffA);
;             PG8_WAIT_V(8); PG8_WAIT_L(0); PG8_BAR; PG8_MMA(0, 0, At, B0); PG8_MMA(0, 1, At, B1); PG8_BAR; PG8_SCHED;
	s_setprio 1
	s_waitcnt lgkmcnt(0)
	v_mfma_f32_16x16x32_bf16 v[60:63], v[142:145], v[202:205], v[60:63]
	v_mfma_f32_16x16x32_bf16 v[52:55], v[150:153], v[202:205], v[52:55]
	v_mfma_f32_16x16x32_bf16 v[44:47], v[142:145], v[210:213], v[44:47]
	v_mfma_f32_16x16x32_bf16 v[36:39], v[150:153], v[210:213], v[36:39]
	v_mfma_f32_16x16x32_bf16 v[28:31], v[142:145], v[218:221], v[28:31]
	v_mfma_f32_16x16x32_bf16 v[20:23], v[150:153], v[218:221], v[20:23]
	v_mfma_f32_16x16x32_bf16 v[12:15], v[142:145], v[232:235], v[12:15]
	v_mfma_f32_16x16x32_bf16 v[4:7], v[150:153], v[232:235], v[4:7]
	v_mfma_f32_16x16x32_bf16 v[60:63], v[146:149], v[206:209], v[60:63]
	v_mfma_f32_16x16x32_bf16 v[52:55], v[154:157], v[206:209], v[52:55]
	v_mfma_f32_16x16x32_bf16 v[44:47], v[146:149], v[214:217], v[44:47]
	v_mfma_f32_16x16x32_bf16 v[36:39], v[154:157], v[214:217], v[36:39]
	v_mfma_f32_16x16x32_bf16 v[28:31], v[146:149], v[228:231], v[28:31]
	v_mfma_f32_16x16x32_bf16 v[20:23], v[154:157], v[228:231], v[20:23]
	v_mfma_f32_16x16x32_bf16 v[12:15], v[146:149], v[236:239], v[12:15]
	v_mfma_f32_16x16x32_bf16 v[4:7], v[154:157], v[236:239], v[4:7]
	v_mfma_f32_16x16x32_bf16 v[56:59], v[158:161], v[202:205], v[56:59]
	v_mfma_f32_16x16x32_bf16 v[48:51], v[166:169], v[202:205], v[48:51]
	v_mfma_f32_16x16x32_bf16 v[40:43], v[158:161], v[210:213], v[40:43]
	v_mfma_f32_16x16x32_bf16 v[32:35], v[166:169], v[210:213], v[32:35]
	v_mfma_f32_16x16x32_bf16 v[24:27], v[158:161], v[218:221], v[24:27]
	v_mfma_f32_16x16x32_bf16 v[16:19], v[166:169], v[218:221], v[16:19]
	v_mfma_f32_16x16x32_bf16 v[8:11], v[158:161], v[232:235], v[8:11]
	v_mfma_f32_16x16x32_bf16 v[0:3], v[166:169], v[232:235], v[0:3]
	v_mfma_f32_16x16x32_bf16 v[56:59], v[162:165], v[206:209], v[56:59]
	v_mfma_f32_16x16x32_bf16 v[48:51], v[198:201], v[206:209], v[48:51]
	v_mfma_f32_16x16x32_bf16 v[40:43], v[162:165], v[214:217], v[40:43]
	v_mfma_f32_16x16x32_bf16 v[32:35], v[198:201], v[214:217], v[32:35]
	v_mfma_f32_16x16x32_bf16 v[24:27], v[162:165], v[228:231], v[24:27]
	v_mfma_f32_16x16x32_bf16 v[16:19], v[198:201], v[228:231], v[16:19]
	v_mfma_f32_16x16x32_bf16 v[8:11], v[162:165], v[236:239], v[8:11]
	v_mfma_f32_16x16x32_bf16 v[0:3], v[198:201], v[236:239], v[0:3]
	s_setprio 0
	s_barrier
	s_add_i32 s73, 0, 0x18000
	s_add_i32 s76, 0, 0x1c000
	v_add_u32_e32 v154, s73, v139
	v_add_u32_e32 v198, s76, v139
	ds_read_b128 v[142:145], v154
	ds_read_b128 v[146:149], v154 offset:1024
	ds_read_b128 v[150:153], v154 offset:2048
	ds_read_b128 v[154:157], v154 offset:3072
	ds_read_b128 v[158:161], v198
	ds_read_b128 v[162:165], v198 offset:1024
	ds_read_b128 v[166:169], v198 offset:2048
	ds_read_b128 v[198:201], v198 offset:3072
	s_add_u32 s52, s52, 0x80000
	s_addc_u32 s53, s53, 0
	s_mov_b32 m0, s63
	v_lshl_add_u64 v[242:243], s[52:53], 0, v[132:133]
	ds_read_b128 v[202:205], v141 offset:32768
	ds_read_b128 v[206:209], v141 offset:33792
	ds_read_b128 v[210:213], v141 offset:34816
	ds_read_b128 v[214:217], v141 offset:35840
	ds_read_b128 v[218:221], v141 offset:36864
	ds_read_b128 v[228:231], v141 offset:37888
	ds_read_b128 v[232:235], v141 offset:38912
	ds_read_b128 v[236:239], v141 offset:39936
	global_load_lds_dwordx4 v[242:243], off
	v_lshl_add_u64 v[242:243], s[52:53], 0, v[130:131]
	s_mov_b32 m0, s65
	s_nop 0
	global_load_lds_dwordx4 v[242:243], off
	s_waitcnt vmcnt(8)
	s_waitcnt lgkmcnt(0)
	s_barrier
	s_setprio 1
	s_waitcnt lgkmcnt(0)
	v_mfma_f32_16x16x32_bf16 v[124:127], v[142:145], v[202:205], v[124:127]
	v_mfma_f32_16x16x32_bf16 v[116:119], v[150:153], v[202:205], v[116:119]
	v_mfma_f32_16x16x32_bf16 v[108:111], v[142:145], v[210:213], v[108:111]
	v_mfma_f32_16x16x32_bf16 v[100:103], v[150:153], v[210:213], v[100:103]
	v_mfma_f32_16x16x32_bf16 v[92:95], v[142:145], v[218:221], v[92:95]
	v_mfma_f32_16x16x32_bf16 v[84:87], v[150:153], v[218:221], v[84:87]
	v_mfma_f32_16x16x32_bf16 v[76:79], v[142:145], v[232:235], v[76:79]
	v_mfma_f32_16x16x32_bf16 v[68:71], v[150:153], v[232:235], v[68:71]
	v_mfma_f32_16x16x32_bf16 v[124:127], v[146:149], v[206:209], v[124:127]
	v_mfma_f32_16x16x32_bf16 v[116:119], v[154:157], v[206:209], v[116:119]
	v_mfma_f32_16x16x32_bf16 v[108:111], v[146:149], v[214:217], v[108:111]
	v_mfma_f32_16x16x32_bf16 v[100:103], v[154:157], v[214:217], v[100:103]
	v_mfma_f32_16x16x32_bf16 v[92:95], v[146:149], v[228:231], v[92:95]
	v_mfma_f32_16x16x32_bf16 v[84:87], v[154:157], v[228:231], v[84:87]
	v_mfma_f32_16x16x32_bf16 v[76:79], v[146:149], v[236:239], v[76:79]
	v_mfma_f32_16x16x32_bf16 v[68:71], v[154:157], v[236:239], v[68:71]
	v_mfma_f32_16x16x32_bf16 v[120:123], v[158:161], v[202:205], v[120:123]
	v_mfma_f32_16x16x32_bf16 v[112:115], v[166:169], v[202:205], v[112:115]
	v_mfma_f32_16x16x32_bf16 v[104:107], v[158:161], v[210:213], v[104:107]
	v_mfma_f32_16x16x32_bf16 v[96:99], v[166:169], v[210:213], v[96:99]
	v_mfma_f32_16x16x32_bf16 v[88:91], v[158:161], v[218:221], v[88:91]
	v_mfma_f32_16x16x32_bf16 v[80:83], v[166:169], v[218:221], v[80:83]
	v_mfma_f32_16x16x32_bf16 v[72:75], v[158:161], v[232:235], v[72:75]
	v_mfma_f32_16x16x32_bf16 v[64:67], v[166:169], v[232:235], v[64:67]
	v_mfma_f32_16x16x32_bf16 v[120:123], v[162:165], v[206:209], v[120:123]
	v_mfma_f32_16x16x32_bf16 v[112:115], v[198:201], v[206:209], v[112:115]
	v_mfma_f32_16x16x32_bf16 v[104:107], v[162:165], v[214:217], v[104:107]
	v_mfma_f32_16x16x32_bf16 v[96:99], v[198:201], v[214:217], v[96:99]
	v_mfma_f32_16x16x32_bf16 v[88:91], v[162:165], v[228:231], v[88:91]
	v_mfma_f32_16x16x32_bf16 v[80:83], v[198:201], v[228:231], v[80:83]
	v_mfma_f32_16x16x32_bf16 v[72:75], v[162:165], v[236:239], v[72:75]
	v_mfma_f32_16x16x32_bf16 v[64:67], v[198:201], v[236:239], v[64:67]
	s_setprio 0
	s_barrier
; #define PG8_STAGE(bufoff, gbase, voff) do { _Pragma("unroll") for (int _i = 0; _i < 2; ++_i) \
;         __builtin_amdgcn_global_load_lds((const unsigned*)((const char*)(gbase) + (voff)[_i]), (LAS unsigned*)(lds + (bufoff) + ldsw + _i * 8192), 16, 0, 0); } while (0)
; #define PG8_LDA(dst, b, h) do { _Pragma("unroll") for (int m = 0; m < 4; ++m) _Pragma("unroll") for (int k = 0; k < 2; ++k) dst[m][k] = *(const LAS bf16x8*)(lds + PG8_SA(b, h) + aoff + m * 2048 + k * 1024); } while (0)
; #define PG8_MMA(ai, bj, At, Bt) do { __builtin_amdgcn_s_setprio(1); _Pragma("unroll") for (int m = 0; m < 4; ++m) _Pragma("unroll") for (int n = 0; n < 2; ++n) _Pragma("unroll") for (int k = 0; k < 2; ++k) \
;         acc[ai][bj][m][n] = __builtin_amdgcn_mfma_f32_16x16x32_bf16(Bt[n][k], At[m][k], acc[ai][bj][m][n], 0, 0, 0); __builtin_amdgcn_s_setprio(0); } while (0)
; #define PG8_WAIT_V(n) asm volatile("s_waitcnt vmcnt(" #n ")" ::: "memory")
; #define PG8_WAIT_L(n) asm volatile("s_waitcnt lgkmcnt(" #n ")" ::: "memory")
; #define PG8_BAR __builtin_amdgcn_s_barrier()
; #define PG8_SCHED __builtin_amdgcn_sched_barrier(0)
; template <class Epi>
; __device__ __forceinline__ void gemm_phase(LAS unsigned char* lds, const Sched& S, const int K, const Epi& E) {
;     ...
;             PG8_LDA(At, 1, 1); PG8_STAGE(PG8_SB(1, 0), b3, voffB); PG8_STAGE(PG8_SB(1, 1), b3 + hstepB, voffB); PG8_STAGE(PG8_SA(1, 0), a3, voffA);
;             PG8_WAIT_V(8); PG8_WAIT_L(0); PG8_BAR; PG8_MMA(1, 0, At, B0); PG8_MMA(1, 1, At, B1); PG8_BAR; PG8_SCHED;
;         }
;         if (wr == 0) PG8_BAR;
	s_add_i32 s52, s73, s58
	v_lshl_add_u64 v[170:171], v[170:171], 0, s[74:75]
	s_mov_b32 m0, s52
	ds_read_b128 v[202:205], v141 offset:49152
	ds_read_b128 v[206:209], v141 offset:50176
	ds_read_b128 v[210:213], v141 offset:51200
	ds_read_b128 v[214:217], v141 offset:52224
	ds_read_b128 v[218:221], v141 offset:53248
	ds_read_b128 v[228:231], v141 offset:54272
	ds_read_b128 v[232:235], v141 offset:55296
	ds_read_b128 v[236:239], v141 offset:56320
	global_load_lds_dwordx4 v[170:171], off
	s_add_i32 m0, s52, 0x2000
	s_add_u32 s50, s50, 0x80080
	v_lshl_add_u64 v[170:171], v[194:195], 0, s[74:75]
	s_addc_u32 s51, s51, 0
	s_add_i32 s52, s76, s58
	global_load_lds_dwordx4 v[170:171], off
	v_lshl_add_u64 v[170:171], s[50:51], 0, v[172:173]
	s_mov_b32 m0, s52
	s_nop 0
	global_load_lds_dwordx4 v[170:171], off
	v_lshl_add_u64 v[170:171], s[50:51], 0, v[128:129]
	s_add_i32 m0, s52, 0x2000
	s_nop 0
	global_load_lds_dwordx4 v[170:171], off
	v_lshl_add_u64 v[170:171], v[224:225], 0, s[74:75]
	s_mov_b32 m0, s66
	s_nop 0
	global_load_lds_dwordx4 v[170:171], off
	v_lshl_add_u64 v[170:171], v[240:241], 0, s[74:75]
	s_mov_b32 m0, s67
	s_nop 0
	global_load_lds_dwordx4 v[170:171], off
	s_waitcnt vmcnt(8)
	s_waitcnt lgkmcnt(0)
	s_barrier
	s_setprio 1
	s_waitcnt lgkmcnt(0)
	v_mfma_f32_16x16x32_bf16 v[60:63], v[142:145], v[202:205], v[60:63]
	v_mfma_f32_16x16x32_bf16 v[52:55], v[150:153], v[202:205], v[52:55]
	v_mfma_f32_16x16x32_bf16 v[44:47], v[142:145], v[210:213], v[44:47]
	v_mfma_f32_16x16x32_bf16 v[36:39], v[150:153], v[210:213], v[36:39]
	v_mfma_f32_16x16x32_bf16 v[28:31], v[142:145], v[218:221], v[28:31]
	v_mfma_f32_16x16x32_bf16 v[20:23], v[150:153], v[218:221], v[20:23]
	v_mfma_f32_16x16x32_bf16 v[12:15], v[142:145], v[232:235], v[12:15]
	v_mfma_f32_16x16x32_bf16 v[4:7], v[150:153], v[232:235], v[4:7]
	v_mfma_f32_16x16x32_bf16 v[60:63], v[146:149], v[206:209], v[60:63]
	v_mfma_f32_16x16x32_bf16 v[52:55], v[154:157], v[206:209], v[52:55]
	v_mfma_f32_16x16x32_bf16 v[44:47], v[146:149], v[214:217], v[44:47]
	v_mfma_f32_16x16x32_bf16 v[36:39], v[154:157], v[214:217], v[36:39]
	v_mfma_f32_16x16x32_bf16 v[28:31], v[146:149], v[228:231], v[28:31]
	v_mfma_f32_16x16x32_bf16 v[20:23], v[154:157], v[228:231], v[20:23]
	v_mfma_f32_16x16x32_bf16 v[12:15], v[146:149], v[236:239], v[12:15]
	v_mfma_f32_16x16x32_bf16 v[4:7], v[154:157], v[236:239], v[4:7]
	v_mfma_f32_16x16x32_bf16 v[56:59], v[158:161], v[202:205], v[56:59]
	v_mfma_f32_16x16x32_bf16 v[48:51], v[166:169], v[202:205], v[48:51]
	v_mfma_f32_16x16x32_bf16 v[40:43], v[158:161], v[210:213], v[40:43]
	v_mfma_f32_16x16x32_bf16 v[32:35], v[166:169], v[210:213], v[32:35]
	v_mfma_f32_16x16x32_bf16 v[24:27], v[158:161], v[218:221], v[24:27]
	v_mfma_f32_16x16x32_bf16 v[16:19], v[166:169], v[218:221], v[16:19]
	v_mfma_f32_16x16x32_bf16 v[8:11], v[158:161], v[232:235], v[8:11]
	v_mfma_f32_16x16x32_bf16 v[0:3], v[166:169], v[232:235], v[0:3]
	v_mfma_f32_16x16x32_bf16 v[56:59], v[162:165], v[206:209], v[56:59]
	v_mfma_f32_16x16x32_bf16 v[48:51], v[198:201], v[206:209], v[48:51]
	v_mfma_f32_16x16x32_bf16 v[40:43], v[162:165], v[214:217], v[40:43]
	v_mfma_f32_16x16x32_bf16 v[32:35], v[198:201], v[214:217], v[32:35]
	v_mfma_f32_16x16x32_bf16 v[24:27], v[162:165], v[228:231], v[24:27]
	v_mfma_f32_16x16x32_bf16 v[16:19], v[198:201], v[228:231], v[16:19]
	v_mfma_f32_16x16x32_bf16 v[8:11], v[162:165], v[236:239], v[8:11]
	v_mfma_f32_16x16x32_bf16 v[0:3], v[198:201], v[236:239], v[0:3]
	s_setprio 0
	s_barrier
	s_add_i32 s72, s72, 2
	s_add_u32 s45, s45, 0x100
	s_addc_u32 s71, s71, 0
	s_add_u32 s36, s36, 0x100
	s_addc_u32 s37, s37, 0
	s_cmp_gt_u32 s72, 29
	s_cbranch_scc0 .LBB0_1400
	s_and_b64 vcc, exec, s[42:43]
	s_cbranch_vccz .LBB0_1403
	s_barrier

; #define PG8_STAGE(bufoff, gbase, voff) do { _Pragma("unroll") for (int _i = 0; _i < 2; ++_i) \
;         __builtin_amdgcn_global_load_lds((const unsigned*)((const char*)(gbase) + (voff)[_i]), (LAS unsigned*)(lds + (bufoff) + ldsw + _i * 8192), 16, 0, 0); } while (0)
; #define PG8_LDA(dst, b, h) do { _Pragma("unroll") for (int m = 0; m < 4; ++m) _Pragma("unroll") for (int k = 0; k < 2; ++k) dst[m][k] = *(const LAS bf16x8*)(lds + PG8_SA(b, h) + aoff + m * 2048 + k * 1024); } while (0)
; #define PG8_LDB(dst, b, h) do { _Pragma("unroll") for (int n = 0; n < 2; ++n) _Pragma("unroll") for (int k = 0; k < 2; ++k) dst[n][k] = *(const LAS bf16x8*)(lds + PG8_SB(b, h) + boff + n * 2048 + k * 1024); } while (0)
; #define PG8_MMA(ai, bj, At, Bt) do { __builtin_amdgcn_s_setprio(1); _Pragma("unroll") for (int m = 0; m < 4; ++m) _Pragma("unroll") for (int n = 0; n < 2; ++n) _Pragma("unroll") for (int k = 0; k < 2; ++k) \
;         acc[ai][bj][m][n] = __builtin_amdgcn_mfma_f32_16x16x32_bf16(Bt[n][k], At[m][k], acc[ai][bj][m][n], 0, 0, 0); __builtin_amdgcn_s_setprio(0); } while (0)
; #define PG8_BAR __builtin_amdgcn_s_barrier()
; template <class Epi>
; __device__ __forceinline__ void gemm_phase(LAS unsigned char* lds, const Sched& S, const int K, const Epi& E) {
;     ...
;         for (int t = 0; t < nt; t += 2) {
;             const bool last = (t == nt - 2);
;             const char* a1 = cA + (size_t)(t + 1) * kstep;
;             const char* a2 = last ? nA : cA + (size_t)(t + 2) * kstep; const char* b2 = last ? nB : cB + (size_t)(t + 2) * kstep;
;             const char* a3 = a2 + kstep; const char* b3 = b2 + kstep;
;             PG8_LDB(B0, 0, 0); PG8_LDB(B1, 0, 1); PG8_SCHED; PG8_LDA(At, 0, 0); PG8_STAGE(PG8_SA(1, 1), a1 + hstepA, voffA);
;             PG8_WAIT_V(8); PG8_WAIT_L(0); PG8_BAR; PG8_MMA(0, 0, At, B0); PG8_MMA(0, 1, At, B1); PG8_BAR; PG8_SCHED;
;             PG8_LDA(At, 0, 1); PG8_STAGE(PG8_SB(0, 0), b2, voffB); PG8_STAGE(PG8_SB(0, 1), b2 + hstepB, voffB); PG8_STAGE(PG8_SA(0, 0), a2, voffA);
;             PG8_WAIT_V(8); PG8_WAIT_L(0); PG8_BAR; PG8_MMA(1, 0, At, B0); PG8_MMA(1, 1, At, B1); PG8_BAR; PG8_SCHED;
;             PG8_LDB(B0, 1, 0); PG8_LDB(B1, 1, 1); PG8_SCHED; PG8_LDA(At, 1, 0); PG8_STAGE(PG8_SA(0, 1), a2 + hstepA, voffA);
;             PG8_WAIT_V(8); PG8_WAIT_L(0); PG8_BAR; PG8_MMA(0, 0, At, B0); PG8_MMA(0, 1, At, B1); PG8_BAR; PG8_SCHED;
.LBB0_1487:
	s_add_u32 s48, s36, 0x100
	s_addc_u32 s49, s37, 0
	s_add_i32 s76, 0, 0x10000
	s_cmpk_eq_i32 s92, 0x54
	s_cselect_b32 s53, s29, s49
	s_cselect_b32 s52, s28, s48
	v_add_u32_e32 v134, s76, v137
	s_cselect_b32 s51, s35, s73
	s_cselect_b32 s50, s34, s72
	s_add_i32 s77, 0, 0x14000
	ds_read_b128 v[140:143], v134
	ds_read_b128 v[144:147], v134 offset:1024
	ds_read_b128 v[148:151], v134 offset:2048
	ds_read_b128 v[152:155], v134 offset:3072
	v_add_u32_e32 v134, s77, v137
	ds_read_b128 v[156:159], v134
	ds_read_b128 v[160:163], v134 offset:1024
	ds_read_b128 v[164:167], v134 offset:2048
	ds_read_b128 v[168:171], v134 offset:3072
	v_lshl_add_u64 v[134:135], s[36:37], 0, v[132:133]
	s_add_i32 m0, s59, 0xc000
	ds_read_b128 v[198:201], v139
	ds_read_b128 v[202:205], v139 offset:1024
	ds_read_b128 v[206:209], v139 offset:2048
	ds_read_b128 v[210:213], v139 offset:3072
	ds_read_b128 v[214:217], v139 offset:4096
	ds_read_b128 v[218:221], v139 offset:5120
	ds_read_b128 v[228:231], v139 offset:6144
	ds_read_b128 v[232:235], v139 offset:7168
	global_load_lds_dwordx4 v[134:135], off
	v_lshl_add_u64 v[134:135], s[36:37], 0, v[130:131]
	s_add_i32 m0, s59, 0xe000
	s_nop 0
	global_load_lds_dwordx4 v[134:135], off
	s_waitcnt vmcnt(8)
	s_waitcnt lgkmcnt(0)
	s_barrier
	s_setprio 1
	s_waitcnt lgkmcnt(0)
	v_mfma_f32_16x16x32_bf16 v[124:127], v[140:143], v[198:201], v[124:127]
	v_mfma_f32_16x16x32_bf16 v[120:123], v[148:151], v[198:201], v[120:123]
	v_mfma_f32_16x16x32_bf16 v[116:119], v[140:143], v[206:209], v[116:119]
	v_mfma_f32_16x16x32_bf16 v[112:115], v[148:151], v[206:209], v[112:115]
	v_mfma_f32_16x16x32_bf16 v[104:107], v[140:143], v[214:217], v[104:107]
	v_mfma_f32_16x16x32_bf16 v[96:99], v[148:151], v[214:217], v[96:99]
	v_mfma_f32_16x16x32_bf16 v[88:91], v[140:143], v[228:231], v[88:91]
	v_mfma_f32_16x16x32_bf16 v[80:83], v[148:151], v[228:231], v[80:83]
	v_mfma_f32_16x16x32_bf16 v[124:127], v[144:147], v[202:205], v[124:127]
	v_mfma_f32_16x16x32_bf16 v[120:123], v[152:155], v[202:205], v[120:123]
	v_mfma_f32_16x16x32_bf16 v[116:119], v[144:147], v[210:213], v[116:119]
	v_mfma_f32_16x16x32_bf16 v[112:115], v[152:155], v[210:213], v[112:115]
	v_mfma_f32_16x16x32_bf16 v[104:107], v[144:147], v[218:221], v[104:107]
	v_mfma_f32_16x16x32_bf16 v[96:99], v[152:155], v[218:221], v[96:99]
	v_mfma_f32_16x16x32_bf16 v[88:91], v[144:147], v[232:235], v[88:91]
	v_mfma_f32_16x16x32_bf16 v[80:83], v[152:155], v[232:235], v[80:83]
	v_mfma_f32_16x16x32_bf16 v[108:111], v[156:159], v[198:201], v[108:111]
	v_mfma_f32_16x16x32_bf16 v[100:103], v[164:167], v[198:201], v[100:103]
	v_mfma_f32_16x16x32_bf16 v[92:95], v[156:159], v[206:209], v[92:95]
	v_mfma_f32_16x16x32_bf16 v[84:87], v[164:167], v[206:209], v[84:87]
	v_mfma_f32_16x16x32_bf16 v[76:79], v[156:159], v[214:217], v[76:79]
	v_mfma_f32_16x16x32_bf16 v[72:75], v[164:167], v[214:217], v[72:75]
	v_mfma_f32_16x16x32_bf16 v[68:71], v[156:159], v[228:231], v[68:71]
	v_mfma_f32_16x16x32_bf16 v[64:67], v[164:167], v[228:231], v[64:67]
	v_mfma_f32_16x16x32_bf16 v[108:111], v[160:163], v[202:205], v[108:111]
	v_mfma_f32_16x16x32_bf16 v[100:103], v[168:171], v[202:205], v[100:103]
	v_mfma_f32_16x16x32_bf16 v[92:95], v[160:163], v[210:213], v[92:95]
	v_mfma_f32_16x16x32_bf16 v[84:87], v[168:171], v[210:213], v[84:87]
	v_mfma_f32_16x16x32_bf16 v[76:79], v[160:163], v[218:221], v[76:79]
	v_mfma_f32_16x16x32_bf16 v[72:75], v[168:171], v[218:221], v[72:75]
	v_mfma_f32_16x16x32_bf16 v[68:71], v[160:163], v[232:235], v[68:71]
	v_mfma_f32_16x16x32_bf16 v[64:67], v[168:171], v[232:235], v[64:67]
	s_setprio 0
	s_barrier
	s_add_i32 s36, s76, s58
	v_lshl_add_u64 v[134:135], s[50:51], 0, v[172:173]
	s_mov_b32 m0, s36
	ds_read_b128 v[198:201], v139 offset:16384
	ds_read_b128 v[202:205], v139 offset:17408
	ds_read_b128 v[206:209], v139 offset:18432
	ds_read_b128 v[210:213], v139 offset:19456
	ds_read_b128 v[214:217], v139 offset:20480
	ds_read_b128 v[218:221], v139 offset:21504
	ds_read_b128 v[228:231], v139 offset:22528
	ds_read_b128 v[232:235], v139 offset:23552
	global_load_lds_dwordx4 v[134:135], off
	s_add_i32 m0, s36, 0x2000
	s_add_u32 s36, s50, 0x160000
	v_lshl_add_u64 v[194:195], s[50:51], 0, v[128:129]
	s_addc_u32 s37, s51, 0
	s_add_i32 s76, s77, s58
	global_load_lds_dwordx4 v[194:195], off
	v_lshl_add_u64 v[224:225], s[36:37], 0, v[172:173]
	s_mov_b32 m0, s76
	v_lshl_add_u64 v[236:237], s[52:53], 0, v[128:129]
	global_load_lds_dwordx4 v[224:225], off
	v_lshl_add_u64 v[224:225], s[36:37], 0, v[128:129]
	s_add_i32 m0, s76, 0x2000
	s_nop 0
	global_load_lds_dwordx4 v[224:225], off
	v_lshl_add_u64 v[224:225], s[52:53], 0, v[172:173]
	s_mov_b32 m0, s59
	s_nop 0
	global_load_lds_dwordx4 v[224:225], off
	s_mov_b32 m0, s60
	s_nop 0
	global_load_lds_dwordx4 v[236:237], off
	s_waitcnt vmcnt(8)
	s_waitcnt lgkmcnt(0)
	s_barrier
; #define PG8_STAGE(bufoff, gbase, voff) do { _Pragma("unroll") for (int _i = 0; _i < 2; ++_i) \
;         __builtin_amdgcn_global_load_lds((const unsigned*)((const char*)(gbase) + (voff)[_i]), (LAS unsigned*)(lds + (bufoff) + ldsw + _i * 8192), 16, 0, 0); } while (0)
; #define PG8_LDA(dst, b, h) do { _Pragma("unroll") for (int m = 0; m < 4; ++m) _Pragma("unroll") for (int k = 0; k < 2; ++k) dst[m][k] = *(const LAS bf16x8*)(lds + PG8_SA(b, h) + aoff + m * 2048 + k * 1024); } while (0)
; #define PG8_LDB(dst, b, h) do { _Pragma("unroll") for (int n = 0; n < 2; ++n) _Pragma("unroll") for (int k = 0; k < 2; ++k) dst[n][k] = *(const LAS bf16x8*)(lds + PG8_SB(b, h) + boff + n * 2048 + k * 1024); } while (0)
; #define PG8_MMA(ai, bj, At, Bt) do { __builtin_amdgcn_s_setprio(1); _Pragma("unroll") for (int m = 0; m < 4; ++m) _Pragma("unroll") for (int n = 0; n < 2; ++n) _Pragma("unroll") for (int k = 0; k < 2; ++k) \
;         acc[ai][bj][m][n] = __builtin_amdgcn_mfma_f32_16x16x32_bf16(Bt[n][k], At[m][k], acc[ai][bj][m][n], 0, 0, 0); __builtin_amdgcn_s_setprio(0); } while (0)
; #define PG8_WAIT_V(n) asm volatile("s_waitcnt vmcnt(" #n ")" ::: "memory")
; #define PG8_WAIT_L(n) asm volatile("s_waitcnt lgkmcnt(" #n ")" ::: "memory")
; #define PG8_BAR __builtin_amdgcn_s_barrier()
; #define PG8_SCHED __builtin_amdgcn_sched_barrier(0)
; template <class Epi>
; __device__ __forceinline__ void gemm_phase(LAS unsigned char* lds, const Sched& S, const int K, const Epi& E) {
;     ...
;             PG8_WAIT_V(8); PG8_WAIT_L(0); PG8_BAR; PG8_MMA(1, 0, At, B0); PG8_MMA(1, 1, At, B1); PG8_BAR; PG8_SCHED;
;             PG8_LDB(B0, 1, 0); PG8_LDB(B1, 1, 1); PG8_SCHED; PG8_LDA(At, 1, 0); PG8_STAGE(PG8_SA(0, 1), a2 + hstepA, voffA);
;             PG8_WAIT_V(8); PG8_WAIT_L(0); PG8_BAR; PG8_MMA(0, 0, At, B0); PG8_MMA(0, 1, At, B1); PG8_BAR; PG8_SCHED;
	s_setprio 1
	s_waitcnt lgkmcnt(0)
	v_mfma_f32_16x16x32_bf16 v[60:63], v[140:143], v[198:201], v[60:63]
	v_mfma_f32_16x16x32_bf16 v[56:59], v[148:151], v[198:201], v[56:59]
	v_mfma_f32_16x16x32_bf16 v[48:51], v[140:143], v[206:209], v[48:51]
	v_mfma_f32_16x16x32_bf16 v[40:43], v[148:151], v[206:209], v[40:43]
	v_mfma_f32_16x16x32_bf16 v[32:35], v[140:143], v[214:217], v[32:35]
	v_mfma_f32_16x16x32_bf16 v[24:27], v[148:151], v[214:217], v[24:27]
	v_mfma_f32_16x16x32_bf16 v[16:19], v[140:143], v[228:231], v[16:19]
	v_mfma_f32_16x16x32_bf16 v[8:11], v[148:151], v[228:231], v[8:11]
	v_mfma_f32_16x16x32_bf16 v[60:63], v[144:147], v[202:205], v[60:63]
	v_mfma_f32_16x16x32_bf16 v[56:59], v[152:155], v[202:205], v[56:59]
	v_mfma_f32_16x16x32_bf16 v[48:51], v[144:147], v[210:213], v[48:51]
	v_mfma_f32_16x16x32_bf16 v[40:43], v[152:155], v[210:213], v[40:43]
	v_mfma_f32_16x16x32_bf16 v[32:35], v[144:147], v[218:221], v[32:35]
	v_mfma_f32_16x16x32_bf16 v[24:27], v[152:155], v[218:221], v[24:27]
	v_mfma_f32_16x16x32_bf16 v[16:19], v[144:147], v[232:235], v[16:19]
	v_mfma_f32_16x16x32_bf16 v[8:11], v[152:155], v[232:235], v[8:11]
	v_mfma_f32_16x16x32_bf16 v[52:55], v[156:159], v[198:201], v[52:55]
	v_mfma_f32_16x16x32_bf16 v[44:47], v[164:167], v[198:201], v[44:47]
	v_mfma_f32_16x16x32_bf16 v[36:39], v[156:159], v[206:209], v[36:39]
	v_mfma_f32_16x16x32_bf16 v[28:31], v[164:167], v[206:209], v[28:31]
	v_mfma_f32_16x16x32_bf16 v[20:23], v[156:159], v[214:217], v[20:23]
	v_mfma_f32_16x16x32_bf16 v[12:15], v[164:167], v[214:217], v[12:15]
	v_mfma_f32_16x16x32_bf16 v[4:7], v[156:159], v[228:231], v[4:7]
	v_mfma_f32_16x16x32_bf16 v[0:3], v[164:167], v[228:231], v[0:3]
	v_mfma_f32_16x16x32_bf16 v[52:55], v[160:163], v[202:205], v[52:55]
	v_mfma_f32_16x16x32_bf16 v[44:47], v[168:171], v[202:205], v[44:47]
	v_mfma_f32_16x16x32_bf16 v[36:39], v[160:163], v[210:213], v[36:39]
	v_mfma_f32_16x16x32_bf16 v[28:31], v[168:171], v[210:213], v[28:31]
	v_mfma_f32_16x16x32_bf16 v[20:23], v[160:163], v[218:221], v[20:23]
	v_mfma_f32_16x16x32_bf16 v[12:15], v[168:171], v[218:221], v[12:15]
	v_mfma_f32_16x16x32_bf16 v[4:7], v[160:163], v[232:235], v[4:7]
	v_mfma_f32_16x16x32_bf16 v[0:3], v[168:171], v[232:235], v[0:3]
	s_setprio 0
	s_barrier
	s_add_i32 s76, 0, 0x18000
	s_add_i32 s77, 0, 0x1c000
	v_add_u32_e32 v152, s76, v137
	v_add_u32_e32 v168, s77, v137
	ds_read_b128 v[140:143], v152
	ds_read_b128 v[144:147], v152 offset:1024
	ds_read_b128 v[148:151], v152 offset:2048
	ds_read_b128 v[152:155], v152 offset:3072
	ds_read_b128 v[156:159], v168
	ds_read_b128 v[160:163], v168 offset:1024
	ds_read_b128 v[164:167], v168 offset:2048
	ds_read_b128 v[168:171], v168 offset:3072
	s_add_u32 s36, s52, 0x160000
	s_addc_u32 s37, s53, 0
	s_mov_b32 m0, s63
	v_lshl_add_u64 v[238:239], s[36:37], 0, v[172:173]
	ds_read_b128 v[198:201], v139 offset:32768
	ds_read_b128 v[202:205], v139 offset:33792
	ds_read_b128 v[206:209], v139 offset:34816
	ds_read_b128 v[210:213], v139 offset:35840
	ds_read_b128 v[214:217], v139 offset:36864
	ds_read_b128 v[218:221], v139 offset:37888
	ds_read_b128 v[228:231], v139 offset:38912
	ds_read_b128 v[232:235], v139 offset:39936
	global_load_lds_dwordx4 v[238:239], off
	v_lshl_add_u64 v[238:239], s[36:37], 0, v[128:129]
	s_mov_b32 m0, s65
	s_nop 0
	global_load_lds_dwordx4 v[238:239], off
	s_waitcnt vmcnt(8)
	s_waitcnt lgkmcnt(0)
	s_barrier
	s_setprio 1
	s_waitcnt lgkmcnt(0)
	v_mfma_f32_16x16x32_bf16 v[124:127], v[140:143], v[198:201], v[124:127]
	v_mfma_f32_16x16x32_bf16 v[120:123], v[148:151], v[198:201], v[120:123]
	v_mfma_f32_16x16x32_bf16 v[116:119], v[140:143], v[206:209], v[116:119]
	v_mfma_f32_16x16x32_bf16 v[112:115], v[148:151], v[206:209], v[112:115]
	v_mfma_f32_16x16x32_bf16 v[104:107], v[140:143], v[214:217], v[104:107]
	v_mfma_f32_16x16x32_bf16 v[96:99], v[148:151], v[214:217], v[96:99]
	v_mfma_f32_16x16x32_bf16 v[88:91], v[140:143], v[228:231], v[88:91]
	v_mfma_f32_16x16x32_bf16 v[80:83], v[148:151], v[228:231], v[80:83]
	v_mfma_f32_16x16x32_bf16 v[124:127], v[144:147], v[202:205], v[124:127]
	v_mfma_f32_16x16x32_bf16 v[120:123], v[152:155], v[202:205], v[120:123]
	v_mfma_f32_16x16x32_bf16 v[116:119], v[144:147], v[210:213], v[116:119]
	v_mfma_f32_16x16x32_bf16 v[112:115], v[152:155], v[210:213], v[112:115]
	v_mfma_f32_16x16x32_bf16 v[104:107], v[144:147], v[218:221], v[104:107]
	v_mfma_f32_16x16x32_bf16 v[96:99], v[152:155], v[218:221], v[96:99]
	v_mfma_f32_16x16x32_bf16 v[88:91], v[144:147], v[232:235], v[88:91]
	v_mfma_f32_16x16x32_bf16 v[80:83], v[152:155], v[232:235], v[80:83]
	v_mfma_f32_16x16x32_bf16 v[108:111], v[156:159], v[198:201], v[108:111]
	v_mfma_f32_16x16x32_bf16 v[100:103], v[164:167], v[198:201], v[100:103]
	v_mfma_f32_16x16x32_bf16 v[92:95], v[156:159], v[206:209], v[92:95]
	v_mfma_f32_16x16x32_bf16 v[84:87], v[164:167], v[206:209], v[84:87]
	v_mfma_f32_16x16x32_bf16 v[76:79], v[156:159], v[214:217], v[76:79]
	v_mfma_f32_16x16x32_bf16 v[72:75], v[164:167], v[214:217], v[72:75]
	v_mfma_f32_16x16x32_bf16 v[68:71], v[156:159], v[228:231], v[68:71]
	v_mfma_f32_16x16x32_bf16 v[64:67], v[164:167], v[228:231], v[64:67]
	v_mfma_f32_16x16x32_bf16 v[108:111], v[160:163], v[202:205], v[108:111]
	v_mfma_f32_16x16x32_bf16 v[100:103], v[168:171], v[202:205], v[100:103]
	v_mfma_f32_16x16x32_bf16 v[92:95], v[160:163], v[210:213], v[92:95]
	v_mfma_f32_16x16x32_bf16 v[84:87], v[168:171], v[210:213], v[84:87]
	v_mfma_f32_16x16x32_bf16 v[76:79], v[160:163], v[218:221], v[76:79]
	v_mfma_f32_16x16x32_bf16 v[72:75], v[168:171], v[218:221], v[72:75]
	v_mfma_f32_16x16x32_bf16 v[68:71], v[160:163], v[232:235], v[68:71]
	v_mfma_f32_16x16x32_bf16 v[64:67], v[168:171], v[232:235], v[64:67]
	s_setprio 0
	s_barrier
; #define PG8_STAGE(bufoff, gbase, voff) do { _Pragma("unroll") for (int _i = 0; _i < 2; ++_i) \
;         __builtin_amdgcn_global_load_lds((const unsigned*)((const char*)(gbase) + (voff)[_i]), (LAS unsigned*)(lds + (bufoff) + ldsw + _i * 8192), 16, 0, 0); } while (0)
; #define PG8_LDA(dst, b, h) do { _Pragma("unroll") for (int m = 0; m < 4; ++m) _Pragma("unroll") for (int k = 0; k < 2; ++k) dst[m][k] = *(const LAS bf16x8*)(lds + PG8_SA(b, h) + aoff + m * 2048 + k * 1024); } while (0)
; #define PG8_MMA(ai, bj, At, Bt) do { __builtin_amdgcn_s_setprio(1); _Pragma("unroll") for (int m = 0; m < 4; ++m) _Pragma("unroll") for (int n = 0; n < 2; ++n) _Pragma("unroll") for (int k = 0; k < 2; ++k) \
;         acc[ai][bj][m][n] = __builtin_amdgcn_mfma_f32_16x16x32_bf16(Bt[n][k], At[m][k], acc[ai][bj][m][n], 0, 0, 0); __builtin_amdgcn_s_setprio(0); } while (0)
; #define PG8_WAIT_V(n) asm volatile("s_waitcnt vmcnt(" #n ")" ::: "memory")
; #define PG8_WAIT_L(n) asm volatile("s_waitcnt lgkmcnt(" #n ")" ::: "memory")
; #define PG8_BAR __builtin_amdgcn_s_barrier()
; #define PG8_SCHED __builtin_amdgcn_sched_barrier(0)
; template <class Epi>
; __device__ __forceinline__ void gemm_phase(LAS unsigned char* lds, const Sched& S, const int K, const Epi& E) {
;     ...
;             PG8_LDA(At, 1, 1); PG8_STAGE(PG8_SB(1, 0), b3, voffB); PG8_STAGE(PG8_SB(1, 1), b3 + hstepB, voffB); PG8_STAGE(PG8_SA(1, 0), a3, voffA);
;             PG8_WAIT_V(8); PG8_WAIT_L(0); PG8_BAR; PG8_MMA(1, 0, At, B0); PG8_MMA(1, 1, At, B1); PG8_BAR; PG8_SCHED;
;         }
;         if (wr == 0) PG8_BAR;
	s_add_i32 s36, s76, s58
	v_lshl_add_u64 v[134:135], v[134:135], 0, s[74:75]
	s_mov_b32 m0, s36
	ds_read_b128 v[198:201], v139 offset:49152
	ds_read_b128 v[202:205], v139 offset:50176
	ds_read_b128 v[206:209], v139 offset:51200
	ds_read_b128 v[210:213], v139 offset:52224
	ds_read_b128 v[214:217], v139 offset:53248
	ds_read_b128 v[218:221], v139 offset:54272
	ds_read_b128 v[228:231], v139 offset:55296
	ds_read_b128 v[232:235], v139 offset:56320
	global_load_lds_dwordx4 v[134:135], off
	s_add_i32 m0, s36, 0x2000
	s_add_u32 s36, s50, 0x160080
	v_lshl_add_u64 v[134:135], v[194:195], 0, s[74:75]
	s_addc_u32 s37, s51, 0
	s_add_i32 s50, s77, s58
	global_load_lds_dwordx4 v[134:135], off
	v_lshl_add_u64 v[134:135], s[36:37], 0, v[172:173]
	s_mov_b32 m0, s50
	s_nop 0
	global_load_lds_dwordx4 v[134:135], off
	v_lshl_add_u64 v[134:135], s[36:37], 0, v[128:129]
	s_add_i32 m0, s50, 0x2000
	s_nop 0
	global_load_lds_dwordx4 v[134:135], off
	v_lshl_add_u64 v[134:135], v[224:225], 0, s[74:75]
	s_mov_b32 m0, s66
	s_nop 0
	global_load_lds_dwordx4 v[134:135], off
	v_lshl_add_u64 v[134:135], v[236:237], 0, s[74:75]
	s_mov_b32 m0, s67
	s_nop 0
	global_load_lds_dwordx4 v[134:135], off
	s_waitcnt vmcnt(8)
	s_waitcnt lgkmcnt(0)
	s_barrier
	s_setprio 1
	s_waitcnt lgkmcnt(0)
	v_mfma_f32_16x16x32_bf16 v[60:63], v[140:143], v[198:201], v[60:63]
	v_mfma_f32_16x16x32_bf16 v[56:59], v[148:151], v[198:201], v[56:59]
	v_mfma_f32_16x16x32_bf16 v[48:51], v[140:143], v[206:209], v[48:51]
	v_mfma_f32_16x16x32_bf16 v[40:43], v[148:151], v[206:209], v[40:43]
	v_mfma_f32_16x16x32_bf16 v[32:35], v[140:143], v[214:217], v[32:35]
	v_mfma_f32_16x16x32_bf16 v[24:27], v[148:151], v[214:217], v[24:27]
	v_mfma_f32_16x16x32_bf16 v[16:19], v[140:143], v[228:231], v[16:19]
	v_mfma_f32_16x16x32_bf16 v[8:11], v[148:151], v[228:231], v[8:11]
	v_mfma_f32_16x16x32_bf16 v[60:63], v[144:147], v[202:205], v[60:63]
	v_mfma_f32_16x16x32_bf16 v[56:59], v[152:155], v[202:205], v[56:59]
	v_mfma_f32_16x16x32_bf16 v[48:51], v[144:147], v[210:213], v[48:51]
	v_mfma_f32_16x16x32_bf16 v[40:43], v[152:155], v[210:213], v[40:43]
	v_mfma_f32_16x16x32_bf16 v[32:35], v[144:147], v[218:221], v[32:35]
	v_mfma_f32_16x16x32_bf16 v[24:27], v[152:155], v[218:221], v[24:27]
	v_mfma_f32_16x16x32_bf16 v[16:19], v[144:147], v[232:235], v[16:19]
	v_mfma_f32_16x16x32_bf16 v[8:11], v[152:155], v[232:235], v[8:11]
	v_mfma_f32_16x16x32_bf16 v[52:55], v[156:159], v[198:201], v[52:55]
	v_mfma_f32_16x16x32_bf16 v[44:47], v[164:167], v[198:201], v[44:47]
	v_mfma_f32_16x16x32_bf16 v[36:39], v[156:159], v[206:209], v[36:39]
	v_mfma_f32_16x16x32_bf16 v[28:31], v[164:167], v[206:209], v[28:31]
	v_mfma_f32_16x16x32_bf16 v[20:23], v[156:159], v[214:217], v[20:23]
	v_mfma_f32_16x16x32_bf16 v[12:15], v[164:167], v[214:217], v[12:15]
	v_mfma_f32_16x16x32_bf16 v[4:7], v[156:159], v[228:231], v[4:7]
	v_mfma_f32_16x16x32_bf16 v[0:3], v[164:167], v[228:231], v[0:3]
	v_mfma_f32_16x16x32_bf16 v[52:55], v[160:163], v[202:205], v[52:55]
	v_mfma_f32_16x16x32_bf16 v[44:47], v[168:171], v[202:205], v[44:47]
	v_mfma_f32_16x16x32_bf16 v[36:39], v[160:163], v[210:213], v[36:39]
	v_mfma_f32_16x16x32_bf16 v[28:31], v[168:171], v[210:213], v[28:31]
	v_mfma_f32_16x16x32_bf16 v[20:23], v[160:163], v[218:221], v[20:23]
	v_mfma_f32_16x16x32_bf16 v[12:15], v[168:171], v[218:221], v[12:15]
	v_mfma_f32_16x16x32_bf16 v[4:7], v[160:163], v[232:235], v[4:7]
	v_mfma_f32_16x16x32_bf16 v[0:3], v[168:171], v[232:235], v[0:3]
	s_setprio 0
	s_barrier
	s_add_i32 s92, s92, 2
	s_add_u32 s72, s72, 0x100
	s_addc_u32 s73, s73, 0
	s_cmpk_gt_u32 s92, 0x55
	s_mov_b64 s[36:37], s[48:49]
	s_cbranch_scc0 .LBB0_1487
	s_and_b64 vcc, exec, s[42:43]
	s_cbranch_vccz .LBB0_1490
	s_barrier
